# loop-edge: stage-end vmcnt(0) and lgkmcnt(0) waits merged into one s_waitcnt before each GEMM stage barrier
# baseline (speedup 1.0000x reference)
; DI int otid() { int t = threadIdx.x; asm volatile("" : "+v"(t)); return t; }
; template <bool SWAP, bool HALF>
; DI void gemm_mainloop(const GemmDesc& d, int m0, int n0, bf16_t* smem, f32x16 (&acc)[2][2], int dry) {
;   const int t = otid(), lane = t & 63, w = t >> 6, wm = w >> 1, wn = w & 1, r = lane & 31, hh = lane >> 5;
;   const int lrow = t >> 3, lkc = t & 7;
;   const bf16_t* ap[4]; const bf16_t* bp[4];
; #pragma unroll
;   for (int i = 0; i < 4; ++i) {
;     int am = m0 + lrow + 32 * i; am = am < M ? am : M - 1;
;     ap[i] = d.A + (size_t)am * d.lda + lkc * 8 + (d.a_grp ? (n0 / d.a_grp) * d.a_grp : 0);
;     bp[i] = d.Bt + (size_t)(n0 + lrow + 32 * i) * d.ldb + lkc * 8;
;   }
; #pragma unroll
;   for (int a = 0; a < 2; ++a)
; #pragma unroll
;     for (int b = 0; b < 2; ++b)
; #pragma unroll
;       for (int i = 0; i < 16; ++i) acc[a][b][i] = 0.f;
;   u32x4 ra0[4], rb0[4], ra1[4], rb1[4];
;   const int nk = d.K >> 6;
;   const int lds_w = lrow * LST + lkc * 8;
;   auto gl = [&](u32x4 (&ra)[4], u32x4 (&rb)[4], int ks) {
; #pragma unroll
;     for (int i = 0; i < 4; ++i) {
;       ra[i] = *(const u32x4*)(ap[i] + (size_t)ks * d.a_cs);
;       __builtin_amdgcn_sched_barrier(0);
;       rb[i] = *(const u32x4*)(bp[i] + (size_t)ks * 64);
;       __builtin_amdgcn_sched_barrier(0);
;     }
;   };
;     ...
;   gl(ra0, rb0, 0);
;   gl(ra1, rb1, 1);
;   lw(ra0, rb0, 0);
;   gl(ra0, rb0, 2);
;   __syncthreads();
.LBB0_190:
	s_or_b64 exec, exec, s[4:5]
	s_lshl_b32 s33, s7, 7
	s_and_b32 s4, s7, -8
	s_waitcnt vmcnt(0)
	v_ashrrev_i32_e32 v187, 7, v150
	v_bfe_u32 v188, v150, 6, 1
	v_and_b32_e32 v170, 31, v150
	v_bfe_u32 v189, v150, 5, 1
	s_cmp_lg_u32 s4, 16
	s_mov_b64 s[4:5], -1
	s_cbranch_scc0 .LBB0_260
	v_mov_b32_e32 v32, v172
	v_readlane_b32 s76, v228, 60
	v_ashrrev_i32_e32 v10, 3, v32
	v_lshlrev_b32_e32 v0, 3, v32
	v_and_b32_e32 v33, 56, v0
	v_add_u32_e32 v2, s33, v10
	v_lshlrev_b32_e32 v144, 1, v33
	v_readlane_b32 s90, v223, 10
	v_readlane_b32 s91, v223, 11
	v_ashrrev_i32_e32 v3, 31, v2
	v_add_u32_e32 v11, s25, v10
	v_lshl_add_u64 v[4:5], s[90:91], 0, v[144:145]
	v_lshlrev_b64 v[2:3], 11, v[2:3]
	v_lshl_add_u64 v[154:155], v[4:5], 0, v[2:3]
	v_min_i32_e32 v2, 0x801f, v11
	v_ashrrev_i32_e32 v3, 31, v2
	v_lshl_add_u64 v[0:1], s[56:57], 0, v[144:145]
	v_lshlrev_b64 v[2:3], 11, v[2:3]
	v_lshl_add_u64 v[8:9], v[0:1], 0, v[2:3]
	v_min_i32_e32 v2, 0x7fff, v11
	v_ashrrev_i32_e32 v3, 31, v2
	v_min_i32_e32 v6, 0x803f, v11
	v_lshlrev_b64 v[2:3], 11, v[2:3]
	v_ashrrev_i32_e32 v7, 31, v6
	v_lshl_add_u64 v[16:17], v[0:1], 0, v[2:3]
	v_min_i32_e32 v2, 0x7fdf, v11
	v_lshlrev_b64 v[6:7], 11, v[6:7]
	v_ashrrev_i32_e32 v3, 31, v2
	v_lshl_add_u64 v[152:153], v[0:1], 0, v[6:7]
	v_lshlrev_b64 v[2:3], 11, v[2:3]
	v_lshl_add_u64 v[24:25], v[0:1], 0, v[2:3]
	s_mov_b64 s[4:5], 0x10000
	v_lshl_add_u64 v[156:157], v[8:9], 0, s[4:5]
	v_lshl_add_u64 v[158:159], v[154:155], 0, s[4:5]
	s_mov_b64 s[4:5], 0x20000
	v_lshl_add_u64 v[160:161], v[16:17], 0, s[4:5]
	v_lshl_add_u64 v[162:163], v[154:155], 0, s[4:5]
	s_mov_b64 s[4:5], 0x30000
	v_lshl_add_u64 v[164:165], v[24:25], 0, s[4:5]
	v_lshl_add_u64 v[166:167], v[154:155], 0, s[4:5]
	s_movk_i32 s4, 0x48
	v_and_b32_e32 v34, 31, v32
	v_mul_lo_u32 v35, v10, s4
	v_readlane_b32 s77, v228, 61
	v_readlane_b32 s78, v228, 62
	v_readlane_b32 s79, v228, 63
	v_readlane_b32 s80, v223, 0
	v_readlane_b32 s81, v223, 1
	v_readlane_b32 s82, v223, 2
	v_readlane_b32 s83, v223, 3
	v_readlane_b32 s84, v223, 4
	v_readlane_b32 s85, v223, 5
	v_readlane_b32 s86, v223, 6
	v_readlane_b32 s87, v223, 7
	v_readlane_b32 s88, v223, 8
	v_readlane_b32 s89, v223, 9
	s_mov_b32 s4, 0x10000
	v_add_co_u32_e32 v8, vcc, s4, v8
	s_nop 1
	v_addc_co_u32_e32 v9, vcc, 0, v9, vcc
	s_waitcnt vmcnt(19)
	v_add_co_u32_e32 v12, vcc, s4, v154
	s_nop 1
	v_addc_co_u32_e32 v13, vcc, 0, v155, vcc
	s_mov_b32 s4, 0x20000
	v_add_co_u32_e32 v16, vcc, s4, v16
	s_nop 1
	v_addc_co_u32_e32 v17, vcc, 0, v17, vcc
	v_add_co_u32_e32 v20, vcc, s4, v154
	s_nop 1
	v_addc_co_u32_e32 v21, vcc, 0, v155, vcc
	s_mov_b32 s4, 0x30000
	v_add_co_u32_e32 v24, vcc, s4, v24
	s_nop 1
	v_addc_co_u32_e32 v25, vcc, 0, v25, vcc
	v_add_co_u32_e32 v28, vcc, s4, v154
	s_nop 1
	v_addc_co_u32_e32 v29, vcc, 0, v155, vcc
	s_nop 0
	v_add_lshl_u32 v144, v35, v33, 1
	s_waitcnt vmcnt(15)
	s_waitcnt vmcnt(14)
	s_waitcnt vmcnt(13)
	s_waitcnt vmcnt(12)
	s_waitcnt vmcnt(11)
	s_waitcnt vmcnt(10)
	s_waitcnt vmcnt(9)
	s_waitcnt vmcnt(8)
	v_lshrrev_b32_e32 v0, 1, v32
	v_and_or_b32 v1, v0, s72, v34
	v_and_b32_e32 v0, 16, v0
	s_movk_i32 s4, 0x90
	v_mad_u64_u32 v[168:169], s[4:5], v1, s4, v[0:1]
	v_and_b32_e32 v1, 0x5f, v32
	v_mul_u32_u24_e32 v1, 0x48, v1
	v_lshl_add_u32 v169, v1, 1, v0
	v_bfe_u32 v212, v172, 4, 3
	v_lshlrev_b32_e32 v212, 4, v212
	v_xor_b32_e32 v152, v152, v212
	v_xor_b32_e32 v154, v154, v212
	v_xor_b32_e32 v156, v156, v212
	v_xor_b32_e32 v158, v158, v212
	v_xor_b32_e32 v160, v160, v212
	v_xor_b32_e32 v162, v162, v212
	v_xor_b32_e32 v164, v164, v212
	v_xor_b32_e32 v166, v166, v212
	v_lshrrev_b32_e32 v213, 6, v172
	s_nop 1
	v_readfirstlane_b32 s101, v213
	s_lshl_b32 s101, s101, 10
	s_add_u32 m0, s101, 0x0
	s_nop 0
	global_load_lds_dwordx4 v[152:153], off
	s_add_u32 m0, s101, 0x4000
	s_nop 0
	global_load_lds_dwordx4 v[154:155], off
	s_add_u32 m0, s101, 0x1000
	s_nop 0
	global_load_lds_dwordx4 v[156:157], off
	s_add_u32 m0, s101, 0x5000
	s_nop 0
	global_load_lds_dwordx4 v[158:159], off
	s_add_u32 m0, s101, 0x2000
	s_nop 0
	global_load_lds_dwordx4 v[160:161], off
	s_add_u32 m0, s101, 0x6000
	s_nop 0
	global_load_lds_dwordx4 v[162:163], off
	s_add_u32 m0, s101, 0x3000
	s_nop 0
	global_load_lds_dwordx4 v[164:165], off
	s_add_u32 m0, s101, 0x7000
	s_nop 0
	global_load_lds_dwordx4 v[166:167], off
	v_and_b32_e32 v212, 15, v172
	v_bfe_u32 v213, v172, 4, 2
	v_lshrrev_b32_e32 v214, 1, v212
	v_xor_b32_e32 v213, v213, v214
	v_lshlrev_b32_e32 v213, 4, v213
	v_lshl_or_b32 v212, v212, 7, v213
	v_lshrrev_b32_e32 v214, 7, v172
	v_lshl_add_u32 v168, v214, 13, v212
	v_bfe_u32 v214, v172, 6, 1
	v_lshl_add_u32 v169, v214, 13, v212
	v_add_u32_e32 v169, 0x4000, v169
	v_xor_b32_e32 v220, 64, v168
	v_xor_b32_e32 v221, 64, v169
	s_waitcnt vmcnt(0) lgkmcnt(0)
	s_barrier
; #define MFMA32(a, b, c) __builtin_amdgcn_mfma_f32_32x32x16_bf16((a), (b), (c), 0, 0, 0)
; #define SB_ __builtin_amdgcn_sched_barrier(0)
; template <bool SWAP, bool HALF>
; DI void gemm_mainloop(const GemmDesc& d, int m0, int n0, bf16_t* smem, f32x16 (&acc)[2][2], int dry) {
;     ...
;   auto ldf = [&](int buf, int kk, int set) {
;     const bf16_t* Ab = smem + buf * 2 * TILE_EL + ((HALF ? 0 : wm * 64) + r) * LST + 8 * hh + kk * 16;
;     const bf16_t* Bb = smem + buf * 2 * TILE_EL + TILE_EL + ((HALF ? w * 32 : wn * 64) + r) * LST + 8 * hh + kk * 16;
; #pragma unroll
;     for (int i = 0; i < 2; ++i) { fa[set][i] = *(const bf16x8*)(Ab + i * 32 * LST); if (!HALF || i == 0) fb[set][i] = *(const bf16x8*)(Bb + i * 32 * LST); }
;   };
;   auto mma = [&](int set) {
; #pragma unroll
;     for (int a = 0; a < 2; ++a)
; #pragma unroll
;       for (int b = 0; b < (HALF ? 1 : 2); ++b) {
;         if (SWAP) acc[a][b] = MFMA32(fb[set][b], fa[set][a], acc[a][b]);
;         else      acc[a][b] = MFMA32(fa[set][a], fb[set][b], acc[a][b]);
;       }
;   };
;     ...
;   auto stage = [&](int cur, u32x4 (&ran)[4], u32x4 (&rbn)[4], int ks) {
;     ldf(cur, 1, 1); SB_;
;     mma(0); SB_;
;     ldf(cur, 2, 0); SB_;
;     lw(ran, rbn, cur ^ 1);
;     gl(ran, rbn, (ks + 3 < nk) ? ks + 3 : nk - 1);
;     SB_;
;     mma(1); SB_;
;     __syncthreads();
;     ldf(cur, 3, 1); SB_;
;     mma(0); SB_;
;     ldf(cur ^ 1, 0, 0);
;     SB_;
;     mma(1); SB_;
;     __syncthreads();
;   };
	v_mov_b32_e32 v0, 0
	v_add_u32_e32 v190, 0x9000, v144
	s_mov_b32 s4, -2
	v_mov_b32_e32 v1, v0
	v_mov_b32_e32 v2, v0
	v_mov_b32_e32 v3, v0
	v_mov_b32_e32 v4, v0
	v_mov_b32_e32 v5, v0
	v_mov_b32_e32 v6, v0
	v_mov_b32_e32 v7, v0
	v_mov_b32_e32 v8, v0
	v_mov_b32_e32 v9, v0
	v_mov_b32_e32 v10, v0
	v_mov_b32_e32 v11, v0
	v_mov_b32_e32 v12, v0
	v_mov_b32_e32 v13, v0
	v_mov_b32_e32 v14, v0
	v_mov_b32_e32 v15, v0
	v_mov_b32_e32 v16, v0
	v_mov_b32_e32 v17, v0
	v_mov_b32_e32 v18, v0
	v_mov_b32_e32 v19, v0
	v_mov_b32_e32 v20, v0
	v_mov_b32_e32 v21, v0
	v_mov_b32_e32 v22, v0
	v_mov_b32_e32 v23, v0
	v_mov_b32_e32 v24, v0
	v_mov_b32_e32 v25, v0
	v_mov_b32_e32 v26, v0
	v_mov_b32_e32 v27, v0
	v_mov_b32_e32 v28, v0
	v_mov_b32_e32 v29, v0
	v_mov_b32_e32 v30, v0
	v_mov_b32_e32 v31, v0
	v_mov_b32_e32 v32, v0
	v_mov_b32_e32 v33, v0
	v_mov_b32_e32 v34, v0
	v_mov_b32_e32 v35, v0
	v_mov_b32_e32 v36, v0
	v_mov_b32_e32 v37, v0
	v_mov_b32_e32 v38, v0
	v_mov_b32_e32 v39, v0
	v_mov_b32_e32 v40, v0
	v_mov_b32_e32 v41, v0
	v_mov_b32_e32 v42, v0
	v_mov_b32_e32 v43, v0
	v_mov_b32_e32 v44, v0
	v_mov_b32_e32 v45, v0
	v_mov_b32_e32 v46, v0
	v_mov_b32_e32 v47, v0
	v_mov_b32_e32 v48, v0
	v_mov_b32_e32 v49, v0
	v_mov_b32_e32 v50, v0
	v_mov_b32_e32 v51, v0
	v_mov_b32_e32 v52, v0
	v_mov_b32_e32 v53, v0
	v_mov_b32_e32 v54, v0
	v_mov_b32_e32 v55, v0
	v_mov_b32_e32 v56, v0
	v_mov_b32_e32 v57, v0
	v_mov_b32_e32 v58, v0
	v_mov_b32_e32 v59, v0
	v_mov_b32_e32 v60, v0
	v_mov_b32_e32 v61, v0
	v_mov_b32_e32 v62, v0
	v_mov_b32_e32 v63, v0
	ds_read_b128 v[64:67], v168 offset:0
	ds_read_b128 v[68:71], v168 offset:2048
	ds_read_b128 v[72:75], v168 offset:4096
	ds_read_b128 v[76:79], v168 offset:6144
	ds_read_b128 v[80:83], v169 offset:0
	ds_read_b128 v[84:87], v169 offset:2048
	ds_read_b128 v[88:91], v169 offset:4096
	ds_read_b128 v[92:95], v169 offset:6144
	s_add_i32 s5, s4, 3
	s_min_u32 s5, s5, 15
	s_lshl_b32 s18, s5, 7
	s_add_u32 m0, s101, 0x8000
	v_lshl_add_u64 v[210:211], v[152:153], 0, s[18:19]
	global_load_lds_dwordx4 v[210:211], off
	s_add_u32 m0, s101, 0xc000
	v_lshl_add_u64 v[210:211], v[154:155], 0, s[18:19]
	global_load_lds_dwordx4 v[210:211], off
	ds_read_b128 v[96:99], v220 offset:0
	ds_read_b128 v[100:103], v220 offset:2048
	ds_read_b128 v[104:107], v220 offset:4096
	ds_read_b128 v[108:111], v220 offset:6144
	ds_read_b128 v[112:115], v221 offset:0
	ds_read_b128 v[116:119], v221 offset:2048
	ds_read_b128 v[120:123], v221 offset:4096
	ds_read_b128 v[124:127], v221 offset:6144
	s_waitcnt lgkmcnt(8)
	v_mfma_f32_16x16x32_bf16 v[0:3], v[80:83], v[64:67], v[0:3]
	v_mfma_f32_16x16x32_bf16 v[4:7], v[84:87], v[64:67], v[4:7]
	s_add_u32 m0, s101, 0x9000
	v_lshl_add_u64 v[210:211], v[156:157], 0, s[18:19]
	global_load_lds_dwordx4 v[210:211], off
	v_mfma_f32_16x16x32_bf16 v[8:11], v[88:91], v[64:67], v[8:11]
	v_mfma_f32_16x16x32_bf16 v[12:15], v[92:95], v[64:67], v[12:15]
	s_add_u32 m0, s101, 0xd000
	v_lshl_add_u64 v[210:211], v[158:159], 0, s[18:19]
	global_load_lds_dwordx4 v[210:211], off
	v_mfma_f32_16x16x32_bf16 v[16:19], v[80:83], v[68:71], v[16:19]
	v_mfma_f32_16x16x32_bf16 v[20:23], v[84:87], v[68:71], v[20:23]
	s_add_u32 m0, s101, 0xa000
	v_lshl_add_u64 v[210:211], v[160:161], 0, s[18:19]
	global_load_lds_dwordx4 v[210:211], off
	v_mfma_f32_16x16x32_bf16 v[24:27], v[88:91], v[68:71], v[24:27]
	v_mfma_f32_16x16x32_bf16 v[28:31], v[92:95], v[68:71], v[28:31]
	s_add_u32 m0, s101, 0xe000
	v_lshl_add_u64 v[210:211], v[162:163], 0, s[18:19]
	global_load_lds_dwordx4 v[210:211], off
	v_mfma_f32_16x16x32_bf16 v[32:35], v[80:83], v[72:75], v[32:35]
	v_mfma_f32_16x16x32_bf16 v[36:39], v[84:87], v[72:75], v[36:39]
	s_add_u32 m0, s101, 0xb000
	v_lshl_add_u64 v[210:211], v[164:165], 0, s[18:19]
	global_load_lds_dwordx4 v[210:211], off
	v_mfma_f32_16x16x32_bf16 v[40:43], v[88:91], v[72:75], v[40:43]
	v_mfma_f32_16x16x32_bf16 v[44:47], v[92:95], v[72:75], v[44:47]
	s_add_u32 m0, s101, 0xf000
	v_lshl_add_u64 v[210:211], v[166:167], 0, s[18:19]
	global_load_lds_dwordx4 v[210:211], off
	v_mfma_f32_16x16x32_bf16 v[48:51], v[80:83], v[76:79], v[48:51]
	v_mfma_f32_16x16x32_bf16 v[52:55], v[84:87], v[76:79], v[52:55]
	v_mfma_f32_16x16x32_bf16 v[56:59], v[88:91], v[76:79], v[56:59]
	v_mfma_f32_16x16x32_bf16 v[60:63], v[92:95], v[76:79], v[60:63]
	s_waitcnt vmcnt(0) lgkmcnt(0)
	s_barrier
; #define SB_ __builtin_amdgcn_sched_barrier(0)
; template <bool SWAP, bool HALF>
; DI void gemm_mainloop(const GemmDesc& d, int m0, int n0, bf16_t* smem, f32x16 (&acc)[2][2], int dry) {
;     ...
;   auto stage = [&](int cur, u32x4 (&ran)[4], u32x4 (&rbn)[4], int ks) {
;     ldf(cur, 1, 1); SB_;
;     mma(0); SB_;
;     ldf(cur, 2, 0); SB_;
;     lw(ran, rbn, cur ^ 1);
;     gl(ran, rbn, (ks + 3 < nk) ? ks + 3 : nk - 1);
;     SB_;
;     mma(1); SB_;
;     __syncthreads();
;     ldf(cur, 3, 1); SB_;
;     mma(0); SB_;
;     ldf(cur ^ 1, 0, 0);
;     SB_;
;     mma(1); SB_;
;     __syncthreads();
;   };
;   gl(ra0, rb0, 0);
;   gl(ra1, rb1, 1);
;   lw(ra0, rb0, 0);
;   gl(ra0, rb0, 2);
;   __syncthreads();
;   ldf(0, 0, 0);
; #pragma unroll 1
;   for (int ks = 0; ks < nk; ks += 2) {
;     stage(0, ra1, rb1, ks);
;     stage(1, ra0, rb0, ks + 1);
;   }
.LBB0_192:
	ds_read_b128 v[64:67], v168 offset:32768
	ds_read_b128 v[68:71], v168 offset:34816
	ds_read_b128 v[72:75], v168 offset:36864
	ds_read_b128 v[76:79], v168 offset:38912
	ds_read_b128 v[80:83], v169 offset:32768
	ds_read_b128 v[84:87], v169 offset:34816
	ds_read_b128 v[88:91], v169 offset:36864
	ds_read_b128 v[92:95], v169 offset:38912
	s_add_i32 s4, s4, 2
	s_add_i32 s5, s4, 2
	s_min_u32 s5, s5, 15
	s_lshl_b32 s18, s5, 7
	s_add_u32 m0, s101, 0x0
	v_lshl_add_u64 v[210:211], v[152:153], 0, s[18:19]
	global_load_lds_dwordx4 v[210:211], off
	s_add_u32 m0, s101, 0x4000
	v_lshl_add_u64 v[210:211], v[154:155], 0, s[18:19]
	global_load_lds_dwordx4 v[210:211], off
	ds_read_b128 v[128:131], v220 offset:32768
	ds_read_b128 v[132:135], v220 offset:34816
	ds_read_b128 v[136:139], v220 offset:36864
	ds_read_b128 v[140:143], v220 offset:38912
	ds_read_b128 v[192:195], v221 offset:32768
	ds_read_b128 v[196:199], v221 offset:34816
	ds_read_b128 v[200:203], v221 offset:36864
	ds_read_b128 v[204:207], v221 offset:38912
	v_mfma_f32_16x16x32_bf16 v[0:3], v[112:115], v[96:99], v[0:3]
	v_mfma_f32_16x16x32_bf16 v[4:7], v[116:119], v[96:99], v[4:7]
	s_add_u32 m0, s101, 0x1000
	v_lshl_add_u64 v[210:211], v[156:157], 0, s[18:19]
	global_load_lds_dwordx4 v[210:211], off
	v_mfma_f32_16x16x32_bf16 v[8:11], v[120:123], v[96:99], v[8:11]
	v_mfma_f32_16x16x32_bf16 v[12:15], v[124:127], v[96:99], v[12:15]
	s_add_u32 m0, s101, 0x5000
	v_lshl_add_u64 v[210:211], v[158:159], 0, s[18:19]
	global_load_lds_dwordx4 v[210:211], off
	v_mfma_f32_16x16x32_bf16 v[16:19], v[112:115], v[100:103], v[16:19]
	v_mfma_f32_16x16x32_bf16 v[20:23], v[116:119], v[100:103], v[20:23]
	s_add_u32 m0, s101, 0x2000
	v_lshl_add_u64 v[210:211], v[160:161], 0, s[18:19]
	global_load_lds_dwordx4 v[210:211], off
	v_mfma_f32_16x16x32_bf16 v[24:27], v[120:123], v[100:103], v[24:27]
	v_mfma_f32_16x16x32_bf16 v[28:31], v[124:127], v[100:103], v[28:31]
	s_add_u32 m0, s101, 0x6000
	v_lshl_add_u64 v[210:211], v[162:163], 0, s[18:19]
	global_load_lds_dwordx4 v[210:211], off
	v_mfma_f32_16x16x32_bf16 v[32:35], v[112:115], v[104:107], v[32:35]
	v_mfma_f32_16x16x32_bf16 v[36:39], v[116:119], v[104:107], v[36:39]
	s_add_u32 m0, s101, 0x3000
	v_lshl_add_u64 v[210:211], v[164:165], 0, s[18:19]
	global_load_lds_dwordx4 v[210:211], off
	v_mfma_f32_16x16x32_bf16 v[40:43], v[120:123], v[104:107], v[40:43]
	v_mfma_f32_16x16x32_bf16 v[44:47], v[124:127], v[104:107], v[44:47]
	s_add_u32 m0, s101, 0x7000
	v_lshl_add_u64 v[210:211], v[166:167], 0, s[18:19]
	global_load_lds_dwordx4 v[210:211], off
	v_mfma_f32_16x16x32_bf16 v[48:51], v[112:115], v[108:111], v[48:51]
	v_mfma_f32_16x16x32_bf16 v[52:55], v[116:119], v[108:111], v[52:55]
	v_mfma_f32_16x16x32_bf16 v[56:59], v[120:123], v[108:111], v[56:59]
	v_mfma_f32_16x16x32_bf16 v[60:63], v[124:127], v[108:111], v[60:63]
	s_waitcnt lgkmcnt(8)
	v_mfma_f32_16x16x32_bf16 v[0:3], v[80:83], v[64:67], v[0:3]
	v_mfma_f32_16x16x32_bf16 v[4:7], v[84:87], v[64:67], v[4:7]
	v_mfma_f32_16x16x32_bf16 v[8:11], v[88:91], v[64:67], v[8:11]
	v_mfma_f32_16x16x32_bf16 v[12:15], v[92:95], v[64:67], v[12:15]
	v_mfma_f32_16x16x32_bf16 v[16:19], v[80:83], v[68:71], v[16:19]
	v_mfma_f32_16x16x32_bf16 v[20:23], v[84:87], v[68:71], v[20:23]
	v_mfma_f32_16x16x32_bf16 v[24:27], v[88:91], v[68:71], v[24:27]
	v_mfma_f32_16x16x32_bf16 v[28:31], v[92:95], v[68:71], v[28:31]
	v_mfma_f32_16x16x32_bf16 v[32:35], v[80:83], v[72:75], v[32:35]
	v_mfma_f32_16x16x32_bf16 v[36:39], v[84:87], v[72:75], v[36:39]
	v_mfma_f32_16x16x32_bf16 v[40:43], v[88:91], v[72:75], v[40:43]
	v_mfma_f32_16x16x32_bf16 v[44:47], v[92:95], v[72:75], v[44:47]
	v_mfma_f32_16x16x32_bf16 v[48:51], v[80:83], v[76:79], v[48:51]
	v_mfma_f32_16x16x32_bf16 v[52:55], v[84:87], v[76:79], v[52:55]
	v_mfma_f32_16x16x32_bf16 v[56:59], v[88:91], v[76:79], v[56:59]
	v_mfma_f32_16x16x32_bf16 v[60:63], v[92:95], v[76:79], v[60:63]
	s_waitcnt vmcnt(0) lgkmcnt(0)
	s_barrier
	ds_read_b128 v[64:67], v168 offset:0
	ds_read_b128 v[68:71], v168 offset:2048
	ds_read_b128 v[72:75], v168 offset:4096
	ds_read_b128 v[76:79], v168 offset:6144
	ds_read_b128 v[80:83], v169 offset:0
	ds_read_b128 v[84:87], v169 offset:2048
	ds_read_b128 v[88:91], v169 offset:4096
	ds_read_b128 v[92:95], v169 offset:6144
	s_add_i32 s5, s4, 3
	s_min_u32 s5, s5, 15
	s_lshl_b32 s18, s5, 7
	s_add_u32 m0, s101, 0x8000
	v_lshl_add_u64 v[210:211], v[152:153], 0, s[18:19]
	global_load_lds_dwordx4 v[210:211], off
	s_add_u32 m0, s101, 0xc000
	v_lshl_add_u64 v[210:211], v[154:155], 0, s[18:19]
	global_load_lds_dwordx4 v[210:211], off
	ds_read_b128 v[96:99], v220 offset:0
	ds_read_b128 v[100:103], v220 offset:2048
	ds_read_b128 v[104:107], v220 offset:4096
	ds_read_b128 v[108:111], v220 offset:6144
	ds_read_b128 v[112:115], v221 offset:0
	ds_read_b128 v[116:119], v221 offset:2048
	ds_read_b128 v[120:123], v221 offset:4096
	ds_read_b128 v[124:127], v221 offset:6144
	v_mfma_f32_16x16x32_bf16 v[0:3], v[192:195], v[128:131], v[0:3]
	v_mfma_f32_16x16x32_bf16 v[4:7], v[196:199], v[128:131], v[4:7]
	s_add_u32 m0, s101, 0x9000
	v_lshl_add_u64 v[210:211], v[156:157], 0, s[18:19]
	global_load_lds_dwordx4 v[210:211], off
	v_mfma_f32_16x16x32_bf16 v[8:11], v[200:203], v[128:131], v[8:11]
	v_mfma_f32_16x16x32_bf16 v[12:15], v[204:207], v[128:131], v[12:15]
	s_add_u32 m0, s101, 0xd000
	v_lshl_add_u64 v[210:211], v[158:159], 0, s[18:19]
	global_load_lds_dwordx4 v[210:211], off
	v_mfma_f32_16x16x32_bf16 v[16:19], v[192:195], v[132:135], v[16:19]
	v_mfma_f32_16x16x32_bf16 v[20:23], v[196:199], v[132:135], v[20:23]
	s_add_u32 m0, s101, 0xa000
	v_lshl_add_u64 v[210:211], v[160:161], 0, s[18:19]
	global_load_lds_dwordx4 v[210:211], off
	v_mfma_f32_16x16x32_bf16 v[24:27], v[200:203], v[132:135], v[24:27]
	v_mfma_f32_16x16x32_bf16 v[28:31], v[204:207], v[132:135], v[28:31]
	s_add_u32 m0, s101, 0xe000
	v_lshl_add_u64 v[210:211], v[162:163], 0, s[18:19]
	global_load_lds_dwordx4 v[210:211], off
	v_mfma_f32_16x16x32_bf16 v[32:35], v[192:195], v[136:139], v[32:35]
	v_mfma_f32_16x16x32_bf16 v[36:39], v[196:199], v[136:139], v[36:39]
	s_add_u32 m0, s101, 0xb000
	v_lshl_add_u64 v[210:211], v[164:165], 0, s[18:19]
	global_load_lds_dwordx4 v[210:211], off
	v_mfma_f32_16x16x32_bf16 v[40:43], v[200:203], v[136:139], v[40:43]
	v_mfma_f32_16x16x32_bf16 v[44:47], v[204:207], v[136:139], v[44:47]
	s_add_u32 m0, s101, 0xf000
	v_lshl_add_u64 v[210:211], v[166:167], 0, s[18:19]
	global_load_lds_dwordx4 v[210:211], off
	v_mfma_f32_16x16x32_bf16 v[48:51], v[192:195], v[140:143], v[48:51]
	v_mfma_f32_16x16x32_bf16 v[52:55], v[196:199], v[140:143], v[52:55]
	v_mfma_f32_16x16x32_bf16 v[56:59], v[200:203], v[140:143], v[56:59]
	v_mfma_f32_16x16x32_bf16 v[60:63], v[204:207], v[140:143], v[60:63]
	s_waitcnt lgkmcnt(8)
; DI float ssq_f(u64 v) { return (float)v * (1.f / 1048576.f); }
; #define SB_ __builtin_amdgcn_sched_barrier(0)
; template <bool SWAP, bool HALF>
; DI void gemm_mainloop(const GemmDesc& d, int m0, int n0, bf16_t* smem, f32x16 (&acc)[2][2], int dry) {
;     ...
;   auto stage = [&](int cur, u32x4 (&ran)[4], u32x4 (&rbn)[4], int ks) {
;     ldf(cur, 1, 1); SB_;
;     mma(0); SB_;
;     ldf(cur, 2, 0); SB_;
;     lw(ran, rbn, cur ^ 1);
;     gl(ran, rbn, (ks + 3 < nk) ? ks + 3 : nk - 1);
;     SB_;
;     mma(1); SB_;
;     __syncthreads();
;     ldf(cur, 3, 1); SB_;
;     mma(0); SB_;
;     ldf(cur ^ 1, 0, 0);
;     SB_;
;     mma(1); SB_;
;     __syncthreads();
;   };
;   gl(ra0, rb0, 0);
;   gl(ra1, rb1, 1);
;   lw(ra0, rb0, 0);
;   gl(ra0, rb0, 2);
;   __syncthreads();
;   ldf(0, 0, 0);
; #pragma unroll 1
;   for (int ks = 0; ks < nk; ks += 2) {
;     stage(0, ra1, rb1, ks);
;     stage(1, ra0, rb0, ks + 1);
;   }
; DI void gemm_tile(const GemmDesc& d, int m0, int n0, bf16_t* smem, int dry) {
;     ...
;   } else if (t < 128) {
;     rs_s[t] = rsqrtf(ssq_f(myss) * d.inv_dim + EPS);
;   }
	v_mfma_f32_16x16x32_bf16 v[0:3], v[80:83], v[64:67], v[0:3]
	v_mfma_f32_16x16x32_bf16 v[4:7], v[84:87], v[64:67], v[4:7]
	v_mfma_f32_16x16x32_bf16 v[8:11], v[88:91], v[64:67], v[8:11]
	v_mfma_f32_16x16x32_bf16 v[12:15], v[92:95], v[64:67], v[12:15]
	v_mfma_f32_16x16x32_bf16 v[16:19], v[80:83], v[68:71], v[16:19]
	v_mfma_f32_16x16x32_bf16 v[20:23], v[84:87], v[68:71], v[20:23]
	v_mfma_f32_16x16x32_bf16 v[24:27], v[88:91], v[68:71], v[24:27]
	v_mfma_f32_16x16x32_bf16 v[28:31], v[92:95], v[68:71], v[28:31]
	v_mfma_f32_16x16x32_bf16 v[32:35], v[80:83], v[72:75], v[32:35]
	v_mfma_f32_16x16x32_bf16 v[36:39], v[84:87], v[72:75], v[36:39]
	v_mfma_f32_16x16x32_bf16 v[40:43], v[88:91], v[72:75], v[40:43]
	v_mfma_f32_16x16x32_bf16 v[44:47], v[92:95], v[72:75], v[44:47]
	v_mfma_f32_16x16x32_bf16 v[48:51], v[80:83], v[76:79], v[48:51]
	v_mfma_f32_16x16x32_bf16 v[52:55], v[84:87], v[76:79], v[52:55]
	v_mfma_f32_16x16x32_bf16 v[56:59], v[88:91], v[76:79], v[56:59]
	v_mfma_f32_16x16x32_bf16 v[60:63], v[92:95], v[76:79], v[60:63]
	s_cmp_lt_u32 s4, 12
	s_waitcnt vmcnt(0) lgkmcnt(0)
	s_barrier
	s_cbranch_scc1 .LBB0_192
	ds_read_b128 v[64:67], v168 offset:32768
	ds_read_b128 v[68:71], v168 offset:34816
	ds_read_b128 v[72:75], v168 offset:36864
	ds_read_b128 v[76:79], v168 offset:38912
	ds_read_b128 v[80:83], v169 offset:32768
	ds_read_b128 v[84:87], v169 offset:34816
	ds_read_b128 v[88:91], v169 offset:36864
	ds_read_b128 v[92:95], v169 offset:38912
	ds_read_b128 v[128:131], v220 offset:32768
	ds_read_b128 v[132:135], v220 offset:34816
	ds_read_b128 v[136:139], v220 offset:36864
	ds_read_b128 v[140:143], v220 offset:38912
	ds_read_b128 v[192:195], v221 offset:32768
	ds_read_b128 v[196:199], v221 offset:34816
	ds_read_b128 v[200:203], v221 offset:36864
	ds_read_b128 v[204:207], v221 offset:38912
	v_mfma_f32_16x16x32_bf16 v[0:3], v[112:115], v[96:99], v[0:3]
	v_mfma_f32_16x16x32_bf16 v[4:7], v[116:119], v[96:99], v[4:7]
	v_mfma_f32_16x16x32_bf16 v[8:11], v[120:123], v[96:99], v[8:11]
	v_mfma_f32_16x16x32_bf16 v[12:15], v[124:127], v[96:99], v[12:15]
	v_mfma_f32_16x16x32_bf16 v[16:19], v[112:115], v[100:103], v[16:19]
	v_mfma_f32_16x16x32_bf16 v[20:23], v[116:119], v[100:103], v[20:23]
	v_mfma_f32_16x16x32_bf16 v[24:27], v[120:123], v[100:103], v[24:27]
	v_mfma_f32_16x16x32_bf16 v[28:31], v[124:127], v[100:103], v[28:31]
	v_mfma_f32_16x16x32_bf16 v[32:35], v[112:115], v[104:107], v[32:35]
	v_mfma_f32_16x16x32_bf16 v[36:39], v[116:119], v[104:107], v[36:39]
	v_mfma_f32_16x16x32_bf16 v[40:43], v[120:123], v[104:107], v[40:43]
	v_mfma_f32_16x16x32_bf16 v[44:47], v[124:127], v[104:107], v[44:47]
	v_mfma_f32_16x16x32_bf16 v[48:51], v[112:115], v[108:111], v[48:51]
	v_mfma_f32_16x16x32_bf16 v[52:55], v[116:119], v[108:111], v[52:55]
	v_mfma_f32_16x16x32_bf16 v[56:59], v[120:123], v[108:111], v[56:59]
	v_mfma_f32_16x16x32_bf16 v[60:63], v[124:127], v[108:111], v[60:63]
	s_waitcnt lgkmcnt(8)
	v_mfma_f32_16x16x32_bf16 v[0:3], v[80:83], v[64:67], v[0:3]
	v_mfma_f32_16x16x32_bf16 v[4:7], v[84:87], v[64:67], v[4:7]
	v_mfma_f32_16x16x32_bf16 v[8:11], v[88:91], v[64:67], v[8:11]
	v_mfma_f32_16x16x32_bf16 v[12:15], v[92:95], v[64:67], v[12:15]
	v_mfma_f32_16x16x32_bf16 v[16:19], v[80:83], v[68:71], v[16:19]
	v_mfma_f32_16x16x32_bf16 v[20:23], v[84:87], v[68:71], v[20:23]
	v_mfma_f32_16x16x32_bf16 v[24:27], v[88:91], v[68:71], v[24:27]
	v_mfma_f32_16x16x32_bf16 v[28:31], v[92:95], v[68:71], v[28:31]
	v_mfma_f32_16x16x32_bf16 v[32:35], v[80:83], v[72:75], v[32:35]
	v_mfma_f32_16x16x32_bf16 v[36:39], v[84:87], v[72:75], v[36:39]
	v_mfma_f32_16x16x32_bf16 v[40:43], v[88:91], v[72:75], v[40:43]
	v_mfma_f32_16x16x32_bf16 v[44:47], v[92:95], v[72:75], v[44:47]
	v_mfma_f32_16x16x32_bf16 v[48:51], v[80:83], v[76:79], v[48:51]
	v_mfma_f32_16x16x32_bf16 v[52:55], v[84:87], v[76:79], v[52:55]
	v_mfma_f32_16x16x32_bf16 v[56:59], v[88:91], v[76:79], v[56:59]
	v_mfma_f32_16x16x32_bf16 v[60:63], v[92:95], v[76:79], v[60:63]
	s_waitcnt lgkmcnt(0)
	s_barrier
	v_mfma_f32_16x16x32_bf16 v[0:3], v[192:195], v[128:131], v[0:3]
	v_mfma_f32_16x16x32_bf16 v[4:7], v[196:199], v[128:131], v[4:7]
	v_mfma_f32_16x16x32_bf16 v[8:11], v[200:203], v[128:131], v[8:11]
	v_mfma_f32_16x16x32_bf16 v[12:15], v[204:207], v[128:131], v[12:15]
	v_mfma_f32_16x16x32_bf16 v[16:19], v[192:195], v[132:135], v[16:19]
	v_mfma_f32_16x16x32_bf16 v[20:23], v[196:199], v[132:135], v[20:23]
	v_mfma_f32_16x16x32_bf16 v[24:27], v[200:203], v[132:135], v[24:27]
	v_mfma_f32_16x16x32_bf16 v[28:31], v[204:207], v[132:135], v[28:31]
	v_mfma_f32_16x16x32_bf16 v[32:35], v[192:195], v[136:139], v[32:35]
	v_mfma_f32_16x16x32_bf16 v[36:39], v[196:199], v[136:139], v[36:39]
	v_mfma_f32_16x16x32_bf16 v[40:43], v[200:203], v[136:139], v[40:43]
	v_mfma_f32_16x16x32_bf16 v[44:47], v[204:207], v[136:139], v[44:47]
	v_mfma_f32_16x16x32_bf16 v[48:51], v[192:195], v[140:143], v[48:51]
	v_mfma_f32_16x16x32_bf16 v[52:55], v[196:199], v[140:143], v[52:55]
	v_mfma_f32_16x16x32_bf16 v[56:59], v[200:203], v[140:143], v[56:59]
	v_mfma_f32_16x16x32_bf16 v[60:63], v[204:207], v[140:143], v[60:63]
	s_and_saveexec_b64 s[4:5], s[42:43]
	s_cbranch_execz .LBB0_195
	s_mov_b32 s8, 0x800000
	s_waitcnt vmcnt(15)
	v_mul_f32_e32 v64, 0x4b800000, v171
	v_cmp_gt_f32_e32 vcc, s8, v171
	v_lshl_add_u32 v65, v150, 2, v181
	s_nop 0
	v_cndmask_b32_e32 v64, v171, v64, vcc
	v_rsq_f32_e32 v64, v64
	s_nop 0
	v_mul_f32_e32 v66, 0x45800000, v64
	v_cndmask_b32_e32 v64, v64, v66, vcc
	ds_write_b32 v65, v64

; DI int otid() { int t = threadIdx.x; asm volatile("" : "+v"(t)); return t; }
; template <bool SWAP, bool HALF>
; DI void gemm_mainloop(const GemmDesc& d, int m0, int n0, bf16_t* smem, f32x16 (&acc)[2][2], int dry) {
;   const int t = otid(), lane = t & 63, w = t >> 6, wm = w >> 1, wn = w & 1, r = lane & 31, hh = lane >> 5;
;   const int lrow = t >> 3, lkc = t & 7;
;   const bf16_t* ap[4]; const bf16_t* bp[4];
; #pragma unroll
;   for (int i = 0; i < 4; ++i) {
;     int am = m0 + lrow + 32 * i; am = am < M ? am : M - 1;
;     ap[i] = d.A + (size_t)am * d.lda + lkc * 8 + (d.a_grp ? (n0 / d.a_grp) * d.a_grp : 0);
;     bp[i] = d.Bt + (size_t)(n0 + lrow + 32 * i) * d.ldb + lkc * 8;
;   }
; #pragma unroll
;   for (int a = 0; a < 2; ++a)
; #pragma unroll
;     for (int b = 0; b < 2; ++b)
; #pragma unroll
;       for (int i = 0; i < 16; ++i) acc[a][b][i] = 0.f;
;   u32x4 ra0[4], rb0[4], ra1[4], rb1[4];
;   const int nk = d.K >> 6;
;   const int lds_w = lrow * LST + lkc * 8;
;     ...
;   for (int i = slot; i < total; i += nslots) {
;     const int g = i / (8 * nN), j = i - g * 8 * nN;
;     const int gm = (cx - g * 8) < 8 ? (cx - g * 8) : 8;
;     const int mt = (g * 8 + j % gm) * 8 + x, nt = j / gm;
;     gemm_tile(d, mt * 128, nt * 128, smem, dry);
.LBB0_500:
	s_lshr_b32 s1, s8, 3
	s_and_b32 s1, s1, 0xffffff8
	v_readlane_b32 s5, v228, 38
	s_sub_i32 s5, s5, s1
	s_min_i32 s5, s5, 8
	s_abs_i32 s9, s5
	v_cvt_f32_u32_e32 v0, s9
	s_sub_i32 s10, 0, s9
	s_lshl_b32 s4, s1, 3
	s_sub_i32 s4, s8, s4
	v_rcp_iflag_f32_e32 v0, v0
	s_abs_i32 s7, s4
	s_xor_b32 s6, s4, s5
	s_ashr_i32 s6, s6, 31
	v_mul_f32_e32 v0, 0x4f7ffffe, v0
	v_cvt_u32_f32_e32 v0, v0
	v_mov_b32_e32 v150, v172
	v_mov_b32_e32 v32, v172
	v_readfirstlane_b32 s11, v0
	s_mul_i32 s10, s10, s11
	s_mul_hi_u32 s10, s11, s10
	s_add_i32 s11, s11, s10
	s_mul_hi_u32 s10, s7, s11
	s_mul_i32 s11, s10, s9
	s_sub_i32 s7, s7, s11
	s_add_i32 s11, s10, 1
	s_sub_i32 s12, s7, s9
	s_cmp_ge_u32 s7, s9
	s_cselect_b32 s10, s11, s10
	s_cselect_b32 s7, s12, s7
	s_add_i32 s11, s10, 1
	s_cmp_ge_u32 s7, s9
	s_cselect_b32 s7, s11, s10
	s_xor_b32 s7, s7, s6
	s_sub_i32 s6, s7, s6
	s_mul_i32 s5, s6, s5
	s_sub_i32 s4, s4, s5
	s_add_i32 s1, s1, s4
	s_lshl_b32 s4, s6, 7
	s_lshl_b32 s1, s1, 10
	v_ashrrev_i32_e32 v10, 3, v32
	v_lshlrev_b32_e32 v0, 3, v32
	v_and_b32_e32 v33, 56, v0
	v_add_u32_e32 v2, s4, v10
	v_readlane_b32 s44, v228, 56
	s_or_b32 s9, s1, s29
	v_lshlrev_b32_e32 v144, 1, v33
	v_readlane_b32 s45, v228, 57
	v_ashrrev_i32_e32 v3, 31, v2
	v_add_u32_e32 v11, s9, v10
	v_lshl_add_u64 v[4:5], s[44:45], 0, v[144:145]
	v_lshlrev_b64 v[2:3], 11, v[2:3]
	v_lshl_add_u64 v[154:155], v[4:5], 0, v[2:3]
	v_min_i32_e32 v2, 0x801f, v11
	v_ashrrev_i32_e32 v3, 31, v2
	v_lshl_add_u64 v[0:1], s[68:69], 0, v[144:145]
	v_lshlrev_b64 v[2:3], 11, v[2:3]
	v_lshl_add_u64 v[8:9], v[0:1], 0, v[2:3]
	v_min_i32_e32 v2, 0x7fff, v11
	v_ashrrev_i32_e32 v3, 31, v2
	v_min_i32_e32 v6, 0x803f, v11
	v_lshlrev_b64 v[2:3], 11, v[2:3]
	v_ashrrev_i32_e32 v7, 31, v6
	v_lshl_add_u64 v[16:17], v[0:1], 0, v[2:3]
	v_min_i32_e32 v2, 0x7fdf, v11
	v_lshlrev_b64 v[6:7], 11, v[6:7]
	v_ashrrev_i32_e32 v3, 31, v2
	v_lshl_add_u64 v[152:153], v[0:1], 0, v[6:7]
	v_lshlrev_b64 v[2:3], 11, v[2:3]
	v_lshl_add_u64 v[24:25], v[0:1], 0, v[2:3]
	s_mov_b64 s[6:7], 0x10000
	v_lshl_add_u64 v[156:157], v[8:9], 0, s[6:7]
	v_lshl_add_u64 v[158:159], v[154:155], 0, s[6:7]
	s_mov_b64 s[6:7], 0x20000
	v_lshl_add_u64 v[160:161], v[16:17], 0, s[6:7]
	v_lshl_add_u64 v[162:163], v[154:155], 0, s[6:7]
	s_mov_b64 s[6:7], 0x30000
	s_movk_i32 s1, 0x48
	v_lshl_add_u64 v[164:165], v[24:25], 0, s[6:7]
	v_lshl_add_u64 v[166:167], v[154:155], 0, s[6:7]
	v_and_b32_e32 v34, 31, v32
	v_mul_lo_u32 v35, v10, s1
	v_readlane_b32 s46, v228, 58
	v_readlane_b32 s47, v228, 59
	s_mov_b32 s1, 0x10000
	v_add_co_u32_e32 v8, vcc, s1, v8
	s_nop 1
	v_addc_co_u32_e32 v9, vcc, 0, v9, vcc
	s_waitcnt vmcnt(19)
	v_add_co_u32_e32 v12, vcc, s1, v154
	s_nop 1
	v_addc_co_u32_e32 v13, vcc, 0, v155, vcc
	s_mov_b32 s1, 0x20000
	v_add_co_u32_e32 v16, vcc, s1, v16
	s_nop 1
	v_addc_co_u32_e32 v17, vcc, 0, v17, vcc
	v_add_co_u32_e32 v20, vcc, s1, v154
	s_nop 1
	v_addc_co_u32_e32 v21, vcc, 0, v155, vcc
	s_mov_b32 s1, 0x30000
	v_add_co_u32_e32 v24, vcc, s1, v24
	s_nop 1
	v_addc_co_u32_e32 v25, vcc, 0, v25, vcc
	v_add_co_u32_e32 v28, vcc, s1, v154
	s_nop 1
	v_addc_co_u32_e32 v29, vcc, 0, v155, vcc
	s_nop 0
	v_add_lshl_u32 v144, v35, v33, 1
	s_waitcnt vmcnt(15)
	s_waitcnt vmcnt(14)
	s_waitcnt vmcnt(13)
	s_waitcnt vmcnt(12)
	s_waitcnt vmcnt(11)
	s_waitcnt vmcnt(10)
	s_waitcnt vmcnt(9)
	s_waitcnt vmcnt(8)
	v_lshrrev_b32_e32 v0, 1, v32
	v_and_or_b32 v1, v0, s72, v34
	v_and_b32_e32 v0, 16, v0
	s_movk_i32 s1, 0x90
	v_mad_u64_u32 v[168:169], s[6:7], v1, s1, v[0:1]
	v_and_b32_e32 v1, 0x5f, v32
	v_mul_u32_u24_e32 v1, 0x48, v1
	v_lshl_add_u32 v169, v1, 1, v0
	v_bfe_u32 v212, v172, 4, 3
	v_lshlrev_b32_e32 v212, 4, v212
	v_xor_b32_e32 v152, v152, v212
	v_xor_b32_e32 v154, v154, v212
	v_xor_b32_e32 v156, v156, v212
	v_xor_b32_e32 v158, v158, v212
	v_xor_b32_e32 v160, v160, v212
	v_xor_b32_e32 v162, v162, v212
	v_xor_b32_e32 v164, v164, v212
	v_xor_b32_e32 v166, v166, v212
	v_lshrrev_b32_e32 v213, 6, v172
	s_nop 1
	v_readfirstlane_b32 s101, v213
	s_lshl_b32 s101, s101, 10
	s_add_u32 m0, s101, 0x0
	s_nop 0
	global_load_lds_dwordx4 v[152:153], off
	s_add_u32 m0, s101, 0x4000
	s_nop 0
	global_load_lds_dwordx4 v[154:155], off
	s_add_u32 m0, s101, 0x1000
	s_nop 0
	global_load_lds_dwordx4 v[156:157], off
	s_add_u32 m0, s101, 0x5000
	s_nop 0
	global_load_lds_dwordx4 v[158:159], off
	s_add_u32 m0, s101, 0x2000
	s_nop 0
	global_load_lds_dwordx4 v[160:161], off
	s_add_u32 m0, s101, 0x6000
	s_nop 0
	global_load_lds_dwordx4 v[162:163], off
	s_add_u32 m0, s101, 0x3000
	s_nop 0
	global_load_lds_dwordx4 v[164:165], off
	s_add_u32 m0, s101, 0x7000
	s_nop 0
	global_load_lds_dwordx4 v[166:167], off
	v_and_b32_e32 v212, 15, v172
	v_bfe_u32 v213, v172, 4, 2
	v_lshrrev_b32_e32 v214, 1, v212
	v_xor_b32_e32 v213, v213, v214
	v_lshlrev_b32_e32 v213, 4, v213
	v_lshl_or_b32 v212, v212, 7, v213
	v_lshrrev_b32_e32 v214, 7, v172
	v_lshl_add_u32 v168, v214, 13, v212
	v_bfe_u32 v214, v172, 6, 1
	v_lshl_add_u32 v169, v214, 13, v212
	v_add_u32_e32 v169, 0x4000, v169
	v_xor_b32_e32 v220, 64, v168
	v_xor_b32_e32 v221, 64, v169
	s_waitcnt vmcnt(0) lgkmcnt(0)
	s_barrier
; #define SB_ __builtin_amdgcn_sched_barrier(0)
; template <bool SWAP, bool HALF>
; DI void gemm_mainloop(const GemmDesc& d, int m0, int n0, bf16_t* smem, f32x16 (&acc)[2][2], int dry) {
;     ...
;   for (int a = 0; a < 2; ++a)
; #pragma unroll
;     for (int b = 0; b < 2; ++b)
; #pragma unroll
;       for (int i = 0; i < 16; ++i) acc[a][b][i] = 0.f;
;     ...
;   auto stage = [&](int cur, u32x4 (&ran)[4], u32x4 (&rbn)[4], int ks) {
;     ldf(cur, 1, 1); SB_;
;     mma(0); SB_;
;     ldf(cur, 2, 0); SB_;
;     lw(ran, rbn, cur ^ 1);
;     gl(ran, rbn, (ks + 3 < nk) ? ks + 3 : nk - 1);
;     SB_;
;     mma(1); SB_;
;     __syncthreads();
;     ldf(cur, 3, 1); SB_;
;     mma(0); SB_;
;     ldf(cur ^ 1, 0, 0);
;     SB_;
;     mma(1); SB_;
;     __syncthreads();
;   };
;   gl(ra0, rb0, 0);
;   gl(ra1, rb1, 1);
;   lw(ra0, rb0, 0);
;   gl(ra0, rb0, 2);
;   __syncthreads();
;   ldf(0, 0, 0);
; #pragma unroll 1
;   for (int ks = 0; ks < nk; ks += 2) {
;     stage(0, ra1, rb1, ks);
	v_mov_b32_e32 v0, 0
	v_add_u32_e32 v170, 0x9000, v144
	s_mov_b32 s1, -2
	v_mov_b32_e32 v1, v0
	v_mov_b32_e32 v2, v0
	v_mov_b32_e32 v3, v0
	v_mov_b32_e32 v4, v0
	v_mov_b32_e32 v5, v0
	v_mov_b32_e32 v6, v0
	v_mov_b32_e32 v7, v0
	v_mov_b32_e32 v8, v0
	v_mov_b32_e32 v9, v0
	v_mov_b32_e32 v10, v0
	v_mov_b32_e32 v11, v0
	v_mov_b32_e32 v12, v0
	v_mov_b32_e32 v13, v0
	v_mov_b32_e32 v14, v0
	v_mov_b32_e32 v15, v0
	v_mov_b32_e32 v16, v0
	v_mov_b32_e32 v17, v0
	v_mov_b32_e32 v18, v0
	v_mov_b32_e32 v19, v0
	v_mov_b32_e32 v20, v0
	v_mov_b32_e32 v21, v0
	v_mov_b32_e32 v22, v0
	v_mov_b32_e32 v23, v0
	v_mov_b32_e32 v24, v0
	v_mov_b32_e32 v25, v0
	v_mov_b32_e32 v26, v0
	v_mov_b32_e32 v27, v0
	v_mov_b32_e32 v28, v0
	v_mov_b32_e32 v29, v0
	v_mov_b32_e32 v30, v0
	v_mov_b32_e32 v31, v0
	v_mov_b32_e32 v32, v0
	v_mov_b32_e32 v33, v0
	v_mov_b32_e32 v34, v0
	v_mov_b32_e32 v35, v0
	v_mov_b32_e32 v36, v0
	v_mov_b32_e32 v37, v0
	v_mov_b32_e32 v38, v0
	v_mov_b32_e32 v39, v0
	v_mov_b32_e32 v40, v0
	v_mov_b32_e32 v41, v0
	v_mov_b32_e32 v42, v0
	v_mov_b32_e32 v43, v0
	v_mov_b32_e32 v44, v0
	v_mov_b32_e32 v45, v0
	v_mov_b32_e32 v46, v0
	v_mov_b32_e32 v47, v0
	v_mov_b32_e32 v48, v0
	v_mov_b32_e32 v49, v0
	v_mov_b32_e32 v50, v0
	v_mov_b32_e32 v51, v0
	v_mov_b32_e32 v52, v0
	v_mov_b32_e32 v53, v0
	v_mov_b32_e32 v54, v0
	v_mov_b32_e32 v55, v0
	v_mov_b32_e32 v56, v0
	v_mov_b32_e32 v57, v0
	v_mov_b32_e32 v58, v0
	v_mov_b32_e32 v59, v0
	v_mov_b32_e32 v60, v0
	v_mov_b32_e32 v61, v0
	v_mov_b32_e32 v62, v0
	v_mov_b32_e32 v63, v0
	ds_read_b128 v[64:67], v168 offset:0
	ds_read_b128 v[68:71], v168 offset:2048
	ds_read_b128 v[72:75], v168 offset:4096
	ds_read_b128 v[76:79], v168 offset:6144
	ds_read_b128 v[80:83], v169 offset:0
	ds_read_b128 v[84:87], v169 offset:2048
	ds_read_b128 v[88:91], v169 offset:4096
	ds_read_b128 v[92:95], v169 offset:6144
	s_add_i32 s5, s1, 3
	s_min_u32 s5, s5, 15
	s_lshl_b32 s18, s5, 7
	s_add_u32 m0, s101, 0x8000
	v_lshl_add_u64 v[210:211], v[152:153], 0, s[18:19]
	global_load_lds_dwordx4 v[210:211], off
	s_add_u32 m0, s101, 0xc000
	v_lshl_add_u64 v[210:211], v[154:155], 0, s[18:19]
	global_load_lds_dwordx4 v[210:211], off
	ds_read_b128 v[96:99], v220 offset:0
	ds_read_b128 v[100:103], v220 offset:2048
	ds_read_b128 v[104:107], v220 offset:4096
	ds_read_b128 v[108:111], v220 offset:6144
	ds_read_b128 v[112:115], v221 offset:0
	ds_read_b128 v[116:119], v221 offset:2048
	ds_read_b128 v[120:123], v221 offset:4096
	ds_read_b128 v[124:127], v221 offset:6144
	s_waitcnt lgkmcnt(8)
	v_mfma_f32_16x16x32_bf16 v[0:3], v[80:83], v[64:67], v[0:3]
	v_mfma_f32_16x16x32_bf16 v[4:7], v[84:87], v[64:67], v[4:7]
	s_add_u32 m0, s101, 0x9000
	v_lshl_add_u64 v[210:211], v[156:157], 0, s[18:19]
	global_load_lds_dwordx4 v[210:211], off
	v_mfma_f32_16x16x32_bf16 v[8:11], v[88:91], v[64:67], v[8:11]
	v_mfma_f32_16x16x32_bf16 v[12:15], v[92:95], v[64:67], v[12:15]
	s_add_u32 m0, s101, 0xd000
	v_lshl_add_u64 v[210:211], v[158:159], 0, s[18:19]
	global_load_lds_dwordx4 v[210:211], off
	v_mfma_f32_16x16x32_bf16 v[16:19], v[80:83], v[68:71], v[16:19]
	v_mfma_f32_16x16x32_bf16 v[20:23], v[84:87], v[68:71], v[20:23]
	s_add_u32 m0, s101, 0xa000
	v_lshl_add_u64 v[210:211], v[160:161], 0, s[18:19]
	global_load_lds_dwordx4 v[210:211], off
	v_mfma_f32_16x16x32_bf16 v[24:27], v[88:91], v[68:71], v[24:27]
	v_mfma_f32_16x16x32_bf16 v[28:31], v[92:95], v[68:71], v[28:31]
	s_add_u32 m0, s101, 0xe000
	v_lshl_add_u64 v[210:211], v[162:163], 0, s[18:19]
	global_load_lds_dwordx4 v[210:211], off
	v_mfma_f32_16x16x32_bf16 v[32:35], v[80:83], v[72:75], v[32:35]
	v_mfma_f32_16x16x32_bf16 v[36:39], v[84:87], v[72:75], v[36:39]
	s_add_u32 m0, s101, 0xb000
	v_lshl_add_u64 v[210:211], v[164:165], 0, s[18:19]
	global_load_lds_dwordx4 v[210:211], off
	v_mfma_f32_16x16x32_bf16 v[40:43], v[88:91], v[72:75], v[40:43]
	v_mfma_f32_16x16x32_bf16 v[44:47], v[92:95], v[72:75], v[44:47]
	s_add_u32 m0, s101, 0xf000
	v_lshl_add_u64 v[210:211], v[166:167], 0, s[18:19]
	global_load_lds_dwordx4 v[210:211], off
	v_mfma_f32_16x16x32_bf16 v[48:51], v[80:83], v[76:79], v[48:51]
	v_mfma_f32_16x16x32_bf16 v[52:55], v[84:87], v[76:79], v[52:55]
	v_mfma_f32_16x16x32_bf16 v[56:59], v[88:91], v[76:79], v[56:59]
	v_mfma_f32_16x16x32_bf16 v[60:63], v[92:95], v[76:79], v[60:63]
	s_waitcnt vmcnt(0) lgkmcnt(0)
	s_barrier
; #define SB_ __builtin_amdgcn_sched_barrier(0)
; template <bool SWAP, bool HALF>
; DI void gemm_mainloop(const GemmDesc& d, int m0, int n0, bf16_t* smem, f32x16 (&acc)[2][2], int dry) {
;     ...
;   auto stage = [&](int cur, u32x4 (&ran)[4], u32x4 (&rbn)[4], int ks) {
;     ldf(cur, 1, 1); SB_;
;     mma(0); SB_;
;     ldf(cur, 2, 0); SB_;
;     lw(ran, rbn, cur ^ 1);
;     gl(ran, rbn, (ks + 3 < nk) ? ks + 3 : nk - 1);
;     SB_;
;     mma(1); SB_;
;     __syncthreads();
;     ldf(cur, 3, 1); SB_;
;     mma(0); SB_;
;     ldf(cur ^ 1, 0, 0);
;     SB_;
;     mma(1); SB_;
;     __syncthreads();
;   };
;   gl(ra0, rb0, 0);
;   gl(ra1, rb1, 1);
;   lw(ra0, rb0, 0);
;   gl(ra0, rb0, 2);
;   __syncthreads();
;   ldf(0, 0, 0);
; #pragma unroll 1
;   for (int ks = 0; ks < nk; ks += 2) {
;     stage(0, ra1, rb1, ks);
;     stage(1, ra0, rb0, ks + 1);
;   }
.LBB0_501:
	ds_read_b128 v[64:67], v168 offset:32768
	ds_read_b128 v[68:71], v168 offset:34816
	ds_read_b128 v[72:75], v168 offset:36864
	ds_read_b128 v[76:79], v168 offset:38912
	ds_read_b128 v[80:83], v169 offset:32768
	ds_read_b128 v[84:87], v169 offset:34816
	ds_read_b128 v[88:91], v169 offset:36864
	ds_read_b128 v[92:95], v169 offset:38912
	s_add_i32 s1, s1, 2
	s_add_i32 s5, s1, 2
	s_min_u32 s5, s5, 15
	s_lshl_b32 s18, s5, 7
	s_add_u32 m0, s101, 0x0
	v_lshl_add_u64 v[210:211], v[152:153], 0, s[18:19]
	global_load_lds_dwordx4 v[210:211], off
	s_add_u32 m0, s101, 0x4000
	v_lshl_add_u64 v[210:211], v[154:155], 0, s[18:19]
	global_load_lds_dwordx4 v[210:211], off
	ds_read_b128 v[128:131], v220 offset:32768
	ds_read_b128 v[132:135], v220 offset:34816
	ds_read_b128 v[136:139], v220 offset:36864
	ds_read_b128 v[140:143], v220 offset:38912
	ds_read_b128 v[192:195], v221 offset:32768
	ds_read_b128 v[196:199], v221 offset:34816
	ds_read_b128 v[200:203], v221 offset:36864
	ds_read_b128 v[204:207], v221 offset:38912
	v_mfma_f32_16x16x32_bf16 v[0:3], v[112:115], v[96:99], v[0:3]
	v_mfma_f32_16x16x32_bf16 v[4:7], v[116:119], v[96:99], v[4:7]
	s_add_u32 m0, s101, 0x1000
	v_lshl_add_u64 v[210:211], v[156:157], 0, s[18:19]
	global_load_lds_dwordx4 v[210:211], off
	v_mfma_f32_16x16x32_bf16 v[8:11], v[120:123], v[96:99], v[8:11]
	v_mfma_f32_16x16x32_bf16 v[12:15], v[124:127], v[96:99], v[12:15]
	s_add_u32 m0, s101, 0x5000
	v_lshl_add_u64 v[210:211], v[158:159], 0, s[18:19]
	global_load_lds_dwordx4 v[210:211], off
	v_mfma_f32_16x16x32_bf16 v[16:19], v[112:115], v[100:103], v[16:19]
	v_mfma_f32_16x16x32_bf16 v[20:23], v[116:119], v[100:103], v[20:23]
	s_add_u32 m0, s101, 0x2000
	v_lshl_add_u64 v[210:211], v[160:161], 0, s[18:19]
	global_load_lds_dwordx4 v[210:211], off
	v_mfma_f32_16x16x32_bf16 v[24:27], v[120:123], v[100:103], v[24:27]
	v_mfma_f32_16x16x32_bf16 v[28:31], v[124:127], v[100:103], v[28:31]
	s_add_u32 m0, s101, 0x6000
	v_lshl_add_u64 v[210:211], v[162:163], 0, s[18:19]
	global_load_lds_dwordx4 v[210:211], off
	v_mfma_f32_16x16x32_bf16 v[32:35], v[112:115], v[104:107], v[32:35]
	v_mfma_f32_16x16x32_bf16 v[36:39], v[116:119], v[104:107], v[36:39]
	s_add_u32 m0, s101, 0x3000
	v_lshl_add_u64 v[210:211], v[164:165], 0, s[18:19]
	global_load_lds_dwordx4 v[210:211], off
	v_mfma_f32_16x16x32_bf16 v[40:43], v[120:123], v[104:107], v[40:43]
	v_mfma_f32_16x16x32_bf16 v[44:47], v[124:127], v[104:107], v[44:47]
	s_add_u32 m0, s101, 0x7000
	v_lshl_add_u64 v[210:211], v[166:167], 0, s[18:19]
	global_load_lds_dwordx4 v[210:211], off
	v_mfma_f32_16x16x32_bf16 v[48:51], v[112:115], v[108:111], v[48:51]
	v_mfma_f32_16x16x32_bf16 v[52:55], v[116:119], v[108:111], v[52:55]
	v_mfma_f32_16x16x32_bf16 v[56:59], v[120:123], v[108:111], v[56:59]
	v_mfma_f32_16x16x32_bf16 v[60:63], v[124:127], v[108:111], v[60:63]
	s_waitcnt lgkmcnt(8)
	v_mfma_f32_16x16x32_bf16 v[0:3], v[80:83], v[64:67], v[0:3]
	v_mfma_f32_16x16x32_bf16 v[4:7], v[84:87], v[64:67], v[4:7]
	v_mfma_f32_16x16x32_bf16 v[8:11], v[88:91], v[64:67], v[8:11]
	v_mfma_f32_16x16x32_bf16 v[12:15], v[92:95], v[64:67], v[12:15]
	v_mfma_f32_16x16x32_bf16 v[16:19], v[80:83], v[68:71], v[16:19]
	v_mfma_f32_16x16x32_bf16 v[20:23], v[84:87], v[68:71], v[20:23]
	v_mfma_f32_16x16x32_bf16 v[24:27], v[88:91], v[68:71], v[24:27]
	v_mfma_f32_16x16x32_bf16 v[28:31], v[92:95], v[68:71], v[28:31]
	v_mfma_f32_16x16x32_bf16 v[32:35], v[80:83], v[72:75], v[32:35]
	v_mfma_f32_16x16x32_bf16 v[36:39], v[84:87], v[72:75], v[36:39]
	v_mfma_f32_16x16x32_bf16 v[40:43], v[88:91], v[72:75], v[40:43]
	v_mfma_f32_16x16x32_bf16 v[44:47], v[92:95], v[72:75], v[44:47]
	v_mfma_f32_16x16x32_bf16 v[48:51], v[80:83], v[76:79], v[48:51]
	v_mfma_f32_16x16x32_bf16 v[52:55], v[84:87], v[76:79], v[52:55]
	v_mfma_f32_16x16x32_bf16 v[56:59], v[88:91], v[76:79], v[56:59]
	v_mfma_f32_16x16x32_bf16 v[60:63], v[92:95], v[76:79], v[60:63]
	s_waitcnt vmcnt(0) lgkmcnt(0)
	s_barrier
	ds_read_b128 v[64:67], v168 offset:0
	ds_read_b128 v[68:71], v168 offset:2048
	ds_read_b128 v[72:75], v168 offset:4096
	ds_read_b128 v[76:79], v168 offset:6144
	ds_read_b128 v[80:83], v169 offset:0
	ds_read_b128 v[84:87], v169 offset:2048
	ds_read_b128 v[88:91], v169 offset:4096
	ds_read_b128 v[92:95], v169 offset:6144
	s_add_i32 s5, s1, 3
	s_min_u32 s5, s5, 15
	s_lshl_b32 s18, s5, 7
	s_add_u32 m0, s101, 0x8000
	v_lshl_add_u64 v[210:211], v[152:153], 0, s[18:19]
	global_load_lds_dwordx4 v[210:211], off
	s_add_u32 m0, s101, 0xc000
	v_lshl_add_u64 v[210:211], v[154:155], 0, s[18:19]
	global_load_lds_dwordx4 v[210:211], off
	ds_read_b128 v[96:99], v220 offset:0
	ds_read_b128 v[100:103], v220 offset:2048
	ds_read_b128 v[104:107], v220 offset:4096
	ds_read_b128 v[108:111], v220 offset:6144
	ds_read_b128 v[112:115], v221 offset:0
	ds_read_b128 v[116:119], v221 offset:2048
	ds_read_b128 v[120:123], v221 offset:4096
	ds_read_b128 v[124:127], v221 offset:6144
	v_mfma_f32_16x16x32_bf16 v[0:3], v[192:195], v[128:131], v[0:3]
	v_mfma_f32_16x16x32_bf16 v[4:7], v[196:199], v[128:131], v[4:7]
	s_add_u32 m0, s101, 0x9000
	v_lshl_add_u64 v[210:211], v[156:157], 0, s[18:19]
	global_load_lds_dwordx4 v[210:211], off
	v_mfma_f32_16x16x32_bf16 v[8:11], v[200:203], v[128:131], v[8:11]
	v_mfma_f32_16x16x32_bf16 v[12:15], v[204:207], v[128:131], v[12:15]
	s_add_u32 m0, s101, 0xd000
	v_lshl_add_u64 v[210:211], v[158:159], 0, s[18:19]
	global_load_lds_dwordx4 v[210:211], off
	v_mfma_f32_16x16x32_bf16 v[16:19], v[192:195], v[132:135], v[16:19]
	v_mfma_f32_16x16x32_bf16 v[20:23], v[196:199], v[132:135], v[20:23]
	s_add_u32 m0, s101, 0xa000
	v_lshl_add_u64 v[210:211], v[160:161], 0, s[18:19]
	global_load_lds_dwordx4 v[210:211], off
	v_mfma_f32_16x16x32_bf16 v[24:27], v[200:203], v[132:135], v[24:27]
	v_mfma_f32_16x16x32_bf16 v[28:31], v[204:207], v[132:135], v[28:31]
	s_add_u32 m0, s101, 0xe000
	v_lshl_add_u64 v[210:211], v[162:163], 0, s[18:19]
	global_load_lds_dwordx4 v[210:211], off
	v_mfma_f32_16x16x32_bf16 v[32:35], v[192:195], v[136:139], v[32:35]
	v_mfma_f32_16x16x32_bf16 v[36:39], v[196:199], v[136:139], v[36:39]
	s_add_u32 m0, s101, 0xb000
	v_lshl_add_u64 v[210:211], v[164:165], 0, s[18:19]
	global_load_lds_dwordx4 v[210:211], off
	v_mfma_f32_16x16x32_bf16 v[40:43], v[200:203], v[136:139], v[40:43]
	v_mfma_f32_16x16x32_bf16 v[44:47], v[204:207], v[136:139], v[44:47]
	s_add_u32 m0, s101, 0xf000
	v_lshl_add_u64 v[210:211], v[166:167], 0, s[18:19]
	global_load_lds_dwordx4 v[210:211], off
	v_mfma_f32_16x16x32_bf16 v[48:51], v[192:195], v[140:143], v[48:51]
	v_mfma_f32_16x16x32_bf16 v[52:55], v[196:199], v[140:143], v[52:55]
	v_mfma_f32_16x16x32_bf16 v[56:59], v[200:203], v[140:143], v[56:59]
	v_mfma_f32_16x16x32_bf16 v[60:63], v[204:207], v[140:143], v[60:63]
	s_waitcnt lgkmcnt(8)
; #define SB_ __builtin_amdgcn_sched_barrier(0)
; template <bool SWAP, bool HALF>
; DI void gemm_mainloop(const GemmDesc& d, int m0, int n0, bf16_t* smem, f32x16 (&acc)[2][2], int dry) {
;     ...
;   auto stage = [&](int cur, u32x4 (&ran)[4], u32x4 (&rbn)[4], int ks) {
;     ldf(cur, 1, 1); SB_;
;     mma(0); SB_;
;     ldf(cur, 2, 0); SB_;
;     lw(ran, rbn, cur ^ 1);
;     gl(ran, rbn, (ks + 3 < nk) ? ks + 3 : nk - 1);
;     SB_;
;     mma(1); SB_;
;     __syncthreads();
;     ldf(cur, 3, 1); SB_;
;     mma(0); SB_;
;     ldf(cur ^ 1, 0, 0);
;     SB_;
;     mma(1); SB_;
;     __syncthreads();
;   };
;   gl(ra0, rb0, 0);
;   gl(ra1, rb1, 1);
;   lw(ra0, rb0, 0);
;   gl(ra0, rb0, 2);
;   __syncthreads();
;   ldf(0, 0, 0);
; #pragma unroll 1
;   for (int ks = 0; ks < nk; ks += 2) {
;     stage(0, ra1, rb1, ks);
;     stage(1, ra0, rb0, ks + 1);
;   }
	v_mfma_f32_16x16x32_bf16 v[0:3], v[80:83], v[64:67], v[0:3]
	v_mfma_f32_16x16x32_bf16 v[4:7], v[84:87], v[64:67], v[4:7]
	v_mfma_f32_16x16x32_bf16 v[8:11], v[88:91], v[64:67], v[8:11]
	v_mfma_f32_16x16x32_bf16 v[12:15], v[92:95], v[64:67], v[12:15]
	v_mfma_f32_16x16x32_bf16 v[16:19], v[80:83], v[68:71], v[16:19]
	v_mfma_f32_16x16x32_bf16 v[20:23], v[84:87], v[68:71], v[20:23]
	v_mfma_f32_16x16x32_bf16 v[24:27], v[88:91], v[68:71], v[24:27]
	v_mfma_f32_16x16x32_bf16 v[28:31], v[92:95], v[68:71], v[28:31]
	v_mfma_f32_16x16x32_bf16 v[32:35], v[80:83], v[72:75], v[32:35]
	v_mfma_f32_16x16x32_bf16 v[36:39], v[84:87], v[72:75], v[36:39]
	v_mfma_f32_16x16x32_bf16 v[40:43], v[88:91], v[72:75], v[40:43]
	v_mfma_f32_16x16x32_bf16 v[44:47], v[92:95], v[72:75], v[44:47]
	v_mfma_f32_16x16x32_bf16 v[48:51], v[80:83], v[76:79], v[48:51]
	v_mfma_f32_16x16x32_bf16 v[52:55], v[84:87], v[76:79], v[52:55]
	v_mfma_f32_16x16x32_bf16 v[56:59], v[88:91], v[76:79], v[56:59]
	v_mfma_f32_16x16x32_bf16 v[60:63], v[92:95], v[76:79], v[60:63]
	s_cmp_lt_u32 s1, 12
	s_waitcnt vmcnt(0) lgkmcnt(0)
	s_barrier
	s_cbranch_scc1 .LBB0_501
	ds_read_b128 v[64:67], v168 offset:32768
	ds_read_b128 v[68:71], v168 offset:34816
	ds_read_b128 v[72:75], v168 offset:36864
	ds_read_b128 v[76:79], v168 offset:38912
	ds_read_b128 v[80:83], v169 offset:32768
	ds_read_b128 v[84:87], v169 offset:34816
	ds_read_b128 v[88:91], v169 offset:36864
	ds_read_b128 v[92:95], v169 offset:38912
	ds_read_b128 v[128:131], v220 offset:32768
	ds_read_b128 v[132:135], v220 offset:34816
	ds_read_b128 v[136:139], v220 offset:36864
	ds_read_b128 v[140:143], v220 offset:38912
	ds_read_b128 v[192:195], v221 offset:32768
	ds_read_b128 v[196:199], v221 offset:34816
	ds_read_b128 v[200:203], v221 offset:36864
	ds_read_b128 v[204:207], v221 offset:38912
	v_mfma_f32_16x16x32_bf16 v[0:3], v[112:115], v[96:99], v[0:3]
	v_mfma_f32_16x16x32_bf16 v[4:7], v[116:119], v[96:99], v[4:7]
	v_mfma_f32_16x16x32_bf16 v[8:11], v[120:123], v[96:99], v[8:11]
	v_mfma_f32_16x16x32_bf16 v[12:15], v[124:127], v[96:99], v[12:15]
	v_mfma_f32_16x16x32_bf16 v[16:19], v[112:115], v[100:103], v[16:19]
	v_mfma_f32_16x16x32_bf16 v[20:23], v[116:119], v[100:103], v[20:23]
	v_mfma_f32_16x16x32_bf16 v[24:27], v[120:123], v[100:103], v[24:27]
	v_mfma_f32_16x16x32_bf16 v[28:31], v[124:127], v[100:103], v[28:31]
	v_mfma_f32_16x16x32_bf16 v[32:35], v[112:115], v[104:107], v[32:35]
	v_mfma_f32_16x16x32_bf16 v[36:39], v[116:119], v[104:107], v[36:39]
	v_mfma_f32_16x16x32_bf16 v[40:43], v[120:123], v[104:107], v[40:43]
	v_mfma_f32_16x16x32_bf16 v[44:47], v[124:127], v[104:107], v[44:47]
	v_mfma_f32_16x16x32_bf16 v[48:51], v[112:115], v[108:111], v[48:51]
	v_mfma_f32_16x16x32_bf16 v[52:55], v[116:119], v[108:111], v[52:55]
	v_mfma_f32_16x16x32_bf16 v[56:59], v[120:123], v[108:111], v[56:59]
	v_mfma_f32_16x16x32_bf16 v[60:63], v[124:127], v[108:111], v[60:63]
	s_waitcnt lgkmcnt(8)
	v_mfma_f32_16x16x32_bf16 v[0:3], v[80:83], v[64:67], v[0:3]
	v_mfma_f32_16x16x32_bf16 v[4:7], v[84:87], v[64:67], v[4:7]
	v_mfma_f32_16x16x32_bf16 v[8:11], v[88:91], v[64:67], v[8:11]
	v_mfma_f32_16x16x32_bf16 v[12:15], v[92:95], v[64:67], v[12:15]
	v_mfma_f32_16x16x32_bf16 v[16:19], v[80:83], v[68:71], v[16:19]
	v_mfma_f32_16x16x32_bf16 v[20:23], v[84:87], v[68:71], v[20:23]
	v_mfma_f32_16x16x32_bf16 v[24:27], v[88:91], v[68:71], v[24:27]
	v_mfma_f32_16x16x32_bf16 v[28:31], v[92:95], v[68:71], v[28:31]
	v_mfma_f32_16x16x32_bf16 v[32:35], v[80:83], v[72:75], v[32:35]
	v_mfma_f32_16x16x32_bf16 v[36:39], v[84:87], v[72:75], v[36:39]
	v_mfma_f32_16x16x32_bf16 v[40:43], v[88:91], v[72:75], v[40:43]
	v_mfma_f32_16x16x32_bf16 v[44:47], v[92:95], v[72:75], v[44:47]
	v_mfma_f32_16x16x32_bf16 v[48:51], v[80:83], v[76:79], v[48:51]
	v_mfma_f32_16x16x32_bf16 v[52:55], v[84:87], v[76:79], v[52:55]
	v_mfma_f32_16x16x32_bf16 v[56:59], v[88:91], v[76:79], v[56:59]
	v_mfma_f32_16x16x32_bf16 v[60:63], v[92:95], v[76:79], v[60:63]
	s_waitcnt lgkmcnt(0)
	s_barrier
	v_mfma_f32_16x16x32_bf16 v[0:3], v[192:195], v[128:131], v[0:3]
	v_mfma_f32_16x16x32_bf16 v[4:7], v[196:199], v[128:131], v[4:7]
	v_mfma_f32_16x16x32_bf16 v[8:11], v[200:203], v[128:131], v[8:11]
	v_mfma_f32_16x16x32_bf16 v[12:15], v[204:207], v[128:131], v[12:15]
	v_mfma_f32_16x16x32_bf16 v[16:19], v[192:195], v[132:135], v[16:19]
	v_mfma_f32_16x16x32_bf16 v[20:23], v[196:199], v[132:135], v[20:23]
	v_mfma_f32_16x16x32_bf16 v[24:27], v[200:203], v[132:135], v[24:27]
	v_mfma_f32_16x16x32_bf16 v[28:31], v[204:207], v[132:135], v[28:31]
	v_mfma_f32_16x16x32_bf16 v[32:35], v[192:195], v[136:139], v[32:35]
	v_mfma_f32_16x16x32_bf16 v[36:39], v[196:199], v[136:139], v[36:39]
	v_mfma_f32_16x16x32_bf16 v[40:43], v[200:203], v[136:139], v[40:43]
	v_mfma_f32_16x16x32_bf16 v[44:47], v[204:207], v[136:139], v[44:47]
	v_mfma_f32_16x16x32_bf16 v[48:51], v[192:195], v[140:143], v[48:51]
	v_mfma_f32_16x16x32_bf16 v[52:55], v[196:199], v[140:143], v[52:55]
	v_mfma_f32_16x16x32_bf16 v[56:59], v[200:203], v[140:143], v[56:59]
	v_mfma_f32_16x16x32_bf16 v[60:63], v[204:207], v[140:143], v[60:63]
	s_waitcnt vmcnt(7)
; DI float ssq_f(u64 v) { return (float)v * (1.f / 1048576.f); }
; DI void gemm_tile(const GemmDesc& d, int m0, int n0, bf16_t* smem, int dry) {
;     ...
;   if (d.epi == EPI_RESID) {
; #pragma unroll
;     for (int pass = 0; pass < 16; ++pass) {
;       int m = m0 + pass * 8 + (t >> 5); m = m < M ? m : M - 1;
;       hpre[pass] = *(const u32x2*)(d.hb + (size_t)m * D + d.c_off + n0 + (t & 31) * 4);
;     }
;   } else if (t < 128) {
;     rs_s[t] = rsqrtf(ssq_f(myss) * d.inv_dim + EPS);
;   }
;   if (half) {
; #pragma unroll
;     for (int a = 0; a < 2; ++a)
; #pragma unroll
;       for (int g = 0; g < 4; ++g) {
;         f32x4 o;
; #pragma unroll
;         for (int j = 0; j < 4; ++j) o[j] = acc[a][0][4 * g + j];
;         *(f32x4*)(Ct + (a * 32 + r) * CS + w * 32 + 8 * g + 4 * hh) = o;
;       }
;   } else {
; #pragma unroll
;     for (int a = 0; a < 2; ++a)
; #pragma unroll
;       for (int b = 0; b < 2; ++b)
; #pragma unroll
;         for (int g = 0; g < 4; ++g) {
;           f32x4 o;
; #pragma unroll
;           for (int j = 0; j < 4; ++j) o[j] = acc[a][b][4 * g + j];
;           *(f32x4*)(Ct + (wm * 64 + a * 32 + r) * CS + wn * 64 + b * 32 + 8 * g + 4 * hh) = o;
;         }
;   }
;   __syncthreads();
;   if (d.epi == EPI_RESID) {
; #pragma unroll
;     for (int pass = 0; pass < 16; ++pass) {
;       const int row = pass * 8 + (t >> 5), c4 = t & 31, m = m0 + row;
;       float part = 0.f;
;       if (m < M) {
;         const f32x4 v = *(const f32x4*)(Ct + row * CS + c4 * 4);
;         const int n = d.c_off + n0 + c4 * 4;
;         f32x4 hv;
;         hv[0] = __uint_as_float(hpre[pass][0] << 16); hv[1] = __uint_as_float(hpre[pass][0] & 0xffff0000u);
;         hv[2] = __uint_as_float(hpre[pass][1] << 16); hv[3] = __uint_as_float(hpre[pass][1] & 0xffff0000u);
; #pragma unroll
;         for (int j = 0; j < 4; ++j) { hv[j] += v[j]; part += hv[j] * hv[j]; }
;         u32x2 o; o[0] = pk_bf16(hv[0], hv[1]); o[1] = pk_bf16(hv[2], hv[3]);
;         *(u32x2*)(d.hb + (size_t)m * D + n) = o;
	v_ashrrev_i32_e32 v98, 5, v150
	v_add_u32_e32 v92, s9, v98
	s_ashr_i32 s5, s4, 31
	s_lshl_b64 s[6:7], s[4:5], 1
	v_add_u32_e32 v70, 16, v92
	v_add_u32_e32 v72, 24, v92
	s_add_u32 s6, s56, s6
	v_lshlrev_b32_e32 v64, 3, v150
	v_min_i32_e32 v66, 0x803f, v92
	v_add_u32_e32 v68, 8, v92
	v_min_i32_e32 v70, 0x803f, v70
	v_min_i32_e32 v72, 0x803f, v72
	s_addc_u32 s7, s57, s7
	v_and_b32_e32 v144, 0xf8, v64
	v_ashrrev_i32_e32 v67, 31, v66
	v_min_i32_e32 v68, 0x803f, v68
	v_ashrrev_i32_e32 v71, 31, v70
	v_ashrrev_i32_e32 v73, 31, v72
	v_lshl_add_u64 v[64:65], s[6:7], 0, v[144:145]
	v_lshlrev_b64 v[66:67], 11, v[66:67]
	v_ashrrev_i32_e32 v69, 31, v68
	v_lshlrev_b64 v[70:71], 11, v[70:71]
	v_lshlrev_b64 v[72:73], 11, v[72:73]
	v_lshl_add_u64 v[66:67], v[64:65], 0, v[66:67]
	v_lshlrev_b64 v[68:69], 11, v[68:69]
	v_lshl_add_u64 v[70:71], v[64:65], 0, v[70:71]
	v_lshl_add_u64 v[72:73], v[64:65], 0, v[72:73]
	v_lshl_add_u64 v[68:69], v[64:65], 0, v[68:69]
	global_load_dwordx2 v[96:97], v[66:67], off
	global_load_dwordx2 v[94:95], v[68:69], off
	global_load_dwordx2 v[90:91], v[70:71], off
	global_load_dwordx2 v[88:89], v[72:73], off
	v_add_u32_e32 v66, 32, v92
	v_add_u32_e32 v70, 48, v92
	v_add_u32_e32 v72, 56, v92
	v_min_i32_e32 v66, 0x803f, v66
	v_add_u32_e32 v68, 40, v92
	v_min_i32_e32 v70, 0x803f, v70
	v_min_i32_e32 v72, 0x803f, v72
	v_ashrrev_i32_e32 v67, 31, v66
	v_min_i32_e32 v68, 0x803f, v68
	v_ashrrev_i32_e32 v71, 31, v70
	v_ashrrev_i32_e32 v73, 31, v72
	v_lshlrev_b64 v[66:67], 11, v[66:67]
	v_ashrrev_i32_e32 v69, 31, v68
	v_lshlrev_b64 v[70:71], 11, v[70:71]
	v_lshlrev_b64 v[72:73], 11, v[72:73]
	v_lshl_add_u64 v[66:67], v[64:65], 0, v[66:67]
	v_lshlrev_b64 v[68:69], 11, v[68:69]
	v_lshl_add_u64 v[70:71], v[64:65], 0, v[70:71]
	v_lshl_add_u64 v[72:73], v[64:65], 0, v[72:73]
	v_lshl_add_u64 v[68:69], v[64:65], 0, v[68:69]
	global_load_dwordx2 v[86:87], v[66:67], off
	global_load_dwordx2 v[84:85], v[68:69], off
	global_load_dwordx2 v[82:83], v[70:71], off
	global_load_dwordx2 v[80:81], v[72:73], off
	v_add_u32_e32 v66, 64, v92
	v_add_u32_e32 v70, 0x50, v92
	v_add_u32_e32 v72, 0x58, v92
	v_min_i32_e32 v66, 0x803f, v66
	v_add_u32_e32 v68, 0x48, v92
	v_min_i32_e32 v70, 0x803f, v70
	v_min_i32_e32 v72, 0x803f, v72
	v_ashrrev_i32_e32 v67, 31, v66
	v_min_i32_e32 v68, 0x803f, v68
	v_ashrrev_i32_e32 v71, 31, v70
	v_ashrrev_i32_e32 v73, 31, v72
	v_lshlrev_b64 v[66:67], 11, v[66:67]
	v_ashrrev_i32_e32 v69, 31, v68
	v_lshlrev_b64 v[70:71], 11, v[70:71]
	v_lshlrev_b64 v[72:73], 11, v[72:73]
	v_lshl_add_u64 v[66:67], v[64:65], 0, v[66:67]
	v_lshlrev_b64 v[68:69], 11, v[68:69]
	v_lshl_add_u64 v[70:71], v[64:65], 0, v[70:71]
	v_lshl_add_u64 v[72:73], v[64:65], 0, v[72:73]
	v_lshl_add_u64 v[68:69], v[64:65], 0, v[68:69]
	global_load_dwordx2 v[78:79], v[66:67], off
	global_load_dwordx2 v[76:77], v[68:69], off
	global_load_dwordx2 v[74:75], v[70:71], off
	s_nop 0
	global_load_dwordx2 v[72:73], v[72:73], off
	v_add_u32_e32 v70, 0x70, v92
	v_min_i32_e32 v70, 0x803f, v70
	v_ashrrev_i32_e32 v71, 31, v70
	v_lshlrev_b64 v[70:71], 11, v[70:71]
	v_add_u32_e32 v66, 0x60, v92
	v_add_u32_e32 v68, 0x68, v92
	s_waitcnt vmcnt(18)
	v_lshl_add_u64 v[100:101], v[64:65], 0, v[70:71]
	v_add_u32_e32 v70, 0x78, v92
	v_min_i32_e32 v66, 0x803f, v66
	v_min_i32_e32 v68, 0x803f, v68
	v_min_i32_e32 v70, 0x803f, v70
	v_ashrrev_i32_e32 v67, 31, v66
	v_ashrrev_i32_e32 v69, 31, v68
	v_ashrrev_i32_e32 v71, 31, v70
	v_lshlrev_b64 v[66:67], 11, v[66:67]
	v_lshlrev_b64 v[68:69], 11, v[68:69]
	v_lshlrev_b64 v[70:71], 11, v[70:71]
	v_lshl_add_u64 v[66:67], v[64:65], 0, v[66:67]
	v_lshl_add_u64 v[68:69], v[64:65], 0, v[68:69]
	v_lshl_add_u64 v[64:65], v[64:65], 0, v[70:71]
	global_load_dwordx2 v[70:71], v[66:67], off
	s_nop 0
	global_load_dwordx2 v[68:69], v[68:69], off
	s_nop 0
	global_load_dwordx2 v[66:67], v[100:101], off
	s_nop 0
	global_load_dwordx2 v[64:65], v[64:65], off
	v_and_b32_e32 v99, 31, v150
	v_lshrrev_b32_e32 v100, 1, v150
	v_lshlrev_b32_e32 v93, 2, v150
	v_and_or_b32 v101, v100, s72, v99
	v_and_b32_e32 v100, 16, v100
	s_movk_i32 s1, 0x100
	v_and_or_b32 v100, v93, s1, v100
	v_mad_u64_u32 v[100:101], s[6:7], v101, s22, v[100:101]
	v_and_b32_e32 v212, 15, v172
	v_lshrrev_b32_e32 v213, 1, v172
	v_and_or_b32 v212, v213, s72, v212
	v_lshlrev_b32_e32 v213, 2, v172
	v_and_b32_e32 v214, 0x30, v172
	v_and_b32_e32 v213, 0x100, v213
	v_or_b32_e32 v213, v213, v214
	v_mad_u32_u24 v100, v212, s22, v213
	ds_write_b128 v100, v[0:3]
	ds_write_b128 v100, v[4:7] offset:64
	ds_write_b128 v100, v[8:11] offset:128
	ds_write_b128 v100, v[12:15] offset:192
	ds_write_b128 v100, v[16:19] offset:8448
	ds_write_b128 v100, v[20:23] offset:8512
	ds_write_b128 v100, v[24:27] offset:8576
	ds_write_b128 v100, v[28:31] offset:8640
	ds_write_b128 v100, v[32:35] offset:16896
	ds_write_b128 v100, v[36:39] offset:16960
	ds_write_b128 v100, v[40:43] offset:17024
	ds_write_b128 v100, v[44:47] offset:17088
	ds_write_b128 v100, v[48:51] offset:25344
	ds_write_b128 v100, v[52:55] offset:25408
	ds_write_b128 v100, v[56:59] offset:25472
	ds_write_b128 v100, v[60:63] offset:25536
	v_lshl_or_b32 v0, v99, 2, s4
	v_lshlrev_b32_e32 v2, 4, v99
	v_cmp_gt_i32_e64 s[4:5], s23, v92
	v_mov_b32_e32 v4, 0
	v_ashrrev_i32_e32 v93, 31, v92
	v_ashrrev_i32_e32 v1, 31, v0
	s_waitcnt lgkmcnt(0)
	s_barrier
	s_and_saveexec_b64 s[6:7], s[4:5]
	s_cbranch_execz .LBB0_504
	v_mad_u64_u32 v[4:5], s[10:11], v98, s22, v[2:3]
	ds_read_b128 v[4:7], v4
	s_waitcnt vmcnt(15)
	v_lshlrev_b32_e32 v8, 16, v96
	v_and_b32_e32 v9, 0xffff0000, v96
	v_and_b32_e32 v11, 0xffff0000, v97
	v_lshlrev_b32_e32 v10, 16, v97
	s_waitcnt lgkmcnt(0)
	v_pk_add_f32 v[8:9], v[4:5], v[8:9]
	v_pk_add_f32 v[6:7], v[6:7], v[10:11]
	v_pk_mul_f32 v[4:5], v[8:9], v[8:9]
	v_pk_mul_f32 v[10:11], v[6:7], v[6:7]
	v_add_f32_e32 v3, v4, v5
	v_cvt_pk_bf16_f32 v8, v8, v9
	v_cvt_pk_bf16_f32 v9, v6, v7
	v_lshlrev_b64 v[6:7], 11, v[92:93]
	v_add_f32_e32 v3, v10, v3
	v_lshl_add_u64 v[6:7], s[56:57], 0, v[6:7]
	v_add_f32_e32 v4, v11, v3
	v_lshl_add_u64 v[6:7], v[0:1], 1, v[6:7]
	global_store_dwordx2 v[6:7], v[8:9], off

; DI int otid() { int t = threadIdx.x; asm volatile("" : "+v"(t)); return t; }
; template <bool SWAP, bool HALF>
; DI void gemm_mainloop(const GemmDesc& d, int m0, int n0, bf16_t* smem, f32x16 (&acc)[2][2], int dry) {
;   const int t = otid(), lane = t & 63, w = t >> 6, wm = w >> 1, wn = w & 1, r = lane & 31, hh = lane >> 5;
;   const int lrow = t >> 3, lkc = t & 7;
;   const bf16_t* ap[4]; const bf16_t* bp[4];
; #pragma unroll
;   for (int i = 0; i < 4; ++i) {
;     int am = m0 + lrow + 32 * i; am = am < M ? am : M - 1;
;     ap[i] = d.A + (size_t)am * d.lda + lkc * 8 + (d.a_grp ? (n0 / d.a_grp) * d.a_grp : 0);
;     bp[i] = d.Bt + (size_t)(n0 + lrow + 32 * i) * d.ldb + lkc * 8;
;   }
; #pragma unroll
;   for (int a = 0; a < 2; ++a)
; #pragma unroll
;     for (int b = 0; b < 2; ++b)
; #pragma unroll
;       for (int i = 0; i < 16; ++i) acc[a][b][i] = 0.f;
;   u32x4 ra0[4], rb0[4], ra1[4], rb1[4];
;   const int nk = d.K >> 6;
;   const int lds_w = lrow * LST + lkc * 8;
;     ...
;   for (int i = slot; i < total; i += nslots) {
;     const int g = i / (8 * nN), j = i - g * 8 * nN;
;     const int gm = (cx - g * 8) < 8 ? (cx - g * 8) : 8;
;     const int mt = (g * 8 + j % gm) * 8 + x, nt = j / gm;
;     gemm_tile(d, mt * 128, nt * 128, smem, dry);
.LBB0_626:
	s_or_b64 exec, exec, s[4:5]
	v_mov_b32_e32 v32, v172
	v_readlane_b32 s76, v228, 60
	v_ashrrev_i32_e32 v10, 3, v32
	v_add_u32_e32 v11, s6, v10
	v_lshlrev_b32_e32 v0, 3, v32
	v_and_b32_e32 v33, 56, v0
	v_min_i32_e32 v0, 0x803f, v11
	v_lshlrev_b32_e32 v144, 1, v33
	v_ashrrev_i32_e32 v1, 31, v0
	v_lshl_add_u64 v[4:5], s[56:57], 0, v[144:145]
	v_lshlrev_b64 v[0:1], 11, v[0:1]
	v_lshl_add_u64 v[152:153], v[4:5], 0, v[0:1]
	s_lshl_b32 s6, s10, 7
	v_add_u32_e32 v6, s6, v10
	v_readlane_b32 s82, v223, 2
	v_readlane_b32 s83, v223, 3
	v_ashrrev_i32_e32 v7, 31, v6
	v_lshlrev_b64 v[6:7], 11, v[6:7]
	v_lshl_add_u64 v[8:9], s[82:83], 0, v[144:145]
	v_lshl_add_u64 v[154:155], v[8:9], 0, v[6:7]
	v_min_i32_e32 v6, 0x801f, v11
	v_ashrrev_i32_e32 v7, 31, v6
	v_lshlrev_b64 v[6:7], 11, v[6:7]
	v_lshl_add_u64 v[8:9], v[4:5], 0, v[6:7]
	v_min_i32_e32 v6, 0x7fff, v11
	v_ashrrev_i32_e32 v7, 31, v6
	v_lshlrev_b64 v[6:7], 11, v[6:7]
	v_lshl_add_u64 v[16:17], v[4:5], 0, v[6:7]
	v_min_i32_e32 v6, 0x7fdf, v11
	s_mov_b64 s[4:5], 0x10000
	v_ashrrev_i32_e32 v7, 31, v6
	v_lshl_add_u64 v[156:157], v[8:9], 0, s[4:5]
	v_lshl_add_u64 v[158:159], v[154:155], 0, s[4:5]
	s_mov_b64 s[4:5], 0x20000
	v_lshlrev_b64 v[6:7], 11, v[6:7]
	v_lshl_add_u64 v[160:161], v[16:17], 0, s[4:5]
	v_lshl_add_u64 v[162:163], v[154:155], 0, s[4:5]
	v_lshl_add_u64 v[24:25], v[4:5], 0, v[6:7]
	s_mov_b64 s[4:5], 0x30000
	v_lshl_add_u64 v[164:165], v[24:25], 0, s[4:5]
	v_lshl_add_u64 v[166:167], v[154:155], 0, s[4:5]
	s_movk_i32 s4, 0x48
	v_and_b32_e32 v34, 31, v32
	v_mul_lo_u32 v35, v10, s4
	v_readlane_b32 s77, v228, 61
	v_readlane_b32 s78, v228, 62
	v_readlane_b32 s79, v228, 63
	v_readlane_b32 s80, v223, 0
	v_readlane_b32 s81, v223, 1
	v_readlane_b32 s84, v223, 4
	v_readlane_b32 s85, v223, 5
	v_readlane_b32 s86, v223, 6
	v_readlane_b32 s87, v223, 7
	v_readlane_b32 s88, v223, 8
	v_readlane_b32 s89, v223, 9
	v_readlane_b32 s90, v223, 10
	v_readlane_b32 s91, v223, 11
	s_mov_b32 s8, 0x10000
	v_add_co_u32_e64 v8, s[4:5], s8, v8
	s_nop 1
	v_addc_co_u32_e64 v9, s[4:5], 0, v9, s[4:5]
	s_waitcnt vmcnt(19)
	v_add_co_u32_e64 v12, s[4:5], s8, v154
	s_nop 1
	v_addc_co_u32_e64 v13, s[4:5], 0, v155, s[4:5]
	s_mov_b32 s8, 0x20000
	v_add_co_u32_e64 v16, s[4:5], s8, v16
	s_nop 1
	v_addc_co_u32_e64 v17, s[4:5], 0, v17, s[4:5]
	v_add_co_u32_e64 v20, s[4:5], s8, v154
	s_nop 1
	v_addc_co_u32_e64 v21, s[4:5], 0, v155, s[4:5]
	s_mov_b32 s8, 0x30000
	v_add_co_u32_e64 v24, s[4:5], s8, v24
	s_nop 1
	v_addc_co_u32_e64 v25, s[4:5], 0, v25, s[4:5]
	v_add_co_u32_e64 v28, s[4:5], s8, v154
	s_nop 1
	v_addc_co_u32_e64 v29, s[4:5], 0, v155, s[4:5]
	s_nop 0
	v_add_lshl_u32 v144, v35, v33, 1
	s_waitcnt vmcnt(15)
	s_waitcnt vmcnt(14)
	s_waitcnt vmcnt(13)
	s_waitcnt vmcnt(12)
	s_waitcnt vmcnt(11)
	s_waitcnt vmcnt(10)
	s_waitcnt vmcnt(9)
	s_waitcnt vmcnt(8)
	v_lshrrev_b32_e32 v0, 1, v32
	v_and_or_b32 v1, v0, s72, v34
	v_and_b32_e32 v0, 16, v0
	s_movk_i32 s4, 0x90
	v_mad_u64_u32 v[168:169], s[4:5], v1, s4, v[0:1]
	v_and_b32_e32 v1, 0x5f, v32
	v_mul_u32_u24_e32 v1, 0x48, v1
	v_lshl_add_u32 v169, v1, 1, v0
	v_bfe_u32 v212, v172, 4, 3
	v_lshlrev_b32_e32 v212, 4, v212
	v_xor_b32_e32 v152, v152, v212
	v_xor_b32_e32 v154, v154, v212
	v_xor_b32_e32 v156, v156, v212
	v_xor_b32_e32 v158, v158, v212
	v_xor_b32_e32 v160, v160, v212
	v_xor_b32_e32 v162, v162, v212
	v_xor_b32_e32 v164, v164, v212
	v_xor_b32_e32 v166, v166, v212
	v_lshrrev_b32_e32 v213, 6, v172
	s_nop 1
	v_readfirstlane_b32 s101, v213
	s_lshl_b32 s101, s101, 10
	s_add_u32 m0, s101, 0x0
	s_nop 0
	global_load_lds_dwordx4 v[152:153], off
	s_add_u32 m0, s101, 0x4000
	s_nop 0
	global_load_lds_dwordx4 v[154:155], off
	s_add_u32 m0, s101, 0x1000
	s_nop 0
	global_load_lds_dwordx4 v[156:157], off
	s_add_u32 m0, s101, 0x5000
	s_nop 0
	global_load_lds_dwordx4 v[158:159], off
	s_add_u32 m0, s101, 0x2000
	s_nop 0
	global_load_lds_dwordx4 v[160:161], off
	s_add_u32 m0, s101, 0x6000
	s_nop 0
	global_load_lds_dwordx4 v[162:163], off
	s_add_u32 m0, s101, 0x3000
	s_nop 0
	global_load_lds_dwordx4 v[164:165], off
	s_add_u32 m0, s101, 0x7000
	s_nop 0
	global_load_lds_dwordx4 v[166:167], off
	v_and_b32_e32 v212, 15, v172
	v_bfe_u32 v213, v172, 4, 2
	v_lshrrev_b32_e32 v214, 1, v212
	v_xor_b32_e32 v213, v213, v214
	v_lshlrev_b32_e32 v213, 4, v213
	v_lshl_or_b32 v212, v212, 7, v213
	v_lshrrev_b32_e32 v214, 7, v172
	v_lshl_add_u32 v168, v214, 13, v212
	v_bfe_u32 v214, v172, 6, 1
	v_lshl_add_u32 v169, v214, 13, v212
	v_add_u32_e32 v169, 0x4000, v169
	v_xor_b32_e32 v220, 64, v168
	v_xor_b32_e32 v221, 64, v169
	s_waitcnt vmcnt(0) lgkmcnt(0)
	s_barrier
; #define SB_ __builtin_amdgcn_sched_barrier(0)
; template <bool SWAP, bool HALF>
; DI void gemm_mainloop(const GemmDesc& d, int m0, int n0, bf16_t* smem, f32x16 (&acc)[2][2], int dry) {
;     ...
;   for (int a = 0; a < 2; ++a)
; #pragma unroll
;     for (int b = 0; b < 2; ++b)
; #pragma unroll
;       for (int i = 0; i < 16; ++i) acc[a][b][i] = 0.f;
;     ...
;   auto stage = [&](int cur, u32x4 (&ran)[4], u32x4 (&rbn)[4], int ks) {
;     ldf(cur, 1, 1); SB_;
;     mma(0); SB_;
;     ldf(cur, 2, 0); SB_;
;     lw(ran, rbn, cur ^ 1);
;     gl(ran, rbn, (ks + 3 < nk) ? ks + 3 : nk - 1);
;     SB_;
;     mma(1); SB_;
;     __syncthreads();
;     ldf(cur, 3, 1); SB_;
;     mma(0); SB_;
;     ldf(cur ^ 1, 0, 0);
;     SB_;
;     mma(1); SB_;
;     __syncthreads();
;   };
;   gl(ra0, rb0, 0);
;   gl(ra1, rb1, 1);
;   lw(ra0, rb0, 0);
;   gl(ra0, rb0, 2);
;   __syncthreads();
;   ldf(0, 0, 0);
; #pragma unroll 1
;   for (int ks = 0; ks < nk; ks += 2) {
;     stage(0, ra1, rb1, ks);
	v_mov_b32_e32 v0, 0
	v_add_u32_e32 v171, 0x9000, v144
	s_mov_b32 s4, -2
	v_mov_b32_e32 v1, v0
	v_mov_b32_e32 v2, v0
	v_mov_b32_e32 v3, v0
	v_mov_b32_e32 v4, v0
	v_mov_b32_e32 v5, v0
	v_mov_b32_e32 v6, v0
	v_mov_b32_e32 v7, v0
	v_mov_b32_e32 v8, v0
	v_mov_b32_e32 v9, v0
	v_mov_b32_e32 v10, v0
	v_mov_b32_e32 v11, v0
	v_mov_b32_e32 v12, v0
	v_mov_b32_e32 v13, v0
	v_mov_b32_e32 v14, v0
	v_mov_b32_e32 v15, v0
	v_mov_b32_e32 v16, v0
	v_mov_b32_e32 v17, v0
	v_mov_b32_e32 v18, v0
	v_mov_b32_e32 v19, v0
	v_mov_b32_e32 v20, v0
	v_mov_b32_e32 v21, v0
	v_mov_b32_e32 v22, v0
	v_mov_b32_e32 v23, v0
	v_mov_b32_e32 v24, v0
	v_mov_b32_e32 v25, v0
	v_mov_b32_e32 v26, v0
	v_mov_b32_e32 v27, v0
	v_mov_b32_e32 v28, v0
	v_mov_b32_e32 v29, v0
	v_mov_b32_e32 v30, v0
	v_mov_b32_e32 v31, v0
	v_mov_b32_e32 v32, v0
	v_mov_b32_e32 v33, v0
	v_mov_b32_e32 v34, v0
	v_mov_b32_e32 v35, v0
	v_mov_b32_e32 v36, v0
	v_mov_b32_e32 v37, v0
	v_mov_b32_e32 v38, v0
	v_mov_b32_e32 v39, v0
	v_mov_b32_e32 v40, v0
	v_mov_b32_e32 v41, v0
	v_mov_b32_e32 v42, v0
	v_mov_b32_e32 v43, v0
	v_mov_b32_e32 v44, v0
	v_mov_b32_e32 v45, v0
	v_mov_b32_e32 v46, v0
	v_mov_b32_e32 v47, v0
	v_mov_b32_e32 v48, v0
	v_mov_b32_e32 v49, v0
	v_mov_b32_e32 v50, v0
	v_mov_b32_e32 v51, v0
	v_mov_b32_e32 v52, v0
	v_mov_b32_e32 v53, v0
	v_mov_b32_e32 v54, v0
	v_mov_b32_e32 v55, v0
	v_mov_b32_e32 v56, v0
	v_mov_b32_e32 v57, v0
	v_mov_b32_e32 v58, v0
	v_mov_b32_e32 v59, v0
	v_mov_b32_e32 v60, v0
	v_mov_b32_e32 v61, v0
	v_mov_b32_e32 v62, v0
	v_mov_b32_e32 v63, v0
	ds_read_b128 v[64:67], v168 offset:0
	ds_read_b128 v[68:71], v168 offset:2048
	ds_read_b128 v[72:75], v168 offset:4096
	ds_read_b128 v[76:79], v168 offset:6144
	ds_read_b128 v[80:83], v169 offset:0
	ds_read_b128 v[84:87], v169 offset:2048
	ds_read_b128 v[88:91], v169 offset:4096
	ds_read_b128 v[92:95], v169 offset:6144
	s_add_i32 s5, s4, 3
	s_min_u32 s5, s5, 15
	s_lshl_b32 s18, s5, 7
	s_add_u32 m0, s101, 0x8000
	v_lshl_add_u64 v[210:211], v[152:153], 0, s[18:19]
	global_load_lds_dwordx4 v[210:211], off
	s_add_u32 m0, s101, 0xc000
	v_lshl_add_u64 v[210:211], v[154:155], 0, s[18:19]
	global_load_lds_dwordx4 v[210:211], off
	ds_read_b128 v[96:99], v220 offset:0
	ds_read_b128 v[100:103], v220 offset:2048
	ds_read_b128 v[104:107], v220 offset:4096
	ds_read_b128 v[108:111], v220 offset:6144
	ds_read_b128 v[112:115], v221 offset:0
	ds_read_b128 v[116:119], v221 offset:2048
	ds_read_b128 v[120:123], v221 offset:4096
	ds_read_b128 v[124:127], v221 offset:6144
	s_waitcnt lgkmcnt(8)
	v_mfma_f32_16x16x32_bf16 v[0:3], v[80:83], v[64:67], v[0:3]
	v_mfma_f32_16x16x32_bf16 v[4:7], v[84:87], v[64:67], v[4:7]
	s_add_u32 m0, s101, 0x9000
	v_lshl_add_u64 v[210:211], v[156:157], 0, s[18:19]
	global_load_lds_dwordx4 v[210:211], off
	v_mfma_f32_16x16x32_bf16 v[8:11], v[88:91], v[64:67], v[8:11]
	v_mfma_f32_16x16x32_bf16 v[12:15], v[92:95], v[64:67], v[12:15]
	s_add_u32 m0, s101, 0xd000
	v_lshl_add_u64 v[210:211], v[158:159], 0, s[18:19]
	global_load_lds_dwordx4 v[210:211], off
	v_mfma_f32_16x16x32_bf16 v[16:19], v[80:83], v[68:71], v[16:19]
	v_mfma_f32_16x16x32_bf16 v[20:23], v[84:87], v[68:71], v[20:23]
	s_add_u32 m0, s101, 0xa000
	v_lshl_add_u64 v[210:211], v[160:161], 0, s[18:19]
	global_load_lds_dwordx4 v[210:211], off
	v_mfma_f32_16x16x32_bf16 v[24:27], v[88:91], v[68:71], v[24:27]
	v_mfma_f32_16x16x32_bf16 v[28:31], v[92:95], v[68:71], v[28:31]
	s_add_u32 m0, s101, 0xe000
	v_lshl_add_u64 v[210:211], v[162:163], 0, s[18:19]
	global_load_lds_dwordx4 v[210:211], off
	v_mfma_f32_16x16x32_bf16 v[32:35], v[80:83], v[72:75], v[32:35]
	v_mfma_f32_16x16x32_bf16 v[36:39], v[84:87], v[72:75], v[36:39]
	s_add_u32 m0, s101, 0xb000
	v_lshl_add_u64 v[210:211], v[164:165], 0, s[18:19]
	global_load_lds_dwordx4 v[210:211], off
	v_mfma_f32_16x16x32_bf16 v[40:43], v[88:91], v[72:75], v[40:43]
	v_mfma_f32_16x16x32_bf16 v[44:47], v[92:95], v[72:75], v[44:47]
	s_add_u32 m0, s101, 0xf000
	v_lshl_add_u64 v[210:211], v[166:167], 0, s[18:19]
	global_load_lds_dwordx4 v[210:211], off
	v_mfma_f32_16x16x32_bf16 v[48:51], v[80:83], v[76:79], v[48:51]
	v_mfma_f32_16x16x32_bf16 v[52:55], v[84:87], v[76:79], v[52:55]
	v_mfma_f32_16x16x32_bf16 v[56:59], v[88:91], v[76:79], v[56:59]
	v_mfma_f32_16x16x32_bf16 v[60:63], v[92:95], v[76:79], v[60:63]
	s_waitcnt vmcnt(0) lgkmcnt(0)
	s_barrier
; #define SB_ __builtin_amdgcn_sched_barrier(0)
; template <bool SWAP, bool HALF>
; DI void gemm_mainloop(const GemmDesc& d, int m0, int n0, bf16_t* smem, f32x16 (&acc)[2][2], int dry) {
;     ...
;   auto stage = [&](int cur, u32x4 (&ran)[4], u32x4 (&rbn)[4], int ks) {
;     ldf(cur, 1, 1); SB_;
;     mma(0); SB_;
;     ldf(cur, 2, 0); SB_;
;     lw(ran, rbn, cur ^ 1);
;     gl(ran, rbn, (ks + 3 < nk) ? ks + 3 : nk - 1);
;     SB_;
;     mma(1); SB_;
;     __syncthreads();
;     ldf(cur, 3, 1); SB_;
;     mma(0); SB_;
;     ldf(cur ^ 1, 0, 0);
;     SB_;
;     mma(1); SB_;
;     __syncthreads();
;   };
;   gl(ra0, rb0, 0);
;   gl(ra1, rb1, 1);
;   lw(ra0, rb0, 0);
;   gl(ra0, rb0, 2);
;   __syncthreads();
;   ldf(0, 0, 0);
; #pragma unroll 1
;   for (int ks = 0; ks < nk; ks += 2) {
;     stage(0, ra1, rb1, ks);
;     stage(1, ra0, rb0, ks + 1);
;   }
.LBB0_627:
	ds_read_b128 v[64:67], v168 offset:32768
	ds_read_b128 v[68:71], v168 offset:34816
	ds_read_b128 v[72:75], v168 offset:36864
	ds_read_b128 v[76:79], v168 offset:38912
	ds_read_b128 v[80:83], v169 offset:32768
	ds_read_b128 v[84:87], v169 offset:34816
	ds_read_b128 v[88:91], v169 offset:36864
	ds_read_b128 v[92:95], v169 offset:38912
	s_add_i32 s4, s4, 2
	s_add_i32 s5, s4, 2
	s_min_u32 s5, s5, 15
	s_lshl_b32 s18, s5, 7
	s_add_u32 m0, s101, 0x0
	v_lshl_add_u64 v[210:211], v[152:153], 0, s[18:19]
	global_load_lds_dwordx4 v[210:211], off
	s_add_u32 m0, s101, 0x4000
	v_lshl_add_u64 v[210:211], v[154:155], 0, s[18:19]
	global_load_lds_dwordx4 v[210:211], off
	ds_read_b128 v[128:131], v220 offset:32768
	ds_read_b128 v[132:135], v220 offset:34816
	ds_read_b128 v[136:139], v220 offset:36864
	ds_read_b128 v[140:143], v220 offset:38912
	ds_read_b128 v[192:195], v221 offset:32768
	ds_read_b128 v[196:199], v221 offset:34816
	ds_read_b128 v[200:203], v221 offset:36864
	ds_read_b128 v[204:207], v221 offset:38912
	v_mfma_f32_16x16x32_bf16 v[0:3], v[112:115], v[96:99], v[0:3]
	v_mfma_f32_16x16x32_bf16 v[4:7], v[116:119], v[96:99], v[4:7]
	s_add_u32 m0, s101, 0x1000
	v_lshl_add_u64 v[210:211], v[156:157], 0, s[18:19]
	global_load_lds_dwordx4 v[210:211], off
	v_mfma_f32_16x16x32_bf16 v[8:11], v[120:123], v[96:99], v[8:11]
	v_mfma_f32_16x16x32_bf16 v[12:15], v[124:127], v[96:99], v[12:15]
	s_add_u32 m0, s101, 0x5000
	v_lshl_add_u64 v[210:211], v[158:159], 0, s[18:19]
	global_load_lds_dwordx4 v[210:211], off
	v_mfma_f32_16x16x32_bf16 v[16:19], v[112:115], v[100:103], v[16:19]
	v_mfma_f32_16x16x32_bf16 v[20:23], v[116:119], v[100:103], v[20:23]
	s_add_u32 m0, s101, 0x2000
	v_lshl_add_u64 v[210:211], v[160:161], 0, s[18:19]
	global_load_lds_dwordx4 v[210:211], off
	v_mfma_f32_16x16x32_bf16 v[24:27], v[120:123], v[100:103], v[24:27]
	v_mfma_f32_16x16x32_bf16 v[28:31], v[124:127], v[100:103], v[28:31]
	s_add_u32 m0, s101, 0x6000
	v_lshl_add_u64 v[210:211], v[162:163], 0, s[18:19]
	global_load_lds_dwordx4 v[210:211], off
	v_mfma_f32_16x16x32_bf16 v[32:35], v[112:115], v[104:107], v[32:35]
	v_mfma_f32_16x16x32_bf16 v[36:39], v[116:119], v[104:107], v[36:39]
	s_add_u32 m0, s101, 0x3000
	v_lshl_add_u64 v[210:211], v[164:165], 0, s[18:19]
	global_load_lds_dwordx4 v[210:211], off
	v_mfma_f32_16x16x32_bf16 v[40:43], v[120:123], v[104:107], v[40:43]
	v_mfma_f32_16x16x32_bf16 v[44:47], v[124:127], v[104:107], v[44:47]
	s_add_u32 m0, s101, 0x7000
	v_lshl_add_u64 v[210:211], v[166:167], 0, s[18:19]
	global_load_lds_dwordx4 v[210:211], off
	v_mfma_f32_16x16x32_bf16 v[48:51], v[112:115], v[108:111], v[48:51]
	v_mfma_f32_16x16x32_bf16 v[52:55], v[116:119], v[108:111], v[52:55]
	v_mfma_f32_16x16x32_bf16 v[56:59], v[120:123], v[108:111], v[56:59]
	v_mfma_f32_16x16x32_bf16 v[60:63], v[124:127], v[108:111], v[60:63]
	s_waitcnt lgkmcnt(8)
	v_mfma_f32_16x16x32_bf16 v[0:3], v[80:83], v[64:67], v[0:3]
	v_mfma_f32_16x16x32_bf16 v[4:7], v[84:87], v[64:67], v[4:7]
	v_mfma_f32_16x16x32_bf16 v[8:11], v[88:91], v[64:67], v[8:11]
	v_mfma_f32_16x16x32_bf16 v[12:15], v[92:95], v[64:67], v[12:15]
	v_mfma_f32_16x16x32_bf16 v[16:19], v[80:83], v[68:71], v[16:19]
	v_mfma_f32_16x16x32_bf16 v[20:23], v[84:87], v[68:71], v[20:23]
	v_mfma_f32_16x16x32_bf16 v[24:27], v[88:91], v[68:71], v[24:27]
	v_mfma_f32_16x16x32_bf16 v[28:31], v[92:95], v[68:71], v[28:31]
	v_mfma_f32_16x16x32_bf16 v[32:35], v[80:83], v[72:75], v[32:35]
	v_mfma_f32_16x16x32_bf16 v[36:39], v[84:87], v[72:75], v[36:39]
	v_mfma_f32_16x16x32_bf16 v[40:43], v[88:91], v[72:75], v[40:43]
	v_mfma_f32_16x16x32_bf16 v[44:47], v[92:95], v[72:75], v[44:47]
	v_mfma_f32_16x16x32_bf16 v[48:51], v[80:83], v[76:79], v[48:51]
	v_mfma_f32_16x16x32_bf16 v[52:55], v[84:87], v[76:79], v[52:55]
	v_mfma_f32_16x16x32_bf16 v[56:59], v[88:91], v[76:79], v[56:59]
	v_mfma_f32_16x16x32_bf16 v[60:63], v[92:95], v[76:79], v[60:63]
	s_waitcnt vmcnt(0) lgkmcnt(0)
	s_barrier
	ds_read_b128 v[64:67], v168 offset:0
	ds_read_b128 v[68:71], v168 offset:2048
	ds_read_b128 v[72:75], v168 offset:4096
	ds_read_b128 v[76:79], v168 offset:6144
	ds_read_b128 v[80:83], v169 offset:0
	ds_read_b128 v[84:87], v169 offset:2048
	ds_read_b128 v[88:91], v169 offset:4096
	ds_read_b128 v[92:95], v169 offset:6144
	s_add_i32 s5, s4, 3
	s_min_u32 s5, s5, 15
	s_lshl_b32 s18, s5, 7
	s_add_u32 m0, s101, 0x8000
	v_lshl_add_u64 v[210:211], v[152:153], 0, s[18:19]
	global_load_lds_dwordx4 v[210:211], off
	s_add_u32 m0, s101, 0xc000
	v_lshl_add_u64 v[210:211], v[154:155], 0, s[18:19]
	global_load_lds_dwordx4 v[210:211], off
	ds_read_b128 v[96:99], v220 offset:0
	ds_read_b128 v[100:103], v220 offset:2048
	ds_read_b128 v[104:107], v220 offset:4096
	ds_read_b128 v[108:111], v220 offset:6144
	ds_read_b128 v[112:115], v221 offset:0
	ds_read_b128 v[116:119], v221 offset:2048
	ds_read_b128 v[120:123], v221 offset:4096
	ds_read_b128 v[124:127], v221 offset:6144
	v_mfma_f32_16x16x32_bf16 v[0:3], v[192:195], v[128:131], v[0:3]
	v_mfma_f32_16x16x32_bf16 v[4:7], v[196:199], v[128:131], v[4:7]
	s_add_u32 m0, s101, 0x9000
	v_lshl_add_u64 v[210:211], v[156:157], 0, s[18:19]
	global_load_lds_dwordx4 v[210:211], off
	v_mfma_f32_16x16x32_bf16 v[8:11], v[200:203], v[128:131], v[8:11]
	v_mfma_f32_16x16x32_bf16 v[12:15], v[204:207], v[128:131], v[12:15]
	s_add_u32 m0, s101, 0xd000
	v_lshl_add_u64 v[210:211], v[158:159], 0, s[18:19]
	global_load_lds_dwordx4 v[210:211], off
	v_mfma_f32_16x16x32_bf16 v[16:19], v[192:195], v[132:135], v[16:19]
	v_mfma_f32_16x16x32_bf16 v[20:23], v[196:199], v[132:135], v[20:23]
	s_add_u32 m0, s101, 0xa000
	v_lshl_add_u64 v[210:211], v[160:161], 0, s[18:19]
	global_load_lds_dwordx4 v[210:211], off
	v_mfma_f32_16x16x32_bf16 v[24:27], v[200:203], v[132:135], v[24:27]
	v_mfma_f32_16x16x32_bf16 v[28:31], v[204:207], v[132:135], v[28:31]
	s_add_u32 m0, s101, 0xe000
	v_lshl_add_u64 v[210:211], v[162:163], 0, s[18:19]
	global_load_lds_dwordx4 v[210:211], off
	v_mfma_f32_16x16x32_bf16 v[32:35], v[192:195], v[136:139], v[32:35]
	v_mfma_f32_16x16x32_bf16 v[36:39], v[196:199], v[136:139], v[36:39]
	s_add_u32 m0, s101, 0xb000
	v_lshl_add_u64 v[210:211], v[164:165], 0, s[18:19]
	global_load_lds_dwordx4 v[210:211], off
	v_mfma_f32_16x16x32_bf16 v[40:43], v[200:203], v[136:139], v[40:43]
	v_mfma_f32_16x16x32_bf16 v[44:47], v[204:207], v[136:139], v[44:47]
	s_add_u32 m0, s101, 0xf000
	v_lshl_add_u64 v[210:211], v[166:167], 0, s[18:19]
	global_load_lds_dwordx4 v[210:211], off
	v_mfma_f32_16x16x32_bf16 v[48:51], v[192:195], v[140:143], v[48:51]
	v_mfma_f32_16x16x32_bf16 v[52:55], v[196:199], v[140:143], v[52:55]
	v_mfma_f32_16x16x32_bf16 v[56:59], v[200:203], v[140:143], v[56:59]
	v_mfma_f32_16x16x32_bf16 v[60:63], v[204:207], v[140:143], v[60:63]
	s_waitcnt lgkmcnt(8)
; DI float ssq_f(u64 v) { return (float)v * (1.f / 1048576.f); }
; #define SB_ __builtin_amdgcn_sched_barrier(0)
; template <bool SWAP, bool HALF>
; DI void gemm_mainloop(const GemmDesc& d, int m0, int n0, bf16_t* smem, f32x16 (&acc)[2][2], int dry) {
;     ...
;   auto stage = [&](int cur, u32x4 (&ran)[4], u32x4 (&rbn)[4], int ks) {
;     ldf(cur, 1, 1); SB_;
;     mma(0); SB_;
;     ldf(cur, 2, 0); SB_;
;     lw(ran, rbn, cur ^ 1);
;     gl(ran, rbn, (ks + 3 < nk) ? ks + 3 : nk - 1);
;     SB_;
;     mma(1); SB_;
;     __syncthreads();
;     ldf(cur, 3, 1); SB_;
;     mma(0); SB_;
;     ldf(cur ^ 1, 0, 0);
;     SB_;
;     mma(1); SB_;
;     __syncthreads();
;   };
;   gl(ra0, rb0, 0);
;   gl(ra1, rb1, 1);
;   lw(ra0, rb0, 0);
;   gl(ra0, rb0, 2);
;   __syncthreads();
;   ldf(0, 0, 0);
; #pragma unroll 1
;   for (int ks = 0; ks < nk; ks += 2) {
;     stage(0, ra1, rb1, ks);
;     stage(1, ra0, rb0, ks + 1);
;   }
; DI void gemm_tile(const GemmDesc& d, int m0, int n0, bf16_t* smem, int dry) {
;     ...
;   } else if (t < 128) {
;     rs_s[t] = rsqrtf(ssq_f(myss) * d.inv_dim + EPS);
;   }
	v_mfma_f32_16x16x32_bf16 v[0:3], v[80:83], v[64:67], v[0:3]
	v_mfma_f32_16x16x32_bf16 v[4:7], v[84:87], v[64:67], v[4:7]
	v_mfma_f32_16x16x32_bf16 v[8:11], v[88:91], v[64:67], v[8:11]
	v_mfma_f32_16x16x32_bf16 v[12:15], v[92:95], v[64:67], v[12:15]
	v_mfma_f32_16x16x32_bf16 v[16:19], v[80:83], v[68:71], v[16:19]
	v_mfma_f32_16x16x32_bf16 v[20:23], v[84:87], v[68:71], v[20:23]
	v_mfma_f32_16x16x32_bf16 v[24:27], v[88:91], v[68:71], v[24:27]
	v_mfma_f32_16x16x32_bf16 v[28:31], v[92:95], v[68:71], v[28:31]
	v_mfma_f32_16x16x32_bf16 v[32:35], v[80:83], v[72:75], v[32:35]
	v_mfma_f32_16x16x32_bf16 v[36:39], v[84:87], v[72:75], v[36:39]
	v_mfma_f32_16x16x32_bf16 v[40:43], v[88:91], v[72:75], v[40:43]
	v_mfma_f32_16x16x32_bf16 v[44:47], v[92:95], v[72:75], v[44:47]
	v_mfma_f32_16x16x32_bf16 v[48:51], v[80:83], v[76:79], v[48:51]
	v_mfma_f32_16x16x32_bf16 v[52:55], v[84:87], v[76:79], v[52:55]
	v_mfma_f32_16x16x32_bf16 v[56:59], v[88:91], v[76:79], v[56:59]
	v_mfma_f32_16x16x32_bf16 v[60:63], v[92:95], v[76:79], v[60:63]
	s_cmp_lt_u32 s4, 12
	s_waitcnt vmcnt(0) lgkmcnt(0)
	s_barrier
	s_cbranch_scc1 .LBB0_627
	ds_read_b128 v[64:67], v168 offset:32768
	ds_read_b128 v[68:71], v168 offset:34816
	ds_read_b128 v[72:75], v168 offset:36864
	ds_read_b128 v[76:79], v168 offset:38912
	ds_read_b128 v[80:83], v169 offset:32768
	ds_read_b128 v[84:87], v169 offset:34816
	ds_read_b128 v[88:91], v169 offset:36864
	ds_read_b128 v[92:95], v169 offset:38912
	ds_read_b128 v[128:131], v220 offset:32768
	ds_read_b128 v[132:135], v220 offset:34816
	ds_read_b128 v[136:139], v220 offset:36864
	ds_read_b128 v[140:143], v220 offset:38912
	ds_read_b128 v[192:195], v221 offset:32768
	ds_read_b128 v[196:199], v221 offset:34816
	ds_read_b128 v[200:203], v221 offset:36864
	ds_read_b128 v[204:207], v221 offset:38912
	v_mfma_f32_16x16x32_bf16 v[0:3], v[112:115], v[96:99], v[0:3]
	v_mfma_f32_16x16x32_bf16 v[4:7], v[116:119], v[96:99], v[4:7]
	v_mfma_f32_16x16x32_bf16 v[8:11], v[120:123], v[96:99], v[8:11]
	v_mfma_f32_16x16x32_bf16 v[12:15], v[124:127], v[96:99], v[12:15]
	v_mfma_f32_16x16x32_bf16 v[16:19], v[112:115], v[100:103], v[16:19]
	v_mfma_f32_16x16x32_bf16 v[20:23], v[116:119], v[100:103], v[20:23]
	v_mfma_f32_16x16x32_bf16 v[24:27], v[120:123], v[100:103], v[24:27]
	v_mfma_f32_16x16x32_bf16 v[28:31], v[124:127], v[100:103], v[28:31]
	v_mfma_f32_16x16x32_bf16 v[32:35], v[112:115], v[104:107], v[32:35]
	v_mfma_f32_16x16x32_bf16 v[36:39], v[116:119], v[104:107], v[36:39]
	v_mfma_f32_16x16x32_bf16 v[40:43], v[120:123], v[104:107], v[40:43]
	v_mfma_f32_16x16x32_bf16 v[44:47], v[124:127], v[104:107], v[44:47]
	v_mfma_f32_16x16x32_bf16 v[48:51], v[112:115], v[108:111], v[48:51]
	v_mfma_f32_16x16x32_bf16 v[52:55], v[116:119], v[108:111], v[52:55]
	v_mfma_f32_16x16x32_bf16 v[56:59], v[120:123], v[108:111], v[56:59]
	v_mfma_f32_16x16x32_bf16 v[60:63], v[124:127], v[108:111], v[60:63]
	s_waitcnt lgkmcnt(8)
	v_mfma_f32_16x16x32_bf16 v[0:3], v[80:83], v[64:67], v[0:3]
	v_mfma_f32_16x16x32_bf16 v[4:7], v[84:87], v[64:67], v[4:7]
	v_mfma_f32_16x16x32_bf16 v[8:11], v[88:91], v[64:67], v[8:11]
	v_mfma_f32_16x16x32_bf16 v[12:15], v[92:95], v[64:67], v[12:15]
	v_mfma_f32_16x16x32_bf16 v[16:19], v[80:83], v[68:71], v[16:19]
	v_mfma_f32_16x16x32_bf16 v[20:23], v[84:87], v[68:71], v[20:23]
	v_mfma_f32_16x16x32_bf16 v[24:27], v[88:91], v[68:71], v[24:27]
	v_mfma_f32_16x16x32_bf16 v[28:31], v[92:95], v[68:71], v[28:31]
	v_mfma_f32_16x16x32_bf16 v[32:35], v[80:83], v[72:75], v[32:35]
	v_mfma_f32_16x16x32_bf16 v[36:39], v[84:87], v[72:75], v[36:39]
	v_mfma_f32_16x16x32_bf16 v[40:43], v[88:91], v[72:75], v[40:43]
	v_mfma_f32_16x16x32_bf16 v[44:47], v[92:95], v[72:75], v[44:47]
	v_mfma_f32_16x16x32_bf16 v[48:51], v[80:83], v[76:79], v[48:51]
	v_mfma_f32_16x16x32_bf16 v[52:55], v[84:87], v[76:79], v[52:55]
	v_mfma_f32_16x16x32_bf16 v[56:59], v[88:91], v[76:79], v[56:59]
	v_mfma_f32_16x16x32_bf16 v[60:63], v[92:95], v[76:79], v[60:63]
	s_waitcnt lgkmcnt(0)
	s_barrier
	v_mfma_f32_16x16x32_bf16 v[0:3], v[192:195], v[128:131], v[0:3]
	v_mfma_f32_16x16x32_bf16 v[4:7], v[196:199], v[128:131], v[4:7]
	v_mfma_f32_16x16x32_bf16 v[8:11], v[200:203], v[128:131], v[8:11]
	v_mfma_f32_16x16x32_bf16 v[12:15], v[204:207], v[128:131], v[12:15]
	v_mfma_f32_16x16x32_bf16 v[16:19], v[192:195], v[132:135], v[16:19]
	v_mfma_f32_16x16x32_bf16 v[20:23], v[196:199], v[132:135], v[20:23]
	v_mfma_f32_16x16x32_bf16 v[24:27], v[200:203], v[132:135], v[24:27]
	v_mfma_f32_16x16x32_bf16 v[28:31], v[204:207], v[132:135], v[28:31]
	v_mfma_f32_16x16x32_bf16 v[32:35], v[192:195], v[136:139], v[32:35]
	v_mfma_f32_16x16x32_bf16 v[36:39], v[196:199], v[136:139], v[36:39]
	v_mfma_f32_16x16x32_bf16 v[40:43], v[200:203], v[136:139], v[40:43]
	v_mfma_f32_16x16x32_bf16 v[44:47], v[204:207], v[136:139], v[44:47]
	v_mfma_f32_16x16x32_bf16 v[48:51], v[192:195], v[140:143], v[48:51]
	v_mfma_f32_16x16x32_bf16 v[52:55], v[196:199], v[140:143], v[52:55]
	v_mfma_f32_16x16x32_bf16 v[56:59], v[200:203], v[140:143], v[56:59]
	v_mfma_f32_16x16x32_bf16 v[60:63], v[204:207], v[140:143], v[60:63]
	s_and_saveexec_b64 s[4:5], vcc
	s_cbranch_execz .LBB0_630
	s_mov_b32 s8, 0x800000
	s_waitcnt vmcnt(15)
	v_mul_f32_e32 v64, 0x4b800000, v170
	v_cmp_gt_f32_e32 vcc, s8, v170
	v_lshl_add_u32 v65, v150, 2, v181
	s_nop 0
	v_cndmask_b32_e32 v64, v170, v64, vcc
	v_rsq_f32_e32 v64, v64
	s_nop 0
	v_mul_f32_e32 v66, 0x45800000, v64
	v_cndmask_b32_e32 v64, v64, v66, vcc
	ds_write_b32 v65, v64

; DI int otid() { int t = threadIdx.x; asm volatile("" : "+v"(t)); return t; }
; template <bool SWAP, bool HALF>
; DI void gemm_mainloop(const GemmDesc& d, int m0, int n0, bf16_t* smem, f32x16 (&acc)[2][2], int dry) {
;   const int t = otid(), lane = t & 63, w = t >> 6, wm = w >> 1, wn = w & 1, r = lane & 31, hh = lane >> 5;
;   const int lrow = t >> 3, lkc = t & 7;
;   const bf16_t* ap[4]; const bf16_t* bp[4];
; #pragma unroll
;   for (int i = 0; i < 4; ++i) {
;     int am = m0 + lrow + 32 * i; am = am < M ? am : M - 1;
;     ap[i] = d.A + (size_t)am * d.lda + lkc * 8 + (d.a_grp ? (n0 / d.a_grp) * d.a_grp : 0);
;     bp[i] = d.Bt + (size_t)(n0 + lrow + 32 * i) * d.ldb + lkc * 8;
;   }
; #pragma unroll
;   for (int a = 0; a < 2; ++a)
; #pragma unroll
;     for (int b = 0; b < 2; ++b)
; #pragma unroll
;       for (int i = 0; i < 16; ++i) acc[a][b][i] = 0.f;
;   u32x4 ra0[4], rb0[4], ra1[4], rb1[4];
;   const int nk = d.K >> 6;
;   const int lds_w = lrow * LST + lkc * 8;
;     ...
;   for (int i = slot; i < total; i += nslots) {
;     const int g = i / (8 * nN), j = i - g * 8 * nN;
;     const int gm = (cx - g * 8) < 8 ? (cx - g * 8) : 8;
;     const int mt = (g * 8 + j % gm) * 8 + x, nt = j / gm;
;     gemm_tile(d, mt * 128, nt * 128, smem, dry);
.LBB0_919:
	s_lshr_b32 s1, s8, 3
	s_and_b32 s1, s1, 0xffffff8
	v_readlane_b32 s5, v228, 38
	s_sub_i32 s5, s5, s1
	s_min_i32 s5, s5, 8
	s_abs_i32 s9, s5
	v_cvt_f32_u32_e32 v0, s9
	s_sub_i32 s10, 0, s9
	s_lshl_b32 s4, s1, 3
	s_sub_i32 s4, s8, s4
	v_rcp_iflag_f32_e32 v0, v0
	s_abs_i32 s7, s4
	s_xor_b32 s6, s4, s5
	s_ashr_i32 s6, s6, 31
	v_mul_f32_e32 v0, 0x4f7ffffe, v0
	v_cvt_u32_f32_e32 v0, v0
	v_mov_b32_e32 v150, v172
	v_mov_b32_e32 v32, v172
	v_readfirstlane_b32 s11, v0
	s_mul_i32 s10, s10, s11
	s_mul_hi_u32 s10, s11, s10
	s_add_i32 s11, s11, s10
	s_mul_hi_u32 s10, s7, s11
	s_mul_i32 s11, s10, s9
	s_sub_i32 s7, s7, s11
	s_add_i32 s11, s10, 1
	s_sub_i32 s12, s7, s9
	s_cmp_ge_u32 s7, s9
	s_cselect_b32 s10, s11, s10
	s_cselect_b32 s7, s12, s7
	s_add_i32 s11, s10, 1
	s_cmp_ge_u32 s7, s9
	s_cselect_b32 s7, s11, s10
	s_xor_b32 s7, s7, s6
	s_sub_i32 s6, s7, s6
	s_mul_i32 s5, s6, s5
	s_sub_i32 s4, s4, s5
	s_add_i32 s1, s1, s4
	s_lshl_b32 s1, s1, 10
	s_or_b32 s9, s1, s29
	v_lshlrev_b32_e32 v0, 3, v32
	v_ashrrev_i32_e32 v6, 3, v32
	v_and_b32_e32 v33, 56, v0
	s_lshl_b32 s4, s6, 7
	v_add_u32_e32 v7, s9, v6
	v_lshlrev_b32_e32 v144, 1, v33
	v_lshl_add_u64 v[0:1], s[68:69], 0, v[144:145]
	v_add_u32_e32 v2, s4, v6
	v_readlane_b32 s76, v228, 60
	v_min_i32_e32 v3, 0x803f, v7
	s_movk_i32 s1, 0xc00
	v_readlane_b32 s88, v223, 8
	v_readlane_b32 s89, v223, 9
	v_mad_i64_i32 v[152:153], s[6:7], v3, s1, v[0:1]
	v_ashrrev_i32_e32 v3, 31, v2
	v_lshl_add_u64 v[4:5], s[88:89], 0, v[144:145]
	v_lshlrev_b64 v[2:3], 11, v[2:3]
	v_lshl_add_u64 v[154:155], v[4:5], 0, v[2:3]
	v_min_i32_e32 v2, 0x801f, v7
	v_add_u32_e32 v2, 32, v2
	v_mad_i64_i32 v[156:157], s[6:7], v2, s1, v[0:1]
	v_min_i32_e32 v2, 0x7fff, v7
	s_mov_b64 s[6:7], 0x10000
	v_add_u32_e32 v2, 64, v2
	v_lshl_add_u64 v[158:159], v[154:155], 0, s[6:7]
	v_mad_i64_i32 v[160:161], s[6:7], v2, s1, v[0:1]
	v_min_i32_e32 v2, 0x7fdf, v7
	s_mov_b64 s[6:7], 0x20000
	v_add_u32_e32 v2, 0x60, v2
	v_lshl_add_u64 v[162:163], v[154:155], 0, s[6:7]
	v_mad_i64_i32 v[164:165], s[6:7], v2, s1, v[0:1]
	s_mov_b64 s[6:7], 0x30000
	s_movk_i32 s1, 0x48
	v_lshl_add_u64 v[166:167], v[154:155], 0, s[6:7]
	v_and_b32_e32 v34, 31, v32
	v_mul_lo_u32 v35, v6, s1
	v_readlane_b32 s77, v228, 61
	v_readlane_b32 s78, v228, 62
	v_readlane_b32 s79, v228, 63
	v_readlane_b32 s80, v223, 0
	v_readlane_b32 s81, v223, 1
	v_readlane_b32 s82, v223, 2
	v_readlane_b32 s83, v223, 3
	v_readlane_b32 s84, v223, 4
	v_readlane_b32 s85, v223, 5
	v_readlane_b32 s86, v223, 6
	v_readlane_b32 s87, v223, 7
	v_readlane_b32 s90, v223, 10
	v_readlane_b32 s91, v223, 11
	s_mov_b32 s1, 0x10000
	s_waitcnt vmcnt(19)
	v_add_co_u32_e32 v12, vcc, s1, v154
	s_nop 1
	v_addc_co_u32_e32 v13, vcc, 0, v155, vcc
	s_nop 0
	s_mov_b32 s1, 0x20000
	v_add_co_u32_e32 v20, vcc, s1, v154
	s_nop 1
	v_addc_co_u32_e32 v21, vcc, 0, v155, vcc
	s_nop 0
	s_mov_b32 s1, 0x30000
	v_add_co_u32_e32 v28, vcc, s1, v154
	s_nop 1
	v_addc_co_u32_e32 v29, vcc, 0, v155, vcc
	s_nop 0
	v_add_lshl_u32 v144, v35, v33, 1
	s_waitcnt vmcnt(15)
	s_waitcnt vmcnt(14)
	s_waitcnt vmcnt(13)
	s_waitcnt vmcnt(12)
	s_waitcnt vmcnt(11)
	s_waitcnt vmcnt(10)
	s_waitcnt vmcnt(9)
	s_waitcnt vmcnt(8)
	v_lshrrev_b32_e32 v0, 1, v32
	v_and_or_b32 v1, v0, s72, v34
	v_and_b32_e32 v0, 16, v0
	s_movk_i32 s1, 0x90
	v_mad_u64_u32 v[168:169], s[6:7], v1, s1, v[0:1]
	v_and_b32_e32 v1, 0x5f, v32
	v_mul_u32_u24_e32 v1, 0x48, v1
	v_lshl_add_u32 v169, v1, 1, v0
	v_bfe_u32 v212, v172, 4, 3
	v_lshlrev_b32_e32 v212, 4, v212
	v_and_b32_e32 v213, 7, v172
	v_lshlrev_b32_e32 v213, 4, v213
	v_xor_b32_e32 v214, v213, v212
	v_sub_u32_e32 v210, v214, v213
	v_ashrrev_i32_e32 v211, 31, v210
	v_lshl_add_u64 v[152:153], v[152:153], 0, v[210:211]
	v_xor_b32_e32 v154, v154, v212
	v_lshl_add_u64 v[156:157], v[156:157], 0, v[210:211]
	v_xor_b32_e32 v158, v158, v212
	v_lshl_add_u64 v[160:161], v[160:161], 0, v[210:211]
	v_xor_b32_e32 v162, v162, v212
	v_lshl_add_u64 v[164:165], v[164:165], 0, v[210:211]
	v_xor_b32_e32 v166, v166, v212
	v_lshrrev_b32_e32 v213, 6, v172
	s_nop 1
	v_readfirstlane_b32 s101, v213
	s_lshl_b32 s101, s101, 10
	s_add_u32 m0, s101, 0x0
	s_nop 0
	global_load_lds_dwordx4 v[152:153], off
	s_add_u32 m0, s101, 0x4000
	s_nop 0
	global_load_lds_dwordx4 v[154:155], off
	s_add_u32 m0, s101, 0x1000
	s_nop 0
	global_load_lds_dwordx4 v[156:157], off
	s_add_u32 m0, s101, 0x5000
	s_nop 0
	global_load_lds_dwordx4 v[158:159], off
	s_add_u32 m0, s101, 0x2000
	s_nop 0
	global_load_lds_dwordx4 v[160:161], off
	s_add_u32 m0, s101, 0x6000
	s_nop 0
	global_load_lds_dwordx4 v[162:163], off
	s_add_u32 m0, s101, 0x3000
	s_nop 0
	global_load_lds_dwordx4 v[164:165], off
	s_add_u32 m0, s101, 0x7000
	s_nop 0
	global_load_lds_dwordx4 v[166:167], off
	v_and_b32_e32 v212, 15, v172
	v_bfe_u32 v213, v172, 4, 2
	v_lshrrev_b32_e32 v214, 1, v212
	v_xor_b32_e32 v213, v213, v214
	v_lshlrev_b32_e32 v213, 4, v213
	v_lshl_or_b32 v212, v212, 7, v213
	v_lshrrev_b32_e32 v214, 7, v172
	v_lshl_add_u32 v168, v214, 13, v212
	v_bfe_u32 v214, v172, 6, 1
	v_lshl_add_u32 v169, v214, 13, v212
	v_add_u32_e32 v169, 0x4000, v169
	v_xor_b32_e32 v220, 64, v168
	v_xor_b32_e32 v221, 64, v169
	s_waitcnt vmcnt(0) lgkmcnt(0)
	s_barrier
; #define SB_ __builtin_amdgcn_sched_barrier(0)
; template <bool SWAP, bool HALF>
; DI void gemm_mainloop(const GemmDesc& d, int m0, int n0, bf16_t* smem, f32x16 (&acc)[2][2], int dry) {
;     ...
;   for (int a = 0; a < 2; ++a)
; #pragma unroll
;     for (int b = 0; b < 2; ++b)
; #pragma unroll
;       for (int i = 0; i < 16; ++i) acc[a][b][i] = 0.f;
;     ...
;   auto stage = [&](int cur, u32x4 (&ran)[4], u32x4 (&rbn)[4], int ks) {
;     ldf(cur, 1, 1); SB_;
;     mma(0); SB_;
;     ldf(cur, 2, 0); SB_;
;     lw(ran, rbn, cur ^ 1);
;     gl(ran, rbn, (ks + 3 < nk) ? ks + 3 : nk - 1);
;     SB_;
;     mma(1); SB_;
;     __syncthreads();
;     ldf(cur, 3, 1); SB_;
;     mma(0); SB_;
;     ldf(cur ^ 1, 0, 0);
;     SB_;
;     mma(1); SB_;
;     __syncthreads();
;   };
;   gl(ra0, rb0, 0);
;   gl(ra1, rb1, 1);
;   lw(ra0, rb0, 0);
;   gl(ra0, rb0, 2);
;   __syncthreads();
;   ldf(0, 0, 0);
; #pragma unroll 1
;   for (int ks = 0; ks < nk; ks += 2) {
;     stage(0, ra1, rb1, ks);
	v_mov_b32_e32 v0, 0
	v_add_u32_e32 v170, 0x9000, v144
	s_mov_b32 s1, -2
	v_mov_b32_e32 v1, v0
	v_mov_b32_e32 v2, v0
	v_mov_b32_e32 v3, v0
	v_mov_b32_e32 v4, v0
	v_mov_b32_e32 v5, v0
	v_mov_b32_e32 v6, v0
	v_mov_b32_e32 v7, v0
	v_mov_b32_e32 v8, v0
	v_mov_b32_e32 v9, v0
	v_mov_b32_e32 v10, v0
	v_mov_b32_e32 v11, v0
	v_mov_b32_e32 v12, v0
	v_mov_b32_e32 v13, v0
	v_mov_b32_e32 v14, v0
	v_mov_b32_e32 v15, v0
	v_mov_b32_e32 v16, v0
	v_mov_b32_e32 v17, v0
	v_mov_b32_e32 v18, v0
	v_mov_b32_e32 v19, v0
	v_mov_b32_e32 v20, v0
	v_mov_b32_e32 v21, v0
	v_mov_b32_e32 v22, v0
	v_mov_b32_e32 v23, v0
	v_mov_b32_e32 v24, v0
	v_mov_b32_e32 v25, v0
	v_mov_b32_e32 v26, v0
	v_mov_b32_e32 v27, v0
	v_mov_b32_e32 v28, v0
	v_mov_b32_e32 v29, v0
	v_mov_b32_e32 v30, v0
	v_mov_b32_e32 v31, v0
	v_mov_b32_e32 v32, v0
	v_mov_b32_e32 v33, v0
	v_mov_b32_e32 v34, v0
	v_mov_b32_e32 v35, v0
	v_mov_b32_e32 v36, v0
	v_mov_b32_e32 v37, v0
	v_mov_b32_e32 v38, v0
	v_mov_b32_e32 v39, v0
	v_mov_b32_e32 v40, v0
	v_mov_b32_e32 v41, v0
	v_mov_b32_e32 v42, v0
	v_mov_b32_e32 v43, v0
	v_mov_b32_e32 v44, v0
	v_mov_b32_e32 v45, v0
	v_mov_b32_e32 v46, v0
	v_mov_b32_e32 v47, v0
	v_mov_b32_e32 v48, v0
	v_mov_b32_e32 v49, v0
	v_mov_b32_e32 v50, v0
	v_mov_b32_e32 v51, v0
	v_mov_b32_e32 v52, v0
	v_mov_b32_e32 v53, v0
	v_mov_b32_e32 v54, v0
	v_mov_b32_e32 v55, v0
	v_mov_b32_e32 v56, v0
	v_mov_b32_e32 v57, v0
	v_mov_b32_e32 v58, v0
	v_mov_b32_e32 v59, v0
	v_mov_b32_e32 v60, v0
	v_mov_b32_e32 v61, v0
	v_mov_b32_e32 v62, v0
	v_mov_b32_e32 v63, v0
	ds_read_b128 v[64:67], v168 offset:0
	ds_read_b128 v[68:71], v168 offset:2048
	ds_read_b128 v[72:75], v168 offset:4096
	ds_read_b128 v[76:79], v168 offset:6144
	ds_read_b128 v[80:83], v169 offset:0
	ds_read_b128 v[84:87], v169 offset:2048
	ds_read_b128 v[88:91], v169 offset:4096
	ds_read_b128 v[92:95], v169 offset:6144
	s_add_i32 s5, s1, 3
	s_min_u32 s5, s5, 15
	s_lshl_b32 s18, s5, 7
	s_mul_i32 s6, s5, 0xc0
	s_mov_b32 s7, s19
	s_add_u32 m0, s101, 0x8000
	v_lshl_add_u64 v[210:211], v[152:153], 0, s[6:7]
	global_load_lds_dwordx4 v[210:211], off
	s_add_u32 m0, s101, 0xc000
	v_lshl_add_u64 v[210:211], v[154:155], 0, s[18:19]
	global_load_lds_dwordx4 v[210:211], off
	ds_read_b128 v[96:99], v220 offset:0
	ds_read_b128 v[100:103], v220 offset:2048
	ds_read_b128 v[104:107], v220 offset:4096
	ds_read_b128 v[108:111], v220 offset:6144
	ds_read_b128 v[112:115], v221 offset:0
	ds_read_b128 v[116:119], v221 offset:2048
	ds_read_b128 v[120:123], v221 offset:4096
	ds_read_b128 v[124:127], v221 offset:6144
	s_waitcnt lgkmcnt(8)
	v_mfma_f32_16x16x32_bf16 v[0:3], v[80:83], v[64:67], v[0:3]
	v_mfma_f32_16x16x32_bf16 v[4:7], v[84:87], v[64:67], v[4:7]
	s_add_u32 m0, s101, 0x9000
	v_lshl_add_u64 v[210:211], v[156:157], 0, s[6:7]
	global_load_lds_dwordx4 v[210:211], off
	v_mfma_f32_16x16x32_bf16 v[8:11], v[88:91], v[64:67], v[8:11]
	v_mfma_f32_16x16x32_bf16 v[12:15], v[92:95], v[64:67], v[12:15]
	s_add_u32 m0, s101, 0xd000
	v_lshl_add_u64 v[210:211], v[158:159], 0, s[18:19]
	global_load_lds_dwordx4 v[210:211], off
	v_mfma_f32_16x16x32_bf16 v[16:19], v[80:83], v[68:71], v[16:19]
	v_mfma_f32_16x16x32_bf16 v[20:23], v[84:87], v[68:71], v[20:23]
	s_add_u32 m0, s101, 0xa000
	v_lshl_add_u64 v[210:211], v[160:161], 0, s[6:7]
	global_load_lds_dwordx4 v[210:211], off
	v_mfma_f32_16x16x32_bf16 v[24:27], v[88:91], v[68:71], v[24:27]
	v_mfma_f32_16x16x32_bf16 v[28:31], v[92:95], v[68:71], v[28:31]
	s_add_u32 m0, s101, 0xe000
	v_lshl_add_u64 v[210:211], v[162:163], 0, s[18:19]
	global_load_lds_dwordx4 v[210:211], off
	v_mfma_f32_16x16x32_bf16 v[32:35], v[80:83], v[72:75], v[32:35]
	v_mfma_f32_16x16x32_bf16 v[36:39], v[84:87], v[72:75], v[36:39]
	s_add_u32 m0, s101, 0xb000
	v_lshl_add_u64 v[210:211], v[164:165], 0, s[6:7]
	global_load_lds_dwordx4 v[210:211], off
	v_mfma_f32_16x16x32_bf16 v[40:43], v[88:91], v[72:75], v[40:43]
	v_mfma_f32_16x16x32_bf16 v[44:47], v[92:95], v[72:75], v[44:47]
	s_add_u32 m0, s101, 0xf000
	v_lshl_add_u64 v[210:211], v[166:167], 0, s[18:19]
	global_load_lds_dwordx4 v[210:211], off
	v_mfma_f32_16x16x32_bf16 v[48:51], v[80:83], v[76:79], v[48:51]
	v_mfma_f32_16x16x32_bf16 v[52:55], v[84:87], v[76:79], v[52:55]
	v_mfma_f32_16x16x32_bf16 v[56:59], v[88:91], v[76:79], v[56:59]
	v_mfma_f32_16x16x32_bf16 v[60:63], v[92:95], v[76:79], v[60:63]
	s_waitcnt vmcnt(0) lgkmcnt(0)
	s_barrier
; #define SB_ __builtin_amdgcn_sched_barrier(0)
; template <bool SWAP, bool HALF>
; DI void gemm_mainloop(const GemmDesc& d, int m0, int n0, bf16_t* smem, f32x16 (&acc)[2][2], int dry) {
;     ...
;   auto stage = [&](int cur, u32x4 (&ran)[4], u32x4 (&rbn)[4], int ks) {
;     ldf(cur, 1, 1); SB_;
;     mma(0); SB_;
;     ldf(cur, 2, 0); SB_;
;     lw(ran, rbn, cur ^ 1);
;     gl(ran, rbn, (ks + 3 < nk) ? ks + 3 : nk - 1);
;     SB_;
;     mma(1); SB_;
;     __syncthreads();
;     ldf(cur, 3, 1); SB_;
;     mma(0); SB_;
;     ldf(cur ^ 1, 0, 0);
;     SB_;
;     mma(1); SB_;
;     __syncthreads();
;   };
;   gl(ra0, rb0, 0);
;   gl(ra1, rb1, 1);
;   lw(ra0, rb0, 0);
;   gl(ra0, rb0, 2);
;   __syncthreads();
;   ldf(0, 0, 0);
; #pragma unroll 1
;   for (int ks = 0; ks < nk; ks += 2) {
;     stage(0, ra1, rb1, ks);
;     stage(1, ra0, rb0, ks + 1);
;   }
.LBB0_920:
	ds_read_b128 v[64:67], v168 offset:32768
	ds_read_b128 v[68:71], v168 offset:34816
	ds_read_b128 v[72:75], v168 offset:36864
	ds_read_b128 v[76:79], v168 offset:38912
	ds_read_b128 v[80:83], v169 offset:32768
	ds_read_b128 v[84:87], v169 offset:34816
	ds_read_b128 v[88:91], v169 offset:36864
	ds_read_b128 v[92:95], v169 offset:38912
	s_add_i32 s1, s1, 2
	s_add_i32 s5, s1, 2
	s_min_u32 s5, s5, 15
	s_lshl_b32 s18, s5, 7
	s_mul_i32 s6, s5, 0xc0
	s_mov_b32 s7, s19
	s_add_u32 m0, s101, 0x0
	v_lshl_add_u64 v[210:211], v[152:153], 0, s[6:7]
	global_load_lds_dwordx4 v[210:211], off
	s_add_u32 m0, s101, 0x4000
	v_lshl_add_u64 v[210:211], v[154:155], 0, s[18:19]
	global_load_lds_dwordx4 v[210:211], off
	ds_read_b128 v[128:131], v220 offset:32768
	ds_read_b128 v[132:135], v220 offset:34816
	ds_read_b128 v[136:139], v220 offset:36864
	ds_read_b128 v[140:143], v220 offset:38912
	ds_read_b128 v[192:195], v221 offset:32768
	ds_read_b128 v[196:199], v221 offset:34816
	ds_read_b128 v[200:203], v221 offset:36864
	ds_read_b128 v[204:207], v221 offset:38912
	v_mfma_f32_16x16x32_bf16 v[0:3], v[112:115], v[96:99], v[0:3]
	v_mfma_f32_16x16x32_bf16 v[4:7], v[116:119], v[96:99], v[4:7]
	s_add_u32 m0, s101, 0x1000
	v_lshl_add_u64 v[210:211], v[156:157], 0, s[6:7]
	global_load_lds_dwordx4 v[210:211], off
	v_mfma_f32_16x16x32_bf16 v[8:11], v[120:123], v[96:99], v[8:11]
	v_mfma_f32_16x16x32_bf16 v[12:15], v[124:127], v[96:99], v[12:15]
	s_add_u32 m0, s101, 0x5000
	v_lshl_add_u64 v[210:211], v[158:159], 0, s[18:19]
	global_load_lds_dwordx4 v[210:211], off
	v_mfma_f32_16x16x32_bf16 v[16:19], v[112:115], v[100:103], v[16:19]
	v_mfma_f32_16x16x32_bf16 v[20:23], v[116:119], v[100:103], v[20:23]
	s_add_u32 m0, s101, 0x2000
	v_lshl_add_u64 v[210:211], v[160:161], 0, s[6:7]
	global_load_lds_dwordx4 v[210:211], off
	v_mfma_f32_16x16x32_bf16 v[24:27], v[120:123], v[100:103], v[24:27]
	v_mfma_f32_16x16x32_bf16 v[28:31], v[124:127], v[100:103], v[28:31]
	s_add_u32 m0, s101, 0x6000
	v_lshl_add_u64 v[210:211], v[162:163], 0, s[18:19]
	global_load_lds_dwordx4 v[210:211], off
	v_mfma_f32_16x16x32_bf16 v[32:35], v[112:115], v[104:107], v[32:35]
	v_mfma_f32_16x16x32_bf16 v[36:39], v[116:119], v[104:107], v[36:39]
	s_add_u32 m0, s101, 0x3000
	v_lshl_add_u64 v[210:211], v[164:165], 0, s[6:7]
	global_load_lds_dwordx4 v[210:211], off
	v_mfma_f32_16x16x32_bf16 v[40:43], v[120:123], v[104:107], v[40:43]
	v_mfma_f32_16x16x32_bf16 v[44:47], v[124:127], v[104:107], v[44:47]
	s_add_u32 m0, s101, 0x7000
	v_lshl_add_u64 v[210:211], v[166:167], 0, s[18:19]
	global_load_lds_dwordx4 v[210:211], off
	v_mfma_f32_16x16x32_bf16 v[48:51], v[112:115], v[108:111], v[48:51]
	v_mfma_f32_16x16x32_bf16 v[52:55], v[116:119], v[108:111], v[52:55]
	v_mfma_f32_16x16x32_bf16 v[56:59], v[120:123], v[108:111], v[56:59]
	v_mfma_f32_16x16x32_bf16 v[60:63], v[124:127], v[108:111], v[60:63]
	s_waitcnt lgkmcnt(8)
	v_mfma_f32_16x16x32_bf16 v[0:3], v[80:83], v[64:67], v[0:3]
	v_mfma_f32_16x16x32_bf16 v[4:7], v[84:87], v[64:67], v[4:7]
	v_mfma_f32_16x16x32_bf16 v[8:11], v[88:91], v[64:67], v[8:11]
	v_mfma_f32_16x16x32_bf16 v[12:15], v[92:95], v[64:67], v[12:15]
	v_mfma_f32_16x16x32_bf16 v[16:19], v[80:83], v[68:71], v[16:19]
	v_mfma_f32_16x16x32_bf16 v[20:23], v[84:87], v[68:71], v[20:23]
	v_mfma_f32_16x16x32_bf16 v[24:27], v[88:91], v[68:71], v[24:27]
	v_mfma_f32_16x16x32_bf16 v[28:31], v[92:95], v[68:71], v[28:31]
	v_mfma_f32_16x16x32_bf16 v[32:35], v[80:83], v[72:75], v[32:35]
	v_mfma_f32_16x16x32_bf16 v[36:39], v[84:87], v[72:75], v[36:39]
	v_mfma_f32_16x16x32_bf16 v[40:43], v[88:91], v[72:75], v[40:43]
	v_mfma_f32_16x16x32_bf16 v[44:47], v[92:95], v[72:75], v[44:47]
	v_mfma_f32_16x16x32_bf16 v[48:51], v[80:83], v[76:79], v[48:51]
	v_mfma_f32_16x16x32_bf16 v[52:55], v[84:87], v[76:79], v[52:55]
	v_mfma_f32_16x16x32_bf16 v[56:59], v[88:91], v[76:79], v[56:59]
	v_mfma_f32_16x16x32_bf16 v[60:63], v[92:95], v[76:79], v[60:63]
	s_waitcnt vmcnt(0) lgkmcnt(0)
	s_barrier
	ds_read_b128 v[64:67], v168 offset:0
	ds_read_b128 v[68:71], v168 offset:2048
	ds_read_b128 v[72:75], v168 offset:4096
	ds_read_b128 v[76:79], v168 offset:6144
	ds_read_b128 v[80:83], v169 offset:0
	ds_read_b128 v[84:87], v169 offset:2048
	ds_read_b128 v[88:91], v169 offset:4096
	ds_read_b128 v[92:95], v169 offset:6144
	s_add_i32 s5, s1, 3
	s_min_u32 s5, s5, 15
	s_lshl_b32 s18, s5, 7
	s_mul_i32 s6, s5, 0xc0
	s_mov_b32 s7, s19
	s_add_u32 m0, s101, 0x8000
	v_lshl_add_u64 v[210:211], v[152:153], 0, s[6:7]
	global_load_lds_dwordx4 v[210:211], off
	s_add_u32 m0, s101, 0xc000
	v_lshl_add_u64 v[210:211], v[154:155], 0, s[18:19]
	global_load_lds_dwordx4 v[210:211], off
	ds_read_b128 v[96:99], v220 offset:0
	ds_read_b128 v[100:103], v220 offset:2048
	ds_read_b128 v[104:107], v220 offset:4096
	ds_read_b128 v[108:111], v220 offset:6144
	ds_read_b128 v[112:115], v221 offset:0
	ds_read_b128 v[116:119], v221 offset:2048
	ds_read_b128 v[120:123], v221 offset:4096
	ds_read_b128 v[124:127], v221 offset:6144
	v_mfma_f32_16x16x32_bf16 v[0:3], v[192:195], v[128:131], v[0:3]
	v_mfma_f32_16x16x32_bf16 v[4:7], v[196:199], v[128:131], v[4:7]
	s_add_u32 m0, s101, 0x9000
	v_lshl_add_u64 v[210:211], v[156:157], 0, s[6:7]
	global_load_lds_dwordx4 v[210:211], off
	v_mfma_f32_16x16x32_bf16 v[8:11], v[200:203], v[128:131], v[8:11]
	v_mfma_f32_16x16x32_bf16 v[12:15], v[204:207], v[128:131], v[12:15]
	s_add_u32 m0, s101, 0xd000
	v_lshl_add_u64 v[210:211], v[158:159], 0, s[18:19]
	global_load_lds_dwordx4 v[210:211], off
	v_mfma_f32_16x16x32_bf16 v[16:19], v[192:195], v[132:135], v[16:19]
	v_mfma_f32_16x16x32_bf16 v[20:23], v[196:199], v[132:135], v[20:23]
	s_add_u32 m0, s101, 0xa000
	v_lshl_add_u64 v[210:211], v[160:161], 0, s[6:7]
	global_load_lds_dwordx4 v[210:211], off
	v_mfma_f32_16x16x32_bf16 v[24:27], v[200:203], v[132:135], v[24:27]
	v_mfma_f32_16x16x32_bf16 v[28:31], v[204:207], v[132:135], v[28:31]
	s_add_u32 m0, s101, 0xe000
	v_lshl_add_u64 v[210:211], v[162:163], 0, s[18:19]
	global_load_lds_dwordx4 v[210:211], off
	v_mfma_f32_16x16x32_bf16 v[32:35], v[192:195], v[136:139], v[32:35]
	v_mfma_f32_16x16x32_bf16 v[36:39], v[196:199], v[136:139], v[36:39]
	s_add_u32 m0, s101, 0xb000
	v_lshl_add_u64 v[210:211], v[164:165], 0, s[6:7]
	global_load_lds_dwordx4 v[210:211], off
	v_mfma_f32_16x16x32_bf16 v[40:43], v[200:203], v[136:139], v[40:43]
	v_mfma_f32_16x16x32_bf16 v[44:47], v[204:207], v[136:139], v[44:47]
	s_add_u32 m0, s101, 0xf000
	v_lshl_add_u64 v[210:211], v[166:167], 0, s[18:19]
	global_load_lds_dwordx4 v[210:211], off
	v_mfma_f32_16x16x32_bf16 v[48:51], v[192:195], v[140:143], v[48:51]
	v_mfma_f32_16x16x32_bf16 v[52:55], v[196:199], v[140:143], v[52:55]
	v_mfma_f32_16x16x32_bf16 v[56:59], v[200:203], v[140:143], v[56:59]
	v_mfma_f32_16x16x32_bf16 v[60:63], v[204:207], v[140:143], v[60:63]
	s_waitcnt lgkmcnt(8)
; #define SB_ __builtin_amdgcn_sched_barrier(0)
; template <bool SWAP, bool HALF>
; DI void gemm_mainloop(const GemmDesc& d, int m0, int n0, bf16_t* smem, f32x16 (&acc)[2][2], int dry) {
;     ...
;   auto stage = [&](int cur, u32x4 (&ran)[4], u32x4 (&rbn)[4], int ks) {
;     ldf(cur, 1, 1); SB_;
;     mma(0); SB_;
;     ldf(cur, 2, 0); SB_;
;     lw(ran, rbn, cur ^ 1);
;     gl(ran, rbn, (ks + 3 < nk) ? ks + 3 : nk - 1);
;     SB_;
;     mma(1); SB_;
;     __syncthreads();
;     ldf(cur, 3, 1); SB_;
;     mma(0); SB_;
;     ldf(cur ^ 1, 0, 0);
;     SB_;
;     mma(1); SB_;
;     __syncthreads();
;   };
;   gl(ra0, rb0, 0);
;   gl(ra1, rb1, 1);
;   lw(ra0, rb0, 0);
;   gl(ra0, rb0, 2);
;   __syncthreads();
;   ldf(0, 0, 0);
; #pragma unroll 1
;   for (int ks = 0; ks < nk; ks += 2) {
;     stage(0, ra1, rb1, ks);
;     stage(1, ra0, rb0, ks + 1);
;   }
	v_mfma_f32_16x16x32_bf16 v[0:3], v[80:83], v[64:67], v[0:3]
	v_mfma_f32_16x16x32_bf16 v[4:7], v[84:87], v[64:67], v[4:7]
	v_mfma_f32_16x16x32_bf16 v[8:11], v[88:91], v[64:67], v[8:11]
	v_mfma_f32_16x16x32_bf16 v[12:15], v[92:95], v[64:67], v[12:15]
	v_mfma_f32_16x16x32_bf16 v[16:19], v[80:83], v[68:71], v[16:19]
	v_mfma_f32_16x16x32_bf16 v[20:23], v[84:87], v[68:71], v[20:23]
	v_mfma_f32_16x16x32_bf16 v[24:27], v[88:91], v[68:71], v[24:27]
	v_mfma_f32_16x16x32_bf16 v[28:31], v[92:95], v[68:71], v[28:31]
	v_mfma_f32_16x16x32_bf16 v[32:35], v[80:83], v[72:75], v[32:35]
	v_mfma_f32_16x16x32_bf16 v[36:39], v[84:87], v[72:75], v[36:39]
	v_mfma_f32_16x16x32_bf16 v[40:43], v[88:91], v[72:75], v[40:43]
	v_mfma_f32_16x16x32_bf16 v[44:47], v[92:95], v[72:75], v[44:47]
	v_mfma_f32_16x16x32_bf16 v[48:51], v[80:83], v[76:79], v[48:51]
	v_mfma_f32_16x16x32_bf16 v[52:55], v[84:87], v[76:79], v[52:55]
	v_mfma_f32_16x16x32_bf16 v[56:59], v[88:91], v[76:79], v[56:59]
	v_mfma_f32_16x16x32_bf16 v[60:63], v[92:95], v[76:79], v[60:63]
	s_cmp_lt_u32 s1, 12
	s_waitcnt vmcnt(0) lgkmcnt(0)
	s_barrier
	s_cbranch_scc1 .LBB0_920
	ds_read_b128 v[64:67], v168 offset:32768
	ds_read_b128 v[68:71], v168 offset:34816
	ds_read_b128 v[72:75], v168 offset:36864
	ds_read_b128 v[76:79], v168 offset:38912
	ds_read_b128 v[80:83], v169 offset:32768
	ds_read_b128 v[84:87], v169 offset:34816
	ds_read_b128 v[88:91], v169 offset:36864
	ds_read_b128 v[92:95], v169 offset:38912
	ds_read_b128 v[128:131], v220 offset:32768
	ds_read_b128 v[132:135], v220 offset:34816
	ds_read_b128 v[136:139], v220 offset:36864
	ds_read_b128 v[140:143], v220 offset:38912
	ds_read_b128 v[192:195], v221 offset:32768
	ds_read_b128 v[196:199], v221 offset:34816
	ds_read_b128 v[200:203], v221 offset:36864
	ds_read_b128 v[204:207], v221 offset:38912
	v_mfma_f32_16x16x32_bf16 v[0:3], v[112:115], v[96:99], v[0:3]
	v_mfma_f32_16x16x32_bf16 v[4:7], v[116:119], v[96:99], v[4:7]
	v_mfma_f32_16x16x32_bf16 v[8:11], v[120:123], v[96:99], v[8:11]
	v_mfma_f32_16x16x32_bf16 v[12:15], v[124:127], v[96:99], v[12:15]
	v_mfma_f32_16x16x32_bf16 v[16:19], v[112:115], v[100:103], v[16:19]
	v_mfma_f32_16x16x32_bf16 v[20:23], v[116:119], v[100:103], v[20:23]
	v_mfma_f32_16x16x32_bf16 v[24:27], v[120:123], v[100:103], v[24:27]
	v_mfma_f32_16x16x32_bf16 v[28:31], v[124:127], v[100:103], v[28:31]
	v_mfma_f32_16x16x32_bf16 v[32:35], v[112:115], v[104:107], v[32:35]
	v_mfma_f32_16x16x32_bf16 v[36:39], v[116:119], v[104:107], v[36:39]
	v_mfma_f32_16x16x32_bf16 v[40:43], v[120:123], v[104:107], v[40:43]
	v_mfma_f32_16x16x32_bf16 v[44:47], v[124:127], v[104:107], v[44:47]
	v_mfma_f32_16x16x32_bf16 v[48:51], v[112:115], v[108:111], v[48:51]
	v_mfma_f32_16x16x32_bf16 v[52:55], v[116:119], v[108:111], v[52:55]
	v_mfma_f32_16x16x32_bf16 v[56:59], v[120:123], v[108:111], v[56:59]
	v_mfma_f32_16x16x32_bf16 v[60:63], v[124:127], v[108:111], v[60:63]
	s_waitcnt lgkmcnt(8)
	v_mfma_f32_16x16x32_bf16 v[0:3], v[80:83], v[64:67], v[0:3]
	v_mfma_f32_16x16x32_bf16 v[4:7], v[84:87], v[64:67], v[4:7]
	v_mfma_f32_16x16x32_bf16 v[8:11], v[88:91], v[64:67], v[8:11]
	v_mfma_f32_16x16x32_bf16 v[12:15], v[92:95], v[64:67], v[12:15]
	v_mfma_f32_16x16x32_bf16 v[16:19], v[80:83], v[68:71], v[16:19]
	v_mfma_f32_16x16x32_bf16 v[20:23], v[84:87], v[68:71], v[20:23]
	v_mfma_f32_16x16x32_bf16 v[24:27], v[88:91], v[68:71], v[24:27]
	v_mfma_f32_16x16x32_bf16 v[28:31], v[92:95], v[68:71], v[28:31]
	v_mfma_f32_16x16x32_bf16 v[32:35], v[80:83], v[72:75], v[32:35]
	v_mfma_f32_16x16x32_bf16 v[36:39], v[84:87], v[72:75], v[36:39]
	v_mfma_f32_16x16x32_bf16 v[40:43], v[88:91], v[72:75], v[40:43]
	v_mfma_f32_16x16x32_bf16 v[44:47], v[92:95], v[72:75], v[44:47]
	v_mfma_f32_16x16x32_bf16 v[48:51], v[80:83], v[76:79], v[48:51]
	v_mfma_f32_16x16x32_bf16 v[52:55], v[84:87], v[76:79], v[52:55]
	v_mfma_f32_16x16x32_bf16 v[56:59], v[88:91], v[76:79], v[56:59]
	v_mfma_f32_16x16x32_bf16 v[60:63], v[92:95], v[76:79], v[60:63]
	s_waitcnt lgkmcnt(0)
	s_barrier
	v_mfma_f32_16x16x32_bf16 v[0:3], v[192:195], v[128:131], v[0:3]
	v_mfma_f32_16x16x32_bf16 v[4:7], v[196:199], v[128:131], v[4:7]
	v_mfma_f32_16x16x32_bf16 v[8:11], v[200:203], v[128:131], v[8:11]
	v_mfma_f32_16x16x32_bf16 v[12:15], v[204:207], v[128:131], v[12:15]
	v_mfma_f32_16x16x32_bf16 v[16:19], v[192:195], v[132:135], v[16:19]
	v_mfma_f32_16x16x32_bf16 v[20:23], v[196:199], v[132:135], v[20:23]
	v_mfma_f32_16x16x32_bf16 v[24:27], v[200:203], v[132:135], v[24:27]
	v_mfma_f32_16x16x32_bf16 v[28:31], v[204:207], v[132:135], v[28:31]
	v_mfma_f32_16x16x32_bf16 v[32:35], v[192:195], v[136:139], v[32:35]
	v_mfma_f32_16x16x32_bf16 v[36:39], v[196:199], v[136:139], v[36:39]
	v_mfma_f32_16x16x32_bf16 v[40:43], v[200:203], v[136:139], v[40:43]
	v_mfma_f32_16x16x32_bf16 v[44:47], v[204:207], v[136:139], v[44:47]
	v_mfma_f32_16x16x32_bf16 v[48:51], v[192:195], v[140:143], v[48:51]
	v_mfma_f32_16x16x32_bf16 v[52:55], v[196:199], v[140:143], v[52:55]
	v_mfma_f32_16x16x32_bf16 v[56:59], v[200:203], v[140:143], v[56:59]
	v_mfma_f32_16x16x32_bf16 v[60:63], v[204:207], v[140:143], v[60:63]
	s_waitcnt vmcnt(7)
; DI float ssq_f(u64 v) { return (float)v * (1.f / 1048576.f); }
; DI void gemm_tile(const GemmDesc& d, int m0, int n0, bf16_t* smem, int dry) {
;     ...
;   if (d.epi == EPI_RESID) {
; #pragma unroll
;     for (int pass = 0; pass < 16; ++pass) {
;       int m = m0 + pass * 8 + (t >> 5); m = m < M ? m : M - 1;
;       hpre[pass] = *(const u32x2*)(d.hb + (size_t)m * D + d.c_off + n0 + (t & 31) * 4);
;     }
;   } else if (t < 128) {
;     rs_s[t] = rsqrtf(ssq_f(myss) * d.inv_dim + EPS);
;   }
;   if (half) {
; #pragma unroll
;     for (int a = 0; a < 2; ++a)
; #pragma unroll
;       for (int g = 0; g < 4; ++g) {
;         f32x4 o;
; #pragma unroll
;         for (int j = 0; j < 4; ++j) o[j] = acc[a][0][4 * g + j];
;         *(f32x4*)(Ct + (a * 32 + r) * CS + w * 32 + 8 * g + 4 * hh) = o;
;       }
;   } else {
; #pragma unroll
;     for (int a = 0; a < 2; ++a)
; #pragma unroll
;       for (int b = 0; b < 2; ++b)
; #pragma unroll
;         for (int g = 0; g < 4; ++g) {
;           f32x4 o;
; #pragma unroll
;           for (int j = 0; j < 4; ++j) o[j] = acc[a][b][4 * g + j];
;           *(f32x4*)(Ct + (wm * 64 + a * 32 + r) * CS + wn * 64 + b * 32 + 8 * g + 4 * hh) = o;
;         }
;   }
;   __syncthreads();
;   if (d.epi == EPI_RESID) {
; #pragma unroll
;     for (int pass = 0; pass < 16; ++pass) {
;       const int row = pass * 8 + (t >> 5), c4 = t & 31, m = m0 + row;
;       float part = 0.f;
;       if (m < M) {
;         const f32x4 v = *(const f32x4*)(Ct + row * CS + c4 * 4);
;         const int n = d.c_off + n0 + c4 * 4;
;         f32x4 hv;
;         hv[0] = __uint_as_float(hpre[pass][0] << 16); hv[1] = __uint_as_float(hpre[pass][0] & 0xffff0000u);
;         hv[2] = __uint_as_float(hpre[pass][1] << 16); hv[3] = __uint_as_float(hpre[pass][1] & 0xffff0000u);
; #pragma unroll
;         for (int j = 0; j < 4; ++j) { hv[j] += v[j]; part += hv[j] * hv[j]; }
;         u32x2 o; o[0] = pk_bf16(hv[0], hv[1]); o[1] = pk_bf16(hv[2], hv[3]);
;         *(u32x2*)(d.hb + (size_t)m * D + n) = o;
	v_ashrrev_i32_e32 v98, 5, v150
	v_add_u32_e32 v92, s9, v98
	s_ashr_i32 s5, s4, 31
	s_lshl_b64 s[6:7], s[4:5], 1
	v_add_u32_e32 v70, 16, v92
	v_add_u32_e32 v72, 24, v92
	s_add_u32 s6, s56, s6
	v_lshlrev_b32_e32 v64, 3, v150
	v_min_i32_e32 v66, 0x803f, v92
	v_add_u32_e32 v68, 8, v92
	v_min_i32_e32 v70, 0x803f, v70
	v_min_i32_e32 v72, 0x803f, v72
	s_addc_u32 s7, s57, s7
	v_and_b32_e32 v144, 0xf8, v64
	v_ashrrev_i32_e32 v67, 31, v66
	v_min_i32_e32 v68, 0x803f, v68
	v_ashrrev_i32_e32 v71, 31, v70
	v_ashrrev_i32_e32 v73, 31, v72
	v_lshl_add_u64 v[64:65], s[6:7], 0, v[144:145]
	v_lshlrev_b64 v[66:67], 11, v[66:67]
	v_ashrrev_i32_e32 v69, 31, v68
	v_lshlrev_b64 v[70:71], 11, v[70:71]
	v_lshlrev_b64 v[72:73], 11, v[72:73]
	v_lshl_add_u64 v[66:67], v[64:65], 0, v[66:67]
	v_lshlrev_b64 v[68:69], 11, v[68:69]
	v_lshl_add_u64 v[70:71], v[64:65], 0, v[70:71]
	v_lshl_add_u64 v[72:73], v[64:65], 0, v[72:73]
	v_lshl_add_u64 v[68:69], v[64:65], 0, v[68:69]
	global_load_dwordx2 v[96:97], v[66:67], off
	global_load_dwordx2 v[94:95], v[68:69], off
	global_load_dwordx2 v[90:91], v[70:71], off
	global_load_dwordx2 v[88:89], v[72:73], off
	v_add_u32_e32 v66, 32, v92
	v_add_u32_e32 v70, 48, v92
	v_add_u32_e32 v72, 56, v92
	v_min_i32_e32 v66, 0x803f, v66
	v_add_u32_e32 v68, 40, v92
	v_min_i32_e32 v70, 0x803f, v70
	v_min_i32_e32 v72, 0x803f, v72
	v_ashrrev_i32_e32 v67, 31, v66
	v_min_i32_e32 v68, 0x803f, v68
	v_ashrrev_i32_e32 v71, 31, v70
	v_ashrrev_i32_e32 v73, 31, v72
	v_lshlrev_b64 v[66:67], 11, v[66:67]
	v_ashrrev_i32_e32 v69, 31, v68
	v_lshlrev_b64 v[70:71], 11, v[70:71]
	v_lshlrev_b64 v[72:73], 11, v[72:73]
	v_lshl_add_u64 v[66:67], v[64:65], 0, v[66:67]
	v_lshlrev_b64 v[68:69], 11, v[68:69]
	v_lshl_add_u64 v[70:71], v[64:65], 0, v[70:71]
	v_lshl_add_u64 v[72:73], v[64:65], 0, v[72:73]
	v_lshl_add_u64 v[68:69], v[64:65], 0, v[68:69]
	global_load_dwordx2 v[86:87], v[66:67], off
	global_load_dwordx2 v[84:85], v[68:69], off
	global_load_dwordx2 v[82:83], v[70:71], off
	global_load_dwordx2 v[80:81], v[72:73], off
	v_add_u32_e32 v66, 64, v92
	v_add_u32_e32 v70, 0x50, v92
	v_add_u32_e32 v72, 0x58, v92
	v_min_i32_e32 v66, 0x803f, v66
	v_add_u32_e32 v68, 0x48, v92
	v_min_i32_e32 v70, 0x803f, v70
	v_min_i32_e32 v72, 0x803f, v72
	v_ashrrev_i32_e32 v67, 31, v66
	v_min_i32_e32 v68, 0x803f, v68
	v_ashrrev_i32_e32 v71, 31, v70
	v_ashrrev_i32_e32 v73, 31, v72
	v_lshlrev_b64 v[66:67], 11, v[66:67]
	v_ashrrev_i32_e32 v69, 31, v68
	v_lshlrev_b64 v[70:71], 11, v[70:71]
	v_lshlrev_b64 v[72:73], 11, v[72:73]
	v_lshl_add_u64 v[66:67], v[64:65], 0, v[66:67]
	v_lshlrev_b64 v[68:69], 11, v[68:69]
	v_lshl_add_u64 v[70:71], v[64:65], 0, v[70:71]
	v_lshl_add_u64 v[72:73], v[64:65], 0, v[72:73]
	v_lshl_add_u64 v[68:69], v[64:65], 0, v[68:69]
	global_load_dwordx2 v[78:79], v[66:67], off
	global_load_dwordx2 v[76:77], v[68:69], off
	global_load_dwordx2 v[74:75], v[70:71], off
	s_nop 0
	global_load_dwordx2 v[72:73], v[72:73], off
	v_add_u32_e32 v70, 0x70, v92
	v_min_i32_e32 v70, 0x803f, v70
	v_ashrrev_i32_e32 v71, 31, v70
	v_lshlrev_b64 v[70:71], 11, v[70:71]
	v_add_u32_e32 v66, 0x60, v92
	v_add_u32_e32 v68, 0x68, v92
	s_waitcnt vmcnt(18)
	v_lshl_add_u64 v[100:101], v[64:65], 0, v[70:71]
	v_add_u32_e32 v70, 0x78, v92
	v_min_i32_e32 v66, 0x803f, v66
	v_min_i32_e32 v68, 0x803f, v68
	v_min_i32_e32 v70, 0x803f, v70
	v_ashrrev_i32_e32 v67, 31, v66
	v_ashrrev_i32_e32 v69, 31, v68
	v_ashrrev_i32_e32 v71, 31, v70
	v_lshlrev_b64 v[66:67], 11, v[66:67]
	v_lshlrev_b64 v[68:69], 11, v[68:69]
	v_lshlrev_b64 v[70:71], 11, v[70:71]
	v_lshl_add_u64 v[66:67], v[64:65], 0, v[66:67]
	v_lshl_add_u64 v[68:69], v[64:65], 0, v[68:69]
	v_lshl_add_u64 v[64:65], v[64:65], 0, v[70:71]
	global_load_dwordx2 v[70:71], v[66:67], off
	s_nop 0
	global_load_dwordx2 v[68:69], v[68:69], off
	s_nop 0
	global_load_dwordx2 v[66:67], v[100:101], off
	s_nop 0
	global_load_dwordx2 v[64:65], v[64:65], off
	v_and_b32_e32 v99, 31, v150
	v_lshrrev_b32_e32 v100, 1, v150
	v_lshlrev_b32_e32 v93, 2, v150
	v_and_or_b32 v101, v100, s72, v99
	v_and_b32_e32 v100, 16, v100
	s_movk_i32 s1, 0x100
	v_and_or_b32 v100, v93, s1, v100
	v_mad_u64_u32 v[100:101], s[6:7], v101, s22, v[100:101]
	v_and_b32_e32 v212, 15, v172
	v_lshrrev_b32_e32 v213, 1, v172
	v_and_or_b32 v212, v213, s72, v212
	v_lshlrev_b32_e32 v213, 2, v172
	v_and_b32_e32 v214, 0x30, v172
	v_and_b32_e32 v213, 0x100, v213
	v_or_b32_e32 v213, v213, v214
	v_mad_u32_u24 v100, v212, s22, v213
	ds_write_b128 v100, v[0:3]
	ds_write_b128 v100, v[4:7] offset:64
	ds_write_b128 v100, v[8:11] offset:128
	ds_write_b128 v100, v[12:15] offset:192
	ds_write_b128 v100, v[16:19] offset:8448
	ds_write_b128 v100, v[20:23] offset:8512
	ds_write_b128 v100, v[24:27] offset:8576
	ds_write_b128 v100, v[28:31] offset:8640
	ds_write_b128 v100, v[32:35] offset:16896
	ds_write_b128 v100, v[36:39] offset:16960
	ds_write_b128 v100, v[40:43] offset:17024
	ds_write_b128 v100, v[44:47] offset:17088
	ds_write_b128 v100, v[48:51] offset:25344
	ds_write_b128 v100, v[52:55] offset:25408
	ds_write_b128 v100, v[56:59] offset:25472
	ds_write_b128 v100, v[60:63] offset:25536
	v_lshl_or_b32 v0, v99, 2, s4
	v_lshlrev_b32_e32 v2, 4, v99
	v_cmp_gt_i32_e64 s[4:5], s23, v92
	v_mov_b32_e32 v4, 0
	v_ashrrev_i32_e32 v93, 31, v92
	v_ashrrev_i32_e32 v1, 31, v0
	s_waitcnt lgkmcnt(0)
	s_barrier
	s_and_saveexec_b64 s[6:7], s[4:5]
	s_cbranch_execz .LBB0_923
	v_mad_u64_u32 v[4:5], s[10:11], v98, s22, v[2:3]
	ds_read_b128 v[4:7], v4
	s_waitcnt vmcnt(15)
	v_lshlrev_b32_e32 v8, 16, v96
	v_and_b32_e32 v9, 0xffff0000, v96
	v_and_b32_e32 v11, 0xffff0000, v97
	v_lshlrev_b32_e32 v10, 16, v97
	s_waitcnt lgkmcnt(0)
	v_pk_add_f32 v[8:9], v[4:5], v[8:9]
	v_pk_add_f32 v[6:7], v[6:7], v[10:11]
	v_pk_mul_f32 v[4:5], v[8:9], v[8:9]
	v_pk_mul_f32 v[10:11], v[6:7], v[6:7]
	v_add_f32_e32 v3, v4, v5
	v_cvt_pk_bf16_f32 v8, v8, v9
	v_cvt_pk_bf16_f32 v9, v6, v7
	v_lshlrev_b64 v[6:7], 11, v[92:93]
	v_add_f32_e32 v3, v10, v3
	v_lshl_add_u64 v[6:7], s[56:57], 0, v[6:7]
	v_add_f32_e32 v4, v11, v3
	v_lshl_add_u64 v[6:7], v[0:1], 1, v[6:7]
	global_store_dwordx2 v[6:7], v[8:9], off

; DI int otid() { int t = threadIdx.x; asm volatile("" : "+v"(t)); return t; }
; template <bool SWAP, bool HALF>
; DI void gemm_mainloop(const GemmDesc& d, int m0, int n0, bf16_t* smem, f32x16 (&acc)[2][2], int dry) {
;   const int t = otid(), lane = t & 63, w = t >> 6, wm = w >> 1, wn = w & 1, r = lane & 31, hh = lane >> 5;
;   const int lrow = t >> 3, lkc = t & 7;
;   const bf16_t* ap[4]; const bf16_t* bp[4];
; #pragma unroll
;   for (int i = 0; i < 4; ++i) {
;     int am = m0 + lrow + 32 * i; am = am < M ? am : M - 1;
;     ap[i] = d.A + (size_t)am * d.lda + lkc * 8 + (d.a_grp ? (n0 / d.a_grp) * d.a_grp : 0);
;     bp[i] = d.Bt + (size_t)(n0 + lrow + 32 * i) * d.ldb + lkc * 8;
;   }
; #pragma unroll
;   for (int a = 0; a < 2; ++a)
; #pragma unroll
;     for (int b = 0; b < 2; ++b)
; #pragma unroll
;       for (int i = 0; i < 16; ++i) acc[a][b][i] = 0.f;
;   u32x4 ra0[4], rb0[4], ra1[4], rb1[4];
;   const int nk = d.K >> 6;
;   const int lds_w = lrow * LST + lkc * 8;
; DI void gemm_tile(const GemmDesc& d, int m0, int n0, bf16_t* smem, int dry) {
;     ...
;   const bool vtile = (d.epi == EPI_STORE) && (n0 >= d.n1end) && (n0 < d.nvend);
;     ...
;   for (int i = slot; i < total; i += nslots) {
;     const int g = i / (8 * nN), j = i - g * 8 * nN;
;     const int gm = (cx - g * 8) < 8 ? (cx - g * 8) : 8;
;     const int mt = (g * 8 + j % gm) * 8 + x, nt = j / gm;
;     gemm_tile(d, mt * 128, nt * 128, smem, dry);
.LBB0_1002:
	s_or_b64 exec, exec, s[4:5]
	s_lshl_b32 s1, s14, 7
	s_and_b32 s4, s14, -8
	s_waitcnt vmcnt(0)
	v_ashrrev_i32_e32 v187, 7, v150
	v_bfe_u32 v188, v150, 6, 1
	v_and_b32_e32 v170, 31, v150
	v_bfe_u32 v189, v150, 5, 1
	s_cmp_lg_u32 s4, 16
	s_mov_b64 s[4:5], -1
	s_cbranch_scc0 .LBB0_1018
	v_mov_b32_e32 v32, v172
	v_readlane_b32 s76, v228, 60
	v_ashrrev_i32_e32 v10, 3, v32
	v_lshlrev_b32_e32 v0, 3, v32
	v_and_b32_e32 v33, 56, v0
	v_add_u32_e32 v2, s1, v10
	v_lshlrev_b32_e32 v144, 1, v33
	v_readlane_b32 s78, v228, 62
	v_readlane_b32 s79, v228, 63
	v_ashrrev_i32_e32 v3, 31, v2
	v_add_u32_e32 v11, s9, v10
	v_lshl_add_u64 v[4:5], s[78:79], 0, v[144:145]
	v_lshlrev_b64 v[2:3], 11, v[2:3]
	v_lshl_add_u64 v[154:155], v[4:5], 0, v[2:3]
	v_min_i32_e32 v2, 0x801f, v11
	v_ashrrev_i32_e32 v3, 31, v2
	v_lshl_add_u64 v[0:1], s[56:57], 0, v[144:145]
	v_lshlrev_b64 v[2:3], 11, v[2:3]
	v_lshl_add_u64 v[8:9], v[0:1], 0, v[2:3]
	v_min_i32_e32 v2, 0x7fff, v11
	v_ashrrev_i32_e32 v3, 31, v2
	v_min_i32_e32 v6, 0x803f, v11
	v_lshlrev_b64 v[2:3], 11, v[2:3]
	v_ashrrev_i32_e32 v7, 31, v6
	v_lshl_add_u64 v[16:17], v[0:1], 0, v[2:3]
	v_min_i32_e32 v2, 0x7fdf, v11
	v_lshlrev_b64 v[6:7], 11, v[6:7]
	v_ashrrev_i32_e32 v3, 31, v2
	v_lshl_add_u64 v[152:153], v[0:1], 0, v[6:7]
	v_lshlrev_b64 v[2:3], 11, v[2:3]
	v_lshl_add_u64 v[24:25], v[0:1], 0, v[2:3]
	s_mov_b64 s[4:5], 0x10000
	v_lshl_add_u64 v[156:157], v[8:9], 0, s[4:5]
	v_lshl_add_u64 v[158:159], v[154:155], 0, s[4:5]
	s_mov_b64 s[4:5], 0x20000
	v_lshl_add_u64 v[160:161], v[16:17], 0, s[4:5]
	v_lshl_add_u64 v[162:163], v[154:155], 0, s[4:5]
	s_mov_b64 s[4:5], 0x30000
	v_lshl_add_u64 v[164:165], v[24:25], 0, s[4:5]
	v_lshl_add_u64 v[166:167], v[154:155], 0, s[4:5]
	s_movk_i32 s4, 0x48
	v_and_b32_e32 v34, 31, v32
	v_mul_lo_u32 v35, v10, s4
	v_readlane_b32 s77, v228, 61
	v_readlane_b32 s80, v223, 0
	v_readlane_b32 s81, v223, 1
	v_readlane_b32 s82, v223, 2
	v_readlane_b32 s83, v223, 3
	v_readlane_b32 s84, v223, 4
	v_readlane_b32 s85, v223, 5
	v_readlane_b32 s86, v223, 6
	v_readlane_b32 s87, v223, 7
	v_readlane_b32 s88, v223, 8
	v_readlane_b32 s89, v223, 9
	v_readlane_b32 s90, v223, 10
	v_readlane_b32 s91, v223, 11
	s_mov_b32 s4, 0x10000
	v_add_co_u32_e32 v8, vcc, s4, v8
	s_nop 1
	v_addc_co_u32_e32 v9, vcc, 0, v9, vcc
	v_add_co_u32_e32 v12, vcc, s4, v154
	s_nop 1
	v_addc_co_u32_e32 v13, vcc, 0, v155, vcc
	s_mov_b32 s4, 0x20000
	v_add_co_u32_e32 v16, vcc, s4, v16
	s_nop 1
	v_addc_co_u32_e32 v17, vcc, 0, v17, vcc
	v_add_co_u32_e32 v20, vcc, s4, v154
	s_nop 1
	v_addc_co_u32_e32 v21, vcc, 0, v155, vcc
	s_mov_b32 s4, 0x30000
	v_add_co_u32_e32 v24, vcc, s4, v24
	s_nop 1
	v_addc_co_u32_e32 v25, vcc, 0, v25, vcc
	v_add_co_u32_e32 v28, vcc, s4, v154
	s_nop 1
	v_addc_co_u32_e32 v29, vcc, 0, v155, vcc
	s_nop 0
	v_add_lshl_u32 v144, v35, v33, 1
	s_waitcnt vmcnt(15)
	s_waitcnt vmcnt(14)
	s_waitcnt vmcnt(13)
	s_waitcnt vmcnt(12)
	s_waitcnt vmcnt(11)
	s_waitcnt vmcnt(10)
	s_waitcnt vmcnt(9)
	s_waitcnt vmcnt(8)
	v_lshrrev_b32_e32 v0, 1, v32
	v_and_or_b32 v1, v0, s72, v34
	v_and_b32_e32 v0, 16, v0
	s_movk_i32 s4, 0x90
	v_mad_u64_u32 v[168:169], s[4:5], v1, s4, v[0:1]
	v_and_b32_e32 v1, 0x5f, v32
	v_mul_u32_u24_e32 v1, 0x48, v1
	v_lshl_add_u32 v169, v1, 1, v0
	v_bfe_u32 v212, v172, 4, 3
	v_lshlrev_b32_e32 v212, 4, v212
	v_xor_b32_e32 v152, v152, v212
	v_xor_b32_e32 v154, v154, v212
	v_xor_b32_e32 v156, v156, v212
	v_xor_b32_e32 v158, v158, v212
	v_xor_b32_e32 v160, v160, v212
	v_xor_b32_e32 v162, v162, v212
	v_xor_b32_e32 v164, v164, v212
	v_xor_b32_e32 v166, v166, v212
	v_lshrrev_b32_e32 v213, 6, v172
	s_nop 1
	v_readfirstlane_b32 s101, v213
	s_lshl_b32 s101, s101, 10
	s_add_u32 m0, s101, 0x0
	s_nop 0
	global_load_lds_dwordx4 v[152:153], off
	s_add_u32 m0, s101, 0x4000
	s_nop 0
	global_load_lds_dwordx4 v[154:155], off
	s_add_u32 m0, s101, 0x1000
	s_nop 0
	global_load_lds_dwordx4 v[156:157], off
	s_add_u32 m0, s101, 0x5000
	s_nop 0
	global_load_lds_dwordx4 v[158:159], off
	s_add_u32 m0, s101, 0x2000
	s_nop 0
	global_load_lds_dwordx4 v[160:161], off
	s_add_u32 m0, s101, 0x6000
	s_nop 0
	global_load_lds_dwordx4 v[162:163], off
	s_add_u32 m0, s101, 0x3000
	s_nop 0
	global_load_lds_dwordx4 v[164:165], off
	s_add_u32 m0, s101, 0x7000
	s_nop 0
	global_load_lds_dwordx4 v[166:167], off
	v_and_b32_e32 v212, 15, v172
	v_bfe_u32 v213, v172, 4, 2
	v_lshrrev_b32_e32 v214, 1, v212
	v_xor_b32_e32 v213, v213, v214
	v_lshlrev_b32_e32 v213, 4, v213
	v_lshl_or_b32 v212, v212, 7, v213
	v_lshrrev_b32_e32 v214, 7, v172
	v_lshl_add_u32 v168, v214, 13, v212
	v_bfe_u32 v214, v172, 6, 1
	v_lshl_add_u32 v169, v214, 13, v212
	v_add_u32_e32 v169, 0x4000, v169
	v_xor_b32_e32 v220, 64, v168
	v_xor_b32_e32 v221, 64, v169
	s_waitcnt vmcnt(0) lgkmcnt(0)
	s_barrier
; #define SB_ __builtin_amdgcn_sched_barrier(0)
; template <bool SWAP, bool HALF>
; DI void gemm_mainloop(const GemmDesc& d, int m0, int n0, bf16_t* smem, f32x16 (&acc)[2][2], int dry) {
;     ...
;   for (int a = 0; a < 2; ++a)
; #pragma unroll
;     for (int b = 0; b < 2; ++b)
; #pragma unroll
;       for (int i = 0; i < 16; ++i) acc[a][b][i] = 0.f;
;     ...
;   auto stage = [&](int cur, u32x4 (&ran)[4], u32x4 (&rbn)[4], int ks) {
;     ldf(cur, 1, 1); SB_;
;     mma(0); SB_;
;     ldf(cur, 2, 0); SB_;
;     lw(ran, rbn, cur ^ 1);
;     gl(ran, rbn, (ks + 3 < nk) ? ks + 3 : nk - 1);
;     SB_;
;     mma(1); SB_;
;     __syncthreads();
;     ldf(cur, 3, 1); SB_;
;     mma(0); SB_;
;     ldf(cur ^ 1, 0, 0);
;     SB_;
;     mma(1); SB_;
;     __syncthreads();
;   };
;   gl(ra0, rb0, 0);
;   gl(ra1, rb1, 1);
;   lw(ra0, rb0, 0);
;   gl(ra0, rb0, 2);
;   __syncthreads();
;   ldf(0, 0, 0);
; #pragma unroll 1
;   for (int ks = 0; ks < nk; ks += 2) {
;     stage(0, ra1, rb1, ks);
	v_mov_b32_e32 v0, 0
	v_add_u32_e32 v190, 0x9000, v144
	s_mov_b32 s4, -2
	v_mov_b32_e32 v1, v0
	v_mov_b32_e32 v2, v0
	v_mov_b32_e32 v3, v0
	v_mov_b32_e32 v4, v0
	v_mov_b32_e32 v5, v0
	v_mov_b32_e32 v6, v0
	v_mov_b32_e32 v7, v0
	v_mov_b32_e32 v8, v0
	v_mov_b32_e32 v9, v0
	v_mov_b32_e32 v10, v0
	v_mov_b32_e32 v11, v0
	v_mov_b32_e32 v12, v0
	v_mov_b32_e32 v13, v0
	v_mov_b32_e32 v14, v0
	v_mov_b32_e32 v15, v0
	v_mov_b32_e32 v16, v0
	v_mov_b32_e32 v17, v0
	v_mov_b32_e32 v18, v0
	v_mov_b32_e32 v19, v0
	v_mov_b32_e32 v20, v0
	v_mov_b32_e32 v21, v0
	v_mov_b32_e32 v22, v0
	v_mov_b32_e32 v23, v0
	v_mov_b32_e32 v24, v0
	v_mov_b32_e32 v25, v0
	v_mov_b32_e32 v26, v0
	v_mov_b32_e32 v27, v0
	v_mov_b32_e32 v28, v0
	v_mov_b32_e32 v29, v0
	v_mov_b32_e32 v30, v0
	v_mov_b32_e32 v31, v0
	v_mov_b32_e32 v32, v0
	v_mov_b32_e32 v33, v0
	v_mov_b32_e32 v34, v0
	v_mov_b32_e32 v35, v0
	v_mov_b32_e32 v36, v0
	v_mov_b32_e32 v37, v0
	v_mov_b32_e32 v38, v0
	v_mov_b32_e32 v39, v0
	v_mov_b32_e32 v40, v0
	v_mov_b32_e32 v41, v0
	v_mov_b32_e32 v42, v0
	v_mov_b32_e32 v43, v0
	v_mov_b32_e32 v44, v0
	v_mov_b32_e32 v45, v0
	v_mov_b32_e32 v46, v0
	v_mov_b32_e32 v47, v0
	v_mov_b32_e32 v48, v0
	v_mov_b32_e32 v49, v0
	v_mov_b32_e32 v50, v0
	v_mov_b32_e32 v51, v0
	v_mov_b32_e32 v52, v0
	v_mov_b32_e32 v53, v0
	v_mov_b32_e32 v54, v0
	v_mov_b32_e32 v55, v0
	v_mov_b32_e32 v56, v0
	v_mov_b32_e32 v57, v0
	v_mov_b32_e32 v58, v0
	v_mov_b32_e32 v59, v0
	v_mov_b32_e32 v60, v0
	v_mov_b32_e32 v61, v0
	v_mov_b32_e32 v62, v0
	v_mov_b32_e32 v63, v0
	ds_read_b128 v[64:67], v168 offset:0
	ds_read_b128 v[68:71], v168 offset:2048
	ds_read_b128 v[72:75], v168 offset:4096
	ds_read_b128 v[76:79], v168 offset:6144
	ds_read_b128 v[80:83], v169 offset:0
	ds_read_b128 v[84:87], v169 offset:2048
	ds_read_b128 v[88:91], v169 offset:4096
	ds_read_b128 v[92:95], v169 offset:6144
	s_add_i32 s5, s4, 3
	s_min_u32 s5, s5, 15
	s_lshl_b32 s18, s5, 7
	s_add_u32 m0, s101, 0x8000
	v_lshl_add_u64 v[210:211], v[152:153], 0, s[18:19]
	global_load_lds_dwordx4 v[210:211], off
	s_add_u32 m0, s101, 0xc000
	v_lshl_add_u64 v[210:211], v[154:155], 0, s[18:19]
	global_load_lds_dwordx4 v[210:211], off
	ds_read_b128 v[96:99], v220 offset:0
	ds_read_b128 v[100:103], v220 offset:2048
	ds_read_b128 v[104:107], v220 offset:4096
	ds_read_b128 v[108:111], v220 offset:6144
	ds_read_b128 v[112:115], v221 offset:0
	ds_read_b128 v[116:119], v221 offset:2048
	ds_read_b128 v[120:123], v221 offset:4096
	ds_read_b128 v[124:127], v221 offset:6144
	s_waitcnt lgkmcnt(8)
	v_mfma_f32_16x16x32_bf16 v[0:3], v[80:83], v[64:67], v[0:3]
	v_mfma_f32_16x16x32_bf16 v[4:7], v[84:87], v[64:67], v[4:7]
	s_add_u32 m0, s101, 0x9000
	v_lshl_add_u64 v[210:211], v[156:157], 0, s[18:19]
	global_load_lds_dwordx4 v[210:211], off
	v_mfma_f32_16x16x32_bf16 v[8:11], v[88:91], v[64:67], v[8:11]
	v_mfma_f32_16x16x32_bf16 v[12:15], v[92:95], v[64:67], v[12:15]
	s_add_u32 m0, s101, 0xd000
	v_lshl_add_u64 v[210:211], v[158:159], 0, s[18:19]
	global_load_lds_dwordx4 v[210:211], off
	v_mfma_f32_16x16x32_bf16 v[16:19], v[80:83], v[68:71], v[16:19]
	v_mfma_f32_16x16x32_bf16 v[20:23], v[84:87], v[68:71], v[20:23]
	s_add_u32 m0, s101, 0xa000
	v_lshl_add_u64 v[210:211], v[160:161], 0, s[18:19]
	global_load_lds_dwordx4 v[210:211], off
	v_mfma_f32_16x16x32_bf16 v[24:27], v[88:91], v[68:71], v[24:27]
	v_mfma_f32_16x16x32_bf16 v[28:31], v[92:95], v[68:71], v[28:31]
	s_add_u32 m0, s101, 0xe000
	v_lshl_add_u64 v[210:211], v[162:163], 0, s[18:19]
	global_load_lds_dwordx4 v[210:211], off
	v_mfma_f32_16x16x32_bf16 v[32:35], v[80:83], v[72:75], v[32:35]
	v_mfma_f32_16x16x32_bf16 v[36:39], v[84:87], v[72:75], v[36:39]
	s_add_u32 m0, s101, 0xb000
	v_lshl_add_u64 v[210:211], v[164:165], 0, s[18:19]
	global_load_lds_dwordx4 v[210:211], off
	v_mfma_f32_16x16x32_bf16 v[40:43], v[88:91], v[72:75], v[40:43]
	v_mfma_f32_16x16x32_bf16 v[44:47], v[92:95], v[72:75], v[44:47]
	s_add_u32 m0, s101, 0xf000
	v_lshl_add_u64 v[210:211], v[166:167], 0, s[18:19]
	global_load_lds_dwordx4 v[210:211], off
	v_mfma_f32_16x16x32_bf16 v[48:51], v[80:83], v[76:79], v[48:51]
	v_mfma_f32_16x16x32_bf16 v[52:55], v[84:87], v[76:79], v[52:55]
	v_mfma_f32_16x16x32_bf16 v[56:59], v[88:91], v[76:79], v[56:59]
	v_mfma_f32_16x16x32_bf16 v[60:63], v[92:95], v[76:79], v[60:63]
	s_waitcnt vmcnt(0) lgkmcnt(0)
	s_barrier
; #define SB_ __builtin_amdgcn_sched_barrier(0)
; template <bool SWAP, bool HALF>
; DI void gemm_mainloop(const GemmDesc& d, int m0, int n0, bf16_t* smem, f32x16 (&acc)[2][2], int dry) {
;     ...
;   auto stage = [&](int cur, u32x4 (&ran)[4], u32x4 (&rbn)[4], int ks) {
;     ldf(cur, 1, 1); SB_;
;     mma(0); SB_;
;     ldf(cur, 2, 0); SB_;
;     lw(ran, rbn, cur ^ 1);
;     gl(ran, rbn, (ks + 3 < nk) ? ks + 3 : nk - 1);
;     SB_;
;     mma(1); SB_;
;     __syncthreads();
;     ldf(cur, 3, 1); SB_;
;     mma(0); SB_;
;     ldf(cur ^ 1, 0, 0);
;     SB_;
;     mma(1); SB_;
;     __syncthreads();
;   };
;   gl(ra0, rb0, 0);
;   gl(ra1, rb1, 1);
;   lw(ra0, rb0, 0);
;   gl(ra0, rb0, 2);
;   __syncthreads();
;   ldf(0, 0, 0);
; #pragma unroll 1
;   for (int ks = 0; ks < nk; ks += 2) {
;     stage(0, ra1, rb1, ks);
;     stage(1, ra0, rb0, ks + 1);
;   }
.LBB0_1004:
	ds_read_b128 v[64:67], v168 offset:32768
	ds_read_b128 v[68:71], v168 offset:34816
	ds_read_b128 v[72:75], v168 offset:36864
	ds_read_b128 v[76:79], v168 offset:38912
	ds_read_b128 v[80:83], v169 offset:32768
	ds_read_b128 v[84:87], v169 offset:34816
	ds_read_b128 v[88:91], v169 offset:36864
	ds_read_b128 v[92:95], v169 offset:38912
	s_add_i32 s4, s4, 2
	s_add_i32 s5, s4, 2
	s_min_u32 s5, s5, 15
	s_lshl_b32 s18, s5, 7
	s_add_u32 m0, s101, 0x0
	v_lshl_add_u64 v[210:211], v[152:153], 0, s[18:19]
	global_load_lds_dwordx4 v[210:211], off
	s_add_u32 m0, s101, 0x4000
	v_lshl_add_u64 v[210:211], v[154:155], 0, s[18:19]
	global_load_lds_dwordx4 v[210:211], off
	ds_read_b128 v[128:131], v220 offset:32768
	ds_read_b128 v[132:135], v220 offset:34816
	ds_read_b128 v[136:139], v220 offset:36864
	ds_read_b128 v[140:143], v220 offset:38912
	ds_read_b128 v[192:195], v221 offset:32768
	ds_read_b128 v[196:199], v221 offset:34816
	ds_read_b128 v[200:203], v221 offset:36864
	ds_read_b128 v[204:207], v221 offset:38912
	v_mfma_f32_16x16x32_bf16 v[0:3], v[112:115], v[96:99], v[0:3]
	v_mfma_f32_16x16x32_bf16 v[4:7], v[116:119], v[96:99], v[4:7]
	s_add_u32 m0, s101, 0x1000
	v_lshl_add_u64 v[210:211], v[156:157], 0, s[18:19]
	global_load_lds_dwordx4 v[210:211], off
	v_mfma_f32_16x16x32_bf16 v[8:11], v[120:123], v[96:99], v[8:11]
	v_mfma_f32_16x16x32_bf16 v[12:15], v[124:127], v[96:99], v[12:15]
	s_add_u32 m0, s101, 0x5000
	v_lshl_add_u64 v[210:211], v[158:159], 0, s[18:19]
	global_load_lds_dwordx4 v[210:211], off
	v_mfma_f32_16x16x32_bf16 v[16:19], v[112:115], v[100:103], v[16:19]
	v_mfma_f32_16x16x32_bf16 v[20:23], v[116:119], v[100:103], v[20:23]
	s_add_u32 m0, s101, 0x2000
	v_lshl_add_u64 v[210:211], v[160:161], 0, s[18:19]
	global_load_lds_dwordx4 v[210:211], off
	v_mfma_f32_16x16x32_bf16 v[24:27], v[120:123], v[100:103], v[24:27]
	v_mfma_f32_16x16x32_bf16 v[28:31], v[124:127], v[100:103], v[28:31]
	s_add_u32 m0, s101, 0x6000
	v_lshl_add_u64 v[210:211], v[162:163], 0, s[18:19]
	global_load_lds_dwordx4 v[210:211], off
	v_mfma_f32_16x16x32_bf16 v[32:35], v[112:115], v[104:107], v[32:35]
	v_mfma_f32_16x16x32_bf16 v[36:39], v[116:119], v[104:107], v[36:39]
	s_add_u32 m0, s101, 0x3000
	v_lshl_add_u64 v[210:211], v[164:165], 0, s[18:19]
	global_load_lds_dwordx4 v[210:211], off
	v_mfma_f32_16x16x32_bf16 v[40:43], v[120:123], v[104:107], v[40:43]
	v_mfma_f32_16x16x32_bf16 v[44:47], v[124:127], v[104:107], v[44:47]
	s_add_u32 m0, s101, 0x7000
	v_lshl_add_u64 v[210:211], v[166:167], 0, s[18:19]
	global_load_lds_dwordx4 v[210:211], off
	v_mfma_f32_16x16x32_bf16 v[48:51], v[112:115], v[108:111], v[48:51]
	v_mfma_f32_16x16x32_bf16 v[52:55], v[116:119], v[108:111], v[52:55]
	v_mfma_f32_16x16x32_bf16 v[56:59], v[120:123], v[108:111], v[56:59]
	v_mfma_f32_16x16x32_bf16 v[60:63], v[124:127], v[108:111], v[60:63]
	s_waitcnt lgkmcnt(8)
	v_mfma_f32_16x16x32_bf16 v[0:3], v[80:83], v[64:67], v[0:3]
	v_mfma_f32_16x16x32_bf16 v[4:7], v[84:87], v[64:67], v[4:7]
	v_mfma_f32_16x16x32_bf16 v[8:11], v[88:91], v[64:67], v[8:11]
	v_mfma_f32_16x16x32_bf16 v[12:15], v[92:95], v[64:67], v[12:15]
	v_mfma_f32_16x16x32_bf16 v[16:19], v[80:83], v[68:71], v[16:19]
	v_mfma_f32_16x16x32_bf16 v[20:23], v[84:87], v[68:71], v[20:23]
	v_mfma_f32_16x16x32_bf16 v[24:27], v[88:91], v[68:71], v[24:27]
	v_mfma_f32_16x16x32_bf16 v[28:31], v[92:95], v[68:71], v[28:31]
	v_mfma_f32_16x16x32_bf16 v[32:35], v[80:83], v[72:75], v[32:35]
	v_mfma_f32_16x16x32_bf16 v[36:39], v[84:87], v[72:75], v[36:39]
	v_mfma_f32_16x16x32_bf16 v[40:43], v[88:91], v[72:75], v[40:43]
	v_mfma_f32_16x16x32_bf16 v[44:47], v[92:95], v[72:75], v[44:47]
	v_mfma_f32_16x16x32_bf16 v[48:51], v[80:83], v[76:79], v[48:51]
	v_mfma_f32_16x16x32_bf16 v[52:55], v[84:87], v[76:79], v[52:55]
	v_mfma_f32_16x16x32_bf16 v[56:59], v[88:91], v[76:79], v[56:59]
	v_mfma_f32_16x16x32_bf16 v[60:63], v[92:95], v[76:79], v[60:63]
	s_waitcnt vmcnt(0) lgkmcnt(0)
	s_barrier
	ds_read_b128 v[64:67], v168 offset:0
	ds_read_b128 v[68:71], v168 offset:2048
	ds_read_b128 v[72:75], v168 offset:4096
	ds_read_b128 v[76:79], v168 offset:6144
	ds_read_b128 v[80:83], v169 offset:0
	ds_read_b128 v[84:87], v169 offset:2048
	ds_read_b128 v[88:91], v169 offset:4096
	ds_read_b128 v[92:95], v169 offset:6144
	s_add_i32 s5, s4, 3
	s_min_u32 s5, s5, 15
	s_lshl_b32 s18, s5, 7
	s_add_u32 m0, s101, 0x8000
	v_lshl_add_u64 v[210:211], v[152:153], 0, s[18:19]
	global_load_lds_dwordx4 v[210:211], off
	s_add_u32 m0, s101, 0xc000
	v_lshl_add_u64 v[210:211], v[154:155], 0, s[18:19]
	global_load_lds_dwordx4 v[210:211], off
	ds_read_b128 v[96:99], v220 offset:0
	ds_read_b128 v[100:103], v220 offset:2048
	ds_read_b128 v[104:107], v220 offset:4096
	ds_read_b128 v[108:111], v220 offset:6144
	ds_read_b128 v[112:115], v221 offset:0
	ds_read_b128 v[116:119], v221 offset:2048
	ds_read_b128 v[120:123], v221 offset:4096
	ds_read_b128 v[124:127], v221 offset:6144
	v_mfma_f32_16x16x32_bf16 v[0:3], v[192:195], v[128:131], v[0:3]
	v_mfma_f32_16x16x32_bf16 v[4:7], v[196:199], v[128:131], v[4:7]
	s_add_u32 m0, s101, 0x9000
	v_lshl_add_u64 v[210:211], v[156:157], 0, s[18:19]
	global_load_lds_dwordx4 v[210:211], off
	v_mfma_f32_16x16x32_bf16 v[8:11], v[200:203], v[128:131], v[8:11]
	v_mfma_f32_16x16x32_bf16 v[12:15], v[204:207], v[128:131], v[12:15]
	s_add_u32 m0, s101, 0xd000
	v_lshl_add_u64 v[210:211], v[158:159], 0, s[18:19]
	global_load_lds_dwordx4 v[210:211], off
	v_mfma_f32_16x16x32_bf16 v[16:19], v[192:195], v[132:135], v[16:19]
	v_mfma_f32_16x16x32_bf16 v[20:23], v[196:199], v[132:135], v[20:23]
	s_add_u32 m0, s101, 0xa000
	v_lshl_add_u64 v[210:211], v[160:161], 0, s[18:19]
	global_load_lds_dwordx4 v[210:211], off
	v_mfma_f32_16x16x32_bf16 v[24:27], v[200:203], v[132:135], v[24:27]
	v_mfma_f32_16x16x32_bf16 v[28:31], v[204:207], v[132:135], v[28:31]
	s_add_u32 m0, s101, 0xe000
	v_lshl_add_u64 v[210:211], v[162:163], 0, s[18:19]
	global_load_lds_dwordx4 v[210:211], off
	v_mfma_f32_16x16x32_bf16 v[32:35], v[192:195], v[136:139], v[32:35]
	v_mfma_f32_16x16x32_bf16 v[36:39], v[196:199], v[136:139], v[36:39]
	s_add_u32 m0, s101, 0xb000
	v_lshl_add_u64 v[210:211], v[164:165], 0, s[18:19]
	global_load_lds_dwordx4 v[210:211], off
	v_mfma_f32_16x16x32_bf16 v[40:43], v[200:203], v[136:139], v[40:43]
	v_mfma_f32_16x16x32_bf16 v[44:47], v[204:207], v[136:139], v[44:47]
	s_add_u32 m0, s101, 0xf000
	v_lshl_add_u64 v[210:211], v[166:167], 0, s[18:19]
	global_load_lds_dwordx4 v[210:211], off
	v_mfma_f32_16x16x32_bf16 v[48:51], v[192:195], v[140:143], v[48:51]
	v_mfma_f32_16x16x32_bf16 v[52:55], v[196:199], v[140:143], v[52:55]
	v_mfma_f32_16x16x32_bf16 v[56:59], v[200:203], v[140:143], v[56:59]
	v_mfma_f32_16x16x32_bf16 v[60:63], v[204:207], v[140:143], v[60:63]
	s_waitcnt lgkmcnt(8)
; DI float ssq_f(u64 v) { return (float)v * (1.f / 1048576.f); }
; #define SB_ __builtin_amdgcn_sched_barrier(0)
; template <bool SWAP, bool HALF>
; DI void gemm_mainloop(const GemmDesc& d, int m0, int n0, bf16_t* smem, f32x16 (&acc)[2][2], int dry) {
;     ...
;   auto stage = [&](int cur, u32x4 (&ran)[4], u32x4 (&rbn)[4], int ks) {
;     ldf(cur, 1, 1); SB_;
;     mma(0); SB_;
;     ldf(cur, 2, 0); SB_;
;     lw(ran, rbn, cur ^ 1);
;     gl(ran, rbn, (ks + 3 < nk) ? ks + 3 : nk - 1);
;     SB_;
;     mma(1); SB_;
;     __syncthreads();
;     ldf(cur, 3, 1); SB_;
;     mma(0); SB_;
;     ldf(cur ^ 1, 0, 0);
;     SB_;
;     mma(1); SB_;
;     __syncthreads();
;   };
;   gl(ra0, rb0, 0);
;   gl(ra1, rb1, 1);
;   lw(ra0, rb0, 0);
;   gl(ra0, rb0, 2);
;   __syncthreads();
;   ldf(0, 0, 0);
; #pragma unroll 1
;   for (int ks = 0; ks < nk; ks += 2) {
;     stage(0, ra1, rb1, ks);
;     stage(1, ra0, rb0, ks + 1);
;   }
; DI void gemm_tile(const GemmDesc& d, int m0, int n0, bf16_t* smem, int dry) {
;     ...
;   } else if (t < 128) {
;     rs_s[t] = rsqrtf(ssq_f(myss) * d.inv_dim + EPS);
;   }
	v_mfma_f32_16x16x32_bf16 v[0:3], v[80:83], v[64:67], v[0:3]
	v_mfma_f32_16x16x32_bf16 v[4:7], v[84:87], v[64:67], v[4:7]
	v_mfma_f32_16x16x32_bf16 v[8:11], v[88:91], v[64:67], v[8:11]
	v_mfma_f32_16x16x32_bf16 v[12:15], v[92:95], v[64:67], v[12:15]
	v_mfma_f32_16x16x32_bf16 v[16:19], v[80:83], v[68:71], v[16:19]
	v_mfma_f32_16x16x32_bf16 v[20:23], v[84:87], v[68:71], v[20:23]
	v_mfma_f32_16x16x32_bf16 v[24:27], v[88:91], v[68:71], v[24:27]
	v_mfma_f32_16x16x32_bf16 v[28:31], v[92:95], v[68:71], v[28:31]
	v_mfma_f32_16x16x32_bf16 v[32:35], v[80:83], v[72:75], v[32:35]
	v_mfma_f32_16x16x32_bf16 v[36:39], v[84:87], v[72:75], v[36:39]
	v_mfma_f32_16x16x32_bf16 v[40:43], v[88:91], v[72:75], v[40:43]
	v_mfma_f32_16x16x32_bf16 v[44:47], v[92:95], v[72:75], v[44:47]
	v_mfma_f32_16x16x32_bf16 v[48:51], v[80:83], v[76:79], v[48:51]
	v_mfma_f32_16x16x32_bf16 v[52:55], v[84:87], v[76:79], v[52:55]
	v_mfma_f32_16x16x32_bf16 v[56:59], v[88:91], v[76:79], v[56:59]
	v_mfma_f32_16x16x32_bf16 v[60:63], v[92:95], v[76:79], v[60:63]
	s_cmp_lt_u32 s4, 12
	s_waitcnt vmcnt(0) lgkmcnt(0)
	s_barrier
	s_cbranch_scc1 .LBB0_1004
	ds_read_b128 v[64:67], v168 offset:32768
	ds_read_b128 v[68:71], v168 offset:34816
	ds_read_b128 v[72:75], v168 offset:36864
	ds_read_b128 v[76:79], v168 offset:38912
	ds_read_b128 v[80:83], v169 offset:32768
	ds_read_b128 v[84:87], v169 offset:34816
	ds_read_b128 v[88:91], v169 offset:36864
	ds_read_b128 v[92:95], v169 offset:38912
	ds_read_b128 v[128:131], v220 offset:32768
	ds_read_b128 v[132:135], v220 offset:34816
	ds_read_b128 v[136:139], v220 offset:36864
	ds_read_b128 v[140:143], v220 offset:38912
	ds_read_b128 v[192:195], v221 offset:32768
	ds_read_b128 v[196:199], v221 offset:34816
	ds_read_b128 v[200:203], v221 offset:36864
	ds_read_b128 v[204:207], v221 offset:38912
	v_mfma_f32_16x16x32_bf16 v[0:3], v[112:115], v[96:99], v[0:3]
	v_mfma_f32_16x16x32_bf16 v[4:7], v[116:119], v[96:99], v[4:7]
	v_mfma_f32_16x16x32_bf16 v[8:11], v[120:123], v[96:99], v[8:11]
	v_mfma_f32_16x16x32_bf16 v[12:15], v[124:127], v[96:99], v[12:15]
	v_mfma_f32_16x16x32_bf16 v[16:19], v[112:115], v[100:103], v[16:19]
	v_mfma_f32_16x16x32_bf16 v[20:23], v[116:119], v[100:103], v[20:23]
	v_mfma_f32_16x16x32_bf16 v[24:27], v[120:123], v[100:103], v[24:27]
	v_mfma_f32_16x16x32_bf16 v[28:31], v[124:127], v[100:103], v[28:31]
	v_mfma_f32_16x16x32_bf16 v[32:35], v[112:115], v[104:107], v[32:35]
	v_mfma_f32_16x16x32_bf16 v[36:39], v[116:119], v[104:107], v[36:39]
	v_mfma_f32_16x16x32_bf16 v[40:43], v[120:123], v[104:107], v[40:43]
	v_mfma_f32_16x16x32_bf16 v[44:47], v[124:127], v[104:107], v[44:47]
	v_mfma_f32_16x16x32_bf16 v[48:51], v[112:115], v[108:111], v[48:51]
	v_mfma_f32_16x16x32_bf16 v[52:55], v[116:119], v[108:111], v[52:55]
	v_mfma_f32_16x16x32_bf16 v[56:59], v[120:123], v[108:111], v[56:59]
	v_mfma_f32_16x16x32_bf16 v[60:63], v[124:127], v[108:111], v[60:63]
	s_waitcnt lgkmcnt(8)
	v_mfma_f32_16x16x32_bf16 v[0:3], v[80:83], v[64:67], v[0:3]
	v_mfma_f32_16x16x32_bf16 v[4:7], v[84:87], v[64:67], v[4:7]
	v_mfma_f32_16x16x32_bf16 v[8:11], v[88:91], v[64:67], v[8:11]
	v_mfma_f32_16x16x32_bf16 v[12:15], v[92:95], v[64:67], v[12:15]
	v_mfma_f32_16x16x32_bf16 v[16:19], v[80:83], v[68:71], v[16:19]
	v_mfma_f32_16x16x32_bf16 v[20:23], v[84:87], v[68:71], v[20:23]
	v_mfma_f32_16x16x32_bf16 v[24:27], v[88:91], v[68:71], v[24:27]
	v_mfma_f32_16x16x32_bf16 v[28:31], v[92:95], v[68:71], v[28:31]
	v_mfma_f32_16x16x32_bf16 v[32:35], v[80:83], v[72:75], v[32:35]
	v_mfma_f32_16x16x32_bf16 v[36:39], v[84:87], v[72:75], v[36:39]
	v_mfma_f32_16x16x32_bf16 v[40:43], v[88:91], v[72:75], v[40:43]
	v_mfma_f32_16x16x32_bf16 v[44:47], v[92:95], v[72:75], v[44:47]
	v_mfma_f32_16x16x32_bf16 v[48:51], v[80:83], v[76:79], v[48:51]
	v_mfma_f32_16x16x32_bf16 v[52:55], v[84:87], v[76:79], v[52:55]
	v_mfma_f32_16x16x32_bf16 v[56:59], v[88:91], v[76:79], v[56:59]
	v_mfma_f32_16x16x32_bf16 v[60:63], v[92:95], v[76:79], v[60:63]
	s_waitcnt lgkmcnt(0)
	s_barrier
	v_mfma_f32_16x16x32_bf16 v[0:3], v[192:195], v[128:131], v[0:3]
	v_mfma_f32_16x16x32_bf16 v[4:7], v[196:199], v[128:131], v[4:7]
	v_mfma_f32_16x16x32_bf16 v[8:11], v[200:203], v[128:131], v[8:11]
	v_mfma_f32_16x16x32_bf16 v[12:15], v[204:207], v[128:131], v[12:15]
	v_mfma_f32_16x16x32_bf16 v[16:19], v[192:195], v[132:135], v[16:19]
	v_mfma_f32_16x16x32_bf16 v[20:23], v[196:199], v[132:135], v[20:23]
	v_mfma_f32_16x16x32_bf16 v[24:27], v[200:203], v[132:135], v[24:27]
	v_mfma_f32_16x16x32_bf16 v[28:31], v[204:207], v[132:135], v[28:31]
	v_mfma_f32_16x16x32_bf16 v[32:35], v[192:195], v[136:139], v[32:35]
	v_mfma_f32_16x16x32_bf16 v[36:39], v[196:199], v[136:139], v[36:39]
	v_mfma_f32_16x16x32_bf16 v[40:43], v[200:203], v[136:139], v[40:43]
	v_mfma_f32_16x16x32_bf16 v[44:47], v[204:207], v[136:139], v[44:47]
	v_mfma_f32_16x16x32_bf16 v[48:51], v[192:195], v[140:143], v[48:51]
	v_mfma_f32_16x16x32_bf16 v[52:55], v[196:199], v[140:143], v[52:55]
	v_mfma_f32_16x16x32_bf16 v[56:59], v[200:203], v[140:143], v[56:59]
	v_mfma_f32_16x16x32_bf16 v[60:63], v[204:207], v[140:143], v[60:63]
	s_and_saveexec_b64 s[4:5], s[42:43]
	s_cbranch_execz .LBB0_1007
	s_mov_b32 s15, 0x800000
	s_waitcnt vmcnt(15)
	v_mul_f32_e32 v64, 0x4b800000, v171
	v_cmp_gt_f32_e32 vcc, s15, v171
	v_lshl_add_u32 v65, v150, 2, v181
	s_nop 0
	v_cndmask_b32_e32 v64, v171, v64, vcc
	v_rsq_f32_e32 v64, v64
	s_nop 0
	v_mul_f32_e32 v66, 0x45800000, v64
	v_cndmask_b32_e32 v64, v64, v66, vcc
	ds_write_b32 v65, v64

; DI int otid() { int t = threadIdx.x; asm volatile("" : "+v"(t)); return t; }
; template <bool SWAP, bool HALF>
; DI void gemm_mainloop(const GemmDesc& d, int m0, int n0, bf16_t* smem, f32x16 (&acc)[2][2], int dry) {
;   const int t = otid(), lane = t & 63, w = t >> 6, wm = w >> 1, wn = w & 1, r = lane & 31, hh = lane >> 5;
;   const int lrow = t >> 3, lkc = t & 7;
;   const bf16_t* ap[4]; const bf16_t* bp[4];
; #pragma unroll
;   for (int i = 0; i < 4; ++i) {
;     int am = m0 + lrow + 32 * i; am = am < M ? am : M - 1;
;     ap[i] = d.A + (size_t)am * d.lda + lkc * 8 + (d.a_grp ? (n0 / d.a_grp) * d.a_grp : 0);
;     bp[i] = d.Bt + (size_t)(n0 + lrow + 32 * i) * d.ldb + lkc * 8;
;   }
; #pragma unroll
;   for (int a = 0; a < 2; ++a)
; #pragma unroll
;     for (int b = 0; b < 2; ++b)
; #pragma unroll
;       for (int i = 0; i < 16; ++i) acc[a][b][i] = 0.f;
;   u32x4 ra0[4], rb0[4], ra1[4], rb1[4];
;   const int nk = d.K >> 6;
;   const int lds_w = lrow * LST + lkc * 8;
;     ...
;   for (int i = slot; i < total; i += nslots) {
;     const int g = i / (8 * nN), j = i - g * 8 * nN;
;     const int gm = (cx - g * 8) < 8 ? (cx - g * 8) : 8;
;     const int mt = (g * 8 + j % gm) * 8 + x, nt = j / gm;
;     gemm_tile(d, mt * 128, nt * 128, smem, dry);
.LBB0_1218:
	s_lshr_b32 s1, s8, 3
	s_and_b32 s1, s1, 0xffffff8
	v_readlane_b32 s5, v228, 38
	s_sub_i32 s5, s5, s1
	s_min_i32 s5, s5, 8
	s_abs_i32 s9, s5
	v_cvt_f32_u32_e32 v0, s9
	s_sub_i32 s10, 0, s9
	s_lshl_b32 s4, s1, 3
	s_sub_i32 s4, s8, s4
	v_rcp_iflag_f32_e32 v0, v0
	s_abs_i32 s7, s4
	s_xor_b32 s6, s4, s5
	s_ashr_i32 s6, s6, 31
	v_mul_f32_e32 v0, 0x4f7ffffe, v0
	v_cvt_u32_f32_e32 v0, v0
	v_mov_b32_e32 v150, v172
	v_mov_b32_e32 v32, v172
	v_readfirstlane_b32 s11, v0
	s_mul_i32 s10, s10, s11
	s_mul_hi_u32 s10, s11, s10
	s_add_i32 s11, s11, s10
	s_mul_hi_u32 s10, s7, s11
	s_mul_i32 s11, s10, s9
	s_sub_i32 s7, s7, s11
	s_add_i32 s11, s10, 1
	s_sub_i32 s12, s7, s9
	s_cmp_ge_u32 s7, s9
	s_cselect_b32 s10, s11, s10
	s_cselect_b32 s7, s12, s7
	s_add_i32 s11, s10, 1
	s_cmp_ge_u32 s7, s9
	s_cselect_b32 s7, s11, s10
	s_xor_b32 s7, s7, s6
	s_sub_i32 s6, s7, s6
	s_mul_i32 s5, s6, s5
	s_sub_i32 s4, s4, s5
	s_add_i32 s1, s1, s4
	s_lshl_b32 s4, s6, 7
	s_lshl_b32 s1, s1, 10
	v_ashrrev_i32_e32 v10, 3, v32
	v_lshlrev_b32_e32 v0, 3, v32
	v_and_b32_e32 v33, 56, v0
	v_add_u32_e32 v2, s4, v10
	v_readlane_b32 s76, v228, 60
	s_or_b32 s9, s1, s29
	v_lshlrev_b32_e32 v144, 1, v33
	v_readlane_b32 s80, v223, 0
	v_readlane_b32 s81, v223, 1
	v_ashrrev_i32_e32 v3, 31, v2
	v_add_u32_e32 v11, s9, v10
	v_lshl_add_u64 v[4:5], s[80:81], 0, v[144:145]
	v_lshlrev_b64 v[2:3], 11, v[2:3]
	v_lshl_add_u64 v[154:155], v[4:5], 0, v[2:3]
	v_min_i32_e32 v2, 0x801f, v11
	v_ashrrev_i32_e32 v3, 31, v2
	v_lshl_add_u64 v[0:1], s[68:69], 0, v[144:145]
	v_lshlrev_b64 v[2:3], 11, v[2:3]
	v_lshl_add_u64 v[8:9], v[0:1], 0, v[2:3]
	v_min_i32_e32 v2, 0x7fff, v11
	v_ashrrev_i32_e32 v3, 31, v2
	v_min_i32_e32 v6, 0x803f, v11
	v_lshlrev_b64 v[2:3], 11, v[2:3]
	v_ashrrev_i32_e32 v7, 31, v6
	v_lshl_add_u64 v[16:17], v[0:1], 0, v[2:3]
	v_min_i32_e32 v2, 0x7fdf, v11
	v_lshlrev_b64 v[6:7], 11, v[6:7]
	v_ashrrev_i32_e32 v3, 31, v2
	v_lshl_add_u64 v[152:153], v[0:1], 0, v[6:7]
	v_lshlrev_b64 v[2:3], 11, v[2:3]
	v_lshl_add_u64 v[24:25], v[0:1], 0, v[2:3]
	s_mov_b64 s[6:7], 0x10000
	v_lshl_add_u64 v[156:157], v[8:9], 0, s[6:7]
	v_lshl_add_u64 v[158:159], v[154:155], 0, s[6:7]
	s_mov_b64 s[6:7], 0x20000
	v_lshl_add_u64 v[160:161], v[16:17], 0, s[6:7]
	v_lshl_add_u64 v[162:163], v[154:155], 0, s[6:7]
	s_mov_b64 s[6:7], 0x30000
	s_movk_i32 s1, 0x48
	v_lshl_add_u64 v[164:165], v[24:25], 0, s[6:7]
	v_lshl_add_u64 v[166:167], v[154:155], 0, s[6:7]
	v_and_b32_e32 v34, 31, v32
	v_mul_lo_u32 v35, v10, s1
	v_readlane_b32 s77, v228, 61
	v_readlane_b32 s78, v228, 62
	v_readlane_b32 s79, v228, 63
	v_readlane_b32 s82, v223, 2
	v_readlane_b32 s83, v223, 3
	v_readlane_b32 s84, v223, 4
	v_readlane_b32 s85, v223, 5
	v_readlane_b32 s86, v223, 6
	v_readlane_b32 s87, v223, 7
	v_readlane_b32 s88, v223, 8
	v_readlane_b32 s89, v223, 9
	v_readlane_b32 s90, v223, 10
	v_readlane_b32 s91, v223, 11
	s_mov_b32 s1, 0x10000
	v_add_co_u32_e32 v8, vcc, s1, v8
	s_nop 1
	v_addc_co_u32_e32 v9, vcc, 0, v9, vcc
	s_waitcnt vmcnt(19)
	v_add_co_u32_e32 v12, vcc, s1, v154
	s_nop 1
	v_addc_co_u32_e32 v13, vcc, 0, v155, vcc
	s_mov_b32 s1, 0x20000
	v_add_co_u32_e32 v16, vcc, s1, v16
	s_nop 1
	v_addc_co_u32_e32 v17, vcc, 0, v17, vcc
	v_add_co_u32_e32 v20, vcc, s1, v154
	s_nop 1
	v_addc_co_u32_e32 v21, vcc, 0, v155, vcc
	s_mov_b32 s1, 0x30000
	v_add_co_u32_e32 v24, vcc, s1, v24
	s_nop 1
	v_addc_co_u32_e32 v25, vcc, 0, v25, vcc
	v_add_co_u32_e32 v28, vcc, s1, v154
	s_nop 1
	v_addc_co_u32_e32 v29, vcc, 0, v155, vcc
	s_nop 0
	v_add_lshl_u32 v144, v35, v33, 1
	s_waitcnt vmcnt(15)
	s_waitcnt vmcnt(14)
	s_waitcnt vmcnt(13)
	s_waitcnt vmcnt(12)
	s_waitcnt vmcnt(11)
	s_waitcnt vmcnt(10)
	s_waitcnt vmcnt(9)
	s_waitcnt vmcnt(8)
	v_lshrrev_b32_e32 v0, 1, v32
	v_and_or_b32 v1, v0, s72, v34
	v_and_b32_e32 v0, 16, v0
	s_movk_i32 s1, 0x90
	v_mad_u64_u32 v[168:169], s[6:7], v1, s1, v[0:1]
	v_and_b32_e32 v1, 0x5f, v32
	v_mul_u32_u24_e32 v1, 0x48, v1
	v_lshl_add_u32 v169, v1, 1, v0
	v_bfe_u32 v212, v172, 4, 3
	v_lshlrev_b32_e32 v212, 4, v212
	v_xor_b32_e32 v152, v152, v212
	v_xor_b32_e32 v154, v154, v212
	v_xor_b32_e32 v156, v156, v212
	v_xor_b32_e32 v158, v158, v212
	v_xor_b32_e32 v160, v160, v212
	v_xor_b32_e32 v162, v162, v212
	v_xor_b32_e32 v164, v164, v212
	v_xor_b32_e32 v166, v166, v212
	v_lshrrev_b32_e32 v213, 6, v172
	s_nop 1
	v_readfirstlane_b32 s101, v213
	s_lshl_b32 s101, s101, 10
	s_add_u32 m0, s101, 0x0
	s_nop 0
	global_load_lds_dwordx4 v[152:153], off
	s_add_u32 m0, s101, 0x4000
	s_nop 0
	global_load_lds_dwordx4 v[154:155], off
	s_add_u32 m0, s101, 0x1000
	s_nop 0
	global_load_lds_dwordx4 v[156:157], off
	s_add_u32 m0, s101, 0x5000
	s_nop 0
	global_load_lds_dwordx4 v[158:159], off
	s_add_u32 m0, s101, 0x2000
	s_nop 0
	global_load_lds_dwordx4 v[160:161], off
	s_add_u32 m0, s101, 0x6000
	s_nop 0
	global_load_lds_dwordx4 v[162:163], off
	s_add_u32 m0, s101, 0x3000
	s_nop 0
	global_load_lds_dwordx4 v[164:165], off
	s_add_u32 m0, s101, 0x7000
	s_nop 0
	global_load_lds_dwordx4 v[166:167], off
	v_and_b32_e32 v212, 15, v172
	v_bfe_u32 v213, v172, 4, 2
	v_lshrrev_b32_e32 v214, 1, v212
	v_xor_b32_e32 v213, v213, v214
	v_lshlrev_b32_e32 v213, 4, v213
	v_lshl_or_b32 v212, v212, 7, v213
	v_lshrrev_b32_e32 v214, 7, v172
	v_lshl_add_u32 v168, v214, 13, v212
	v_bfe_u32 v214, v172, 6, 1
	v_lshl_add_u32 v169, v214, 13, v212
	v_add_u32_e32 v169, 0x4000, v169
	v_xor_b32_e32 v220, 64, v168
	v_xor_b32_e32 v221, 64, v169
	s_waitcnt vmcnt(0) lgkmcnt(0)
	s_barrier
; #define SB_ __builtin_amdgcn_sched_barrier(0)
; template <bool SWAP, bool HALF>
; DI void gemm_mainloop(const GemmDesc& d, int m0, int n0, bf16_t* smem, f32x16 (&acc)[2][2], int dry) {
;     ...
;   for (int a = 0; a < 2; ++a)
; #pragma unroll
;     for (int b = 0; b < 2; ++b)
; #pragma unroll
;       for (int i = 0; i < 16; ++i) acc[a][b][i] = 0.f;
;     ...
;   auto stage = [&](int cur, u32x4 (&ran)[4], u32x4 (&rbn)[4], int ks) {
;     ldf(cur, 1, 1); SB_;
;     mma(0); SB_;
;     ldf(cur, 2, 0); SB_;
;     lw(ran, rbn, cur ^ 1);
;     gl(ran, rbn, (ks + 3 < nk) ? ks + 3 : nk - 1);
;     SB_;
;     mma(1); SB_;
;     __syncthreads();
;     ldf(cur, 3, 1); SB_;
;     mma(0); SB_;
;     ldf(cur ^ 1, 0, 0);
;     SB_;
;     mma(1); SB_;
;     __syncthreads();
;   };
;   gl(ra0, rb0, 0);
;   gl(ra1, rb1, 1);
;   lw(ra0, rb0, 0);
;   gl(ra0, rb0, 2);
;   __syncthreads();
;   ldf(0, 0, 0);
; #pragma unroll 1
;   for (int ks = 0; ks < nk; ks += 2) {
;     stage(0, ra1, rb1, ks);
	v_mov_b32_e32 v0, 0
	v_add_u32_e32 v170, 0x9000, v144
	s_mov_b32 s1, -2
	v_mov_b32_e32 v1, v0
	v_mov_b32_e32 v2, v0
	v_mov_b32_e32 v3, v0
	v_mov_b32_e32 v4, v0
	v_mov_b32_e32 v5, v0
	v_mov_b32_e32 v6, v0
	v_mov_b32_e32 v7, v0
	v_mov_b32_e32 v8, v0
	v_mov_b32_e32 v9, v0
	v_mov_b32_e32 v10, v0
	v_mov_b32_e32 v11, v0
	v_mov_b32_e32 v12, v0
	v_mov_b32_e32 v13, v0
	v_mov_b32_e32 v14, v0
	v_mov_b32_e32 v15, v0
	v_mov_b32_e32 v16, v0
	v_mov_b32_e32 v17, v0
	v_mov_b32_e32 v18, v0
	v_mov_b32_e32 v19, v0
	v_mov_b32_e32 v20, v0
	v_mov_b32_e32 v21, v0
	v_mov_b32_e32 v22, v0
	v_mov_b32_e32 v23, v0
	v_mov_b32_e32 v24, v0
	v_mov_b32_e32 v25, v0
	v_mov_b32_e32 v26, v0
	v_mov_b32_e32 v27, v0
	v_mov_b32_e32 v28, v0
	v_mov_b32_e32 v29, v0
	v_mov_b32_e32 v30, v0
	v_mov_b32_e32 v31, v0
	v_mov_b32_e32 v32, v0
	v_mov_b32_e32 v33, v0
	v_mov_b32_e32 v34, v0
	v_mov_b32_e32 v35, v0
	v_mov_b32_e32 v36, v0
	v_mov_b32_e32 v37, v0
	v_mov_b32_e32 v38, v0
	v_mov_b32_e32 v39, v0
	v_mov_b32_e32 v40, v0
	v_mov_b32_e32 v41, v0
	v_mov_b32_e32 v42, v0
	v_mov_b32_e32 v43, v0
	v_mov_b32_e32 v44, v0
	v_mov_b32_e32 v45, v0
	v_mov_b32_e32 v46, v0
	v_mov_b32_e32 v47, v0
	v_mov_b32_e32 v48, v0
	v_mov_b32_e32 v49, v0
	v_mov_b32_e32 v50, v0
	v_mov_b32_e32 v51, v0
	v_mov_b32_e32 v52, v0
	v_mov_b32_e32 v53, v0
	v_mov_b32_e32 v54, v0
	v_mov_b32_e32 v55, v0
	v_mov_b32_e32 v56, v0
	v_mov_b32_e32 v57, v0
	v_mov_b32_e32 v58, v0
	v_mov_b32_e32 v59, v0
	v_mov_b32_e32 v60, v0
	v_mov_b32_e32 v61, v0
	v_mov_b32_e32 v62, v0
	v_mov_b32_e32 v63, v0
	ds_read_b128 v[64:67], v168 offset:0
	ds_read_b128 v[68:71], v168 offset:2048
	ds_read_b128 v[72:75], v168 offset:4096
	ds_read_b128 v[76:79], v168 offset:6144
	ds_read_b128 v[80:83], v169 offset:0
	ds_read_b128 v[84:87], v169 offset:2048
	ds_read_b128 v[88:91], v169 offset:4096
	ds_read_b128 v[92:95], v169 offset:6144
	s_add_i32 s5, s1, 3
	s_min_u32 s5, s5, 15
	s_lshl_b32 s18, s5, 7
	s_add_u32 m0, s101, 0x8000
	v_lshl_add_u64 v[210:211], v[152:153], 0, s[18:19]
	global_load_lds_dwordx4 v[210:211], off
	s_add_u32 m0, s101, 0xc000
	v_lshl_add_u64 v[210:211], v[154:155], 0, s[18:19]
	global_load_lds_dwordx4 v[210:211], off
	ds_read_b128 v[96:99], v220 offset:0
	ds_read_b128 v[100:103], v220 offset:2048
	ds_read_b128 v[104:107], v220 offset:4096
	ds_read_b128 v[108:111], v220 offset:6144
	ds_read_b128 v[112:115], v221 offset:0
	ds_read_b128 v[116:119], v221 offset:2048
	ds_read_b128 v[120:123], v221 offset:4096
	ds_read_b128 v[124:127], v221 offset:6144
	s_waitcnt lgkmcnt(8)
	v_mfma_f32_16x16x32_bf16 v[0:3], v[80:83], v[64:67], v[0:3]
	v_mfma_f32_16x16x32_bf16 v[4:7], v[84:87], v[64:67], v[4:7]
	s_add_u32 m0, s101, 0x9000
	v_lshl_add_u64 v[210:211], v[156:157], 0, s[18:19]
	global_load_lds_dwordx4 v[210:211], off
	v_mfma_f32_16x16x32_bf16 v[8:11], v[88:91], v[64:67], v[8:11]
	v_mfma_f32_16x16x32_bf16 v[12:15], v[92:95], v[64:67], v[12:15]
	s_add_u32 m0, s101, 0xd000
	v_lshl_add_u64 v[210:211], v[158:159], 0, s[18:19]
	global_load_lds_dwordx4 v[210:211], off
	v_mfma_f32_16x16x32_bf16 v[16:19], v[80:83], v[68:71], v[16:19]
	v_mfma_f32_16x16x32_bf16 v[20:23], v[84:87], v[68:71], v[20:23]
	s_add_u32 m0, s101, 0xa000
	v_lshl_add_u64 v[210:211], v[160:161], 0, s[18:19]
	global_load_lds_dwordx4 v[210:211], off
	v_mfma_f32_16x16x32_bf16 v[24:27], v[88:91], v[68:71], v[24:27]
	v_mfma_f32_16x16x32_bf16 v[28:31], v[92:95], v[68:71], v[28:31]
	s_add_u32 m0, s101, 0xe000
	v_lshl_add_u64 v[210:211], v[162:163], 0, s[18:19]
	global_load_lds_dwordx4 v[210:211], off
	v_mfma_f32_16x16x32_bf16 v[32:35], v[80:83], v[72:75], v[32:35]
	v_mfma_f32_16x16x32_bf16 v[36:39], v[84:87], v[72:75], v[36:39]
	s_add_u32 m0, s101, 0xb000
	v_lshl_add_u64 v[210:211], v[164:165], 0, s[18:19]
	global_load_lds_dwordx4 v[210:211], off
	v_mfma_f32_16x16x32_bf16 v[40:43], v[88:91], v[72:75], v[40:43]
	v_mfma_f32_16x16x32_bf16 v[44:47], v[92:95], v[72:75], v[44:47]
	s_add_u32 m0, s101, 0xf000
	v_lshl_add_u64 v[210:211], v[166:167], 0, s[18:19]
	global_load_lds_dwordx4 v[210:211], off
	v_mfma_f32_16x16x32_bf16 v[48:51], v[80:83], v[76:79], v[48:51]
	v_mfma_f32_16x16x32_bf16 v[52:55], v[84:87], v[76:79], v[52:55]
	v_mfma_f32_16x16x32_bf16 v[56:59], v[88:91], v[76:79], v[56:59]
	v_mfma_f32_16x16x32_bf16 v[60:63], v[92:95], v[76:79], v[60:63]
	s_waitcnt vmcnt(0) lgkmcnt(0)
	s_barrier

; #define MFMA32(a, b, c) __builtin_amdgcn_mfma_f32_32x32x16_bf16((a), (b), (c), 0, 0, 0)
; template <bool SWAP, bool HALF>
; DI void gemm_mainloop(const GemmDesc& d, int m0, int n0, bf16_t* smem, f32x16 (&acc)[2][2], int dry) {
;     ...
;       for (int i = 0; i < 16; ++i) acc[a][b][i] = 0.f;
;   u32x4 ra0[4], rb0[4], ra1[4], rb1[4];
;   const int nk = d.K >> 6;
;   const int lds_w = lrow * LST + lkc * 8;
;   auto gl = [&](u32x4 (&ra)[4], u32x4 (&rb)[4], int ks) {
; #pragma unroll
;     for (int i = 0; i < 4; ++i) {
;       ra[i] = *(const u32x4*)(ap[i] + (size_t)ks * d.a_cs);
;       __builtin_amdgcn_sched_barrier(0);
;       rb[i] = *(const u32x4*)(bp[i] + (size_t)ks * 64);
;       __builtin_amdgcn_sched_barrier(0);
;     }
;   };
;   auto lw = [&](const u32x4 (&ra)[4], const u32x4 (&rb)[4], int buf) {
;     bf16_t* An = smem + buf * 2 * TILE_EL + lds_w; bf16_t* Bn = An + TILE_EL;
; #pragma unroll
;     for (int i = 0; i < 4; ++i) {
;       *(u32x4*)(An + 32 * i * LST) = ra[i];
;       *(u32x4*)(Bn + 32 * i * LST) = rb[i];
;     }
;   };
;   bf16x8 fa[2][2], fb[2][2];
;   auto ldf = [&](int buf, int kk, int set) {
;     const bf16_t* Ab = smem + buf * 2 * TILE_EL + ((HALF ? 0 : wm * 64) + r) * LST + 8 * hh + kk * 16;
;     const bf16_t* Bb = smem + buf * 2 * TILE_EL + TILE_EL + ((HALF ? w * 32 : wn * 64) + r) * LST + 8 * hh + kk * 16;
; #pragma unroll
;     for (int i = 0; i < 2; ++i) { fa[set][i] = *(const bf16x8*)(Ab + i * 32 * LST); if (!HALF || i == 0) fb[set][i] = *(const bf16x8*)(Bb + i * 32 * LST); }
;   };
;   auto mma = [&](int set) {
; #pragma unroll
;     for (int a = 0; a < 2; ++a)
; #pragma unroll
;       for (int b = 0; b < (HALF ? 1 : 2); ++b) {
;         if (SWAP) acc[a][b] = MFMA32(fb[set][b], fa[set][a], acc[a][b]);
;         else      acc[a][b] = MFMA32(fa[set][a], fb[set][b], acc[a][b]);
;       }
;   };
;     ...
;   auto stage = [&](int cur, u32x4 (&ran)[4], u32x4 (&rbn)[4], int ks) {
;     ldf(cur, 1, 1); SB_;
;     mma(0); SB_;
;     ldf(cur, 2, 0); SB_;
;     lw(ran, rbn, cur ^ 1);
;     gl(ran, rbn, (ks + 3 < nk) ? ks + 3 : nk - 1);
;     SB_;
;     mma(1); SB_;
;     __syncthreads();
;     ldf(cur, 3, 1); SB_;
;     mma(0); SB_;
;     ldf(cur ^ 1, 0, 0);
;     SB_;
;     mma(1); SB_;
;     __syncthreads();
;   };
;   gl(ra0, rb0, 0);
;   gl(ra1, rb1, 1);
;   lw(ra0, rb0, 0);
;   gl(ra0, rb0, 2);
;   __syncthreads();
;   ldf(0, 0, 0);
.LBB0_1461:
	s_or_b64 exec, exec, s[4:5]
	v_mov_b32_e32 v32, v172
	s_mov_b64 s[4:5], 0x10000
	v_ashrrev_i32_e32 v10, 3, v32
	v_lshlrev_b32_e32 v0, 3, v32
	v_and_b32_e32 v33, 56, v0
	v_lshl_add_u32 v2, s13, 7, v10
	v_lshlrev_b32_e32 v144, 1, v33
	v_ashrrev_i32_e32 v3, 31, v2
	v_add_u32_e32 v11, s14, v10
	v_lshl_add_u64 v[4:5], s[6:7], 0, v[144:145]
	v_lshlrev_b64 v[2:3], 11, v[2:3]
	v_lshl_add_u64 v[154:155], v[4:5], 0, v[2:3]
	v_min_i32_e32 v2, 0x801f, v11
	v_ashrrev_i32_e32 v3, 31, v2
	v_lshl_add_u64 v[0:1], s[56:57], 0, v[144:145]
	v_lshlrev_b64 v[2:3], 11, v[2:3]
	v_lshl_add_u64 v[8:9], v[0:1], 0, v[2:3]
	v_min_i32_e32 v2, 0x7fff, v11
	v_ashrrev_i32_e32 v3, 31, v2
	v_min_i32_e32 v6, 0x803f, v11
	v_lshlrev_b64 v[2:3], 11, v[2:3]
	v_ashrrev_i32_e32 v7, 31, v6
	v_lshl_add_u64 v[16:17], v[0:1], 0, v[2:3]
	v_min_i32_e32 v2, 0x7fdf, v11
	v_lshlrev_b64 v[6:7], 11, v[6:7]
	v_ashrrev_i32_e32 v3, 31, v2
	v_lshl_add_u64 v[152:153], v[0:1], 0, v[6:7]
	v_lshlrev_b64 v[2:3], 11, v[2:3]
	v_lshl_add_u64 v[24:25], v[0:1], 0, v[2:3]
	v_lshl_add_u64 v[156:157], v[8:9], 0, s[4:5]
	v_lshl_add_u64 v[158:159], v[154:155], 0, s[4:5]
	s_mov_b64 s[4:5], 0x20000
	v_lshl_add_u64 v[160:161], v[16:17], 0, s[4:5]
	v_lshl_add_u64 v[162:163], v[154:155], 0, s[4:5]
	s_mov_b64 s[4:5], 0x30000
	v_lshl_add_u64 v[164:165], v[24:25], 0, s[4:5]
	v_lshl_add_u64 v[166:167], v[154:155], 0, s[4:5]
	s_movk_i32 s4, 0x48
	v_and_b32_e32 v34, 31, v32
	v_mul_lo_u32 v35, v10, s4
	s_mov_b32 s15, 0x10000
	v_add_co_u32_e64 v8, s[4:5], s15, v8
	s_mov_b32 s14, 0
	s_nop 0
	v_addc_co_u32_e64 v9, s[4:5], 0, v9, s[4:5]
	s_waitcnt vmcnt(19)
	v_add_co_u32_e64 v12, s[4:5], s15, v154
	s_nop 1
	v_addc_co_u32_e64 v13, s[4:5], 0, v155, s[4:5]
	s_mov_b32 s15, 0x20000
	v_add_co_u32_e64 v16, s[4:5], s15, v16
	s_nop 1
	v_addc_co_u32_e64 v17, s[4:5], 0, v17, s[4:5]
	v_add_co_u32_e64 v20, s[4:5], s15, v154
	s_nop 1
	v_addc_co_u32_e64 v21, s[4:5], 0, v155, s[4:5]
	s_mov_b32 s15, 0x30000
	v_add_co_u32_e64 v24, s[4:5], s15, v24
	s_nop 1
	v_addc_co_u32_e64 v25, s[4:5], 0, v25, s[4:5]
	v_add_co_u32_e64 v28, s[4:5], s15, v154
	s_nop 1
	v_addc_co_u32_e64 v29, s[4:5], 0, v155, s[4:5]
	s_nop 0
	v_add_lshl_u32 v144, v35, v33, 1
	s_waitcnt vmcnt(15)
	s_waitcnt vmcnt(14)
	s_waitcnt vmcnt(13)
	s_waitcnt vmcnt(12)
	s_waitcnt vmcnt(11)
	s_waitcnt vmcnt(10)
	s_waitcnt vmcnt(9)
	s_waitcnt vmcnt(8)
	v_lshrrev_b32_e32 v0, 1, v32
	v_and_or_b32 v1, v0, s72, v34
	v_and_b32_e32 v0, 16, v0
	s_movk_i32 s4, 0x90
	v_mad_u64_u32 v[168:169], s[4:5], v1, s4, v[0:1]
	v_and_b32_e32 v1, 0x5f, v32
	v_mul_u32_u24_e32 v1, 0x48, v1
	v_lshl_add_u32 v169, v1, 1, v0
	v_bfe_u32 v212, v172, 4, 3
	v_lshlrev_b32_e32 v212, 4, v212
	v_xor_b32_e32 v152, v152, v212
	v_xor_b32_e32 v154, v154, v212
	v_xor_b32_e32 v156, v156, v212
	v_xor_b32_e32 v158, v158, v212
	v_xor_b32_e32 v160, v160, v212
	v_xor_b32_e32 v162, v162, v212
	v_xor_b32_e32 v164, v164, v212
	v_xor_b32_e32 v166, v166, v212
	v_lshrrev_b32_e32 v213, 6, v172
	s_nop 1
	v_readfirstlane_b32 s101, v213
	s_lshl_b32 s101, s101, 10
	s_add_u32 m0, s101, 0x0
	s_nop 0
	global_load_lds_dwordx4 v[152:153], off
	s_add_u32 m0, s101, 0x4000
	s_nop 0
	global_load_lds_dwordx4 v[154:155], off
	s_add_u32 m0, s101, 0x1000
	s_nop 0
	global_load_lds_dwordx4 v[156:157], off
	s_add_u32 m0, s101, 0x5000
	s_nop 0
	global_load_lds_dwordx4 v[158:159], off
	s_add_u32 m0, s101, 0x2000
	s_nop 0
	global_load_lds_dwordx4 v[160:161], off
	s_add_u32 m0, s101, 0x6000
	s_nop 0
	global_load_lds_dwordx4 v[162:163], off
	s_add_u32 m0, s101, 0x3000
	s_nop 0
	global_load_lds_dwordx4 v[164:165], off
	s_add_u32 m0, s101, 0x7000
	s_nop 0
	global_load_lds_dwordx4 v[166:167], off
	v_and_b32_e32 v212, 15, v172
	v_bfe_u32 v213, v172, 4, 2
	v_lshrrev_b32_e32 v214, 1, v212
	v_xor_b32_e32 v213, v213, v214
	v_lshlrev_b32_e32 v213, 4, v213
	v_lshl_or_b32 v212, v212, 7, v213
	v_lshrrev_b32_e32 v214, 7, v172
	v_lshl_add_u32 v168, v214, 13, v212
	v_bfe_u32 v214, v172, 6, 1
	v_lshl_add_u32 v169, v214, 13, v212
	v_add_u32_e32 v169, 0x4000, v169
	v_xor_b32_e32 v220, 64, v168
	v_xor_b32_e32 v221, 64, v169
	s_waitcnt vmcnt(0) lgkmcnt(0)
	s_barrier
	v_mov_b32_e32 v0, 0
	v_add_u32_e32 v171, 0x9000, v144
	v_mov_b32_e32 v1, v0
	v_mov_b32_e32 v2, v0
	v_mov_b32_e32 v3, v0
	v_mov_b32_e32 v4, v0
	v_mov_b32_e32 v5, v0
	v_mov_b32_e32 v6, v0
	v_mov_b32_e32 v7, v0
	v_mov_b32_e32 v8, v0
	v_mov_b32_e32 v9, v0
	v_mov_b32_e32 v10, v0
	v_mov_b32_e32 v11, v0
	v_mov_b32_e32 v12, v0
	v_mov_b32_e32 v13, v0
	v_mov_b32_e32 v14, v0
	v_mov_b32_e32 v15, v0
	v_mov_b32_e32 v16, v0
	v_mov_b32_e32 v17, v0
	v_mov_b32_e32 v18, v0
	v_mov_b32_e32 v19, v0
	v_mov_b32_e32 v20, v0
	v_mov_b32_e32 v21, v0
	v_mov_b32_e32 v22, v0
	v_mov_b32_e32 v23, v0
	v_mov_b32_e32 v24, v0
	v_mov_b32_e32 v25, v0
	v_mov_b32_e32 v26, v0
	v_mov_b32_e32 v27, v0
	v_mov_b32_e32 v28, v0
	v_mov_b32_e32 v29, v0
	v_mov_b32_e32 v30, v0
	v_mov_b32_e32 v31, v0
	v_mov_b32_e32 v32, v0
	v_mov_b32_e32 v33, v0
	v_mov_b32_e32 v34, v0
	v_mov_b32_e32 v35, v0
	v_mov_b32_e32 v36, v0
	v_mov_b32_e32 v37, v0
	v_mov_b32_e32 v38, v0
	v_mov_b32_e32 v39, v0
	v_mov_b32_e32 v40, v0
	v_mov_b32_e32 v41, v0
	v_mov_b32_e32 v42, v0
	v_mov_b32_e32 v43, v0
	v_mov_b32_e32 v44, v0
	v_mov_b32_e32 v45, v0
	v_mov_b32_e32 v46, v0
	v_mov_b32_e32 v47, v0
	v_mov_b32_e32 v48, v0
	v_mov_b32_e32 v49, v0
	v_mov_b32_e32 v50, v0
	v_mov_b32_e32 v51, v0
	v_mov_b32_e32 v52, v0
	v_mov_b32_e32 v53, v0
	v_mov_b32_e32 v54, v0
	v_mov_b32_e32 v55, v0
	v_mov_b32_e32 v56, v0
	v_mov_b32_e32 v57, v0
	v_mov_b32_e32 v58, v0
	v_mov_b32_e32 v59, v0
	v_mov_b32_e32 v60, v0
	v_mov_b32_e32 v61, v0
	v_mov_b32_e32 v62, v0
	v_mov_b32_e32 v63, v0
	ds_read_b128 v[64:67], v168 offset:0
	ds_read_b128 v[68:71], v168 offset:2048
	ds_read_b128 v[72:75], v168 offset:4096
	ds_read_b128 v[76:79], v168 offset:6144
	ds_read_b128 v[80:83], v169 offset:0
	ds_read_b128 v[84:87], v169 offset:2048
	ds_read_b128 v[88:91], v169 offset:4096
	ds_read_b128 v[92:95], v169 offset:6144
	s_add_i32 s4, s14, 1
	s_min_u32 s4, s4, 15
	s_lshl_b32 s18, s4, 7
	s_add_u32 m0, s101, 0x8000
	v_lshl_add_u64 v[210:211], v[152:153], 0, s[18:19]
	global_load_lds_dwordx4 v[210:211], off
	s_add_u32 m0, s101, 0xc000
	v_lshl_add_u64 v[210:211], v[154:155], 0, s[18:19]
	global_load_lds_dwordx4 v[210:211], off
	ds_read_b128 v[96:99], v220 offset:0
	ds_read_b128 v[100:103], v220 offset:2048
	ds_read_b128 v[104:107], v220 offset:4096
	ds_read_b128 v[108:111], v220 offset:6144
	ds_read_b128 v[112:115], v221 offset:0
	ds_read_b128 v[116:119], v221 offset:2048
	ds_read_b128 v[120:123], v221 offset:4096
	ds_read_b128 v[124:127], v221 offset:6144
	s_waitcnt lgkmcnt(8)
; #define MFMA32(a, b, c) __builtin_amdgcn_mfma_f32_32x32x16_bf16((a), (b), (c), 0, 0, 0)
; #define SB_ __builtin_amdgcn_sched_barrier(0)
; template <bool SWAP, bool HALF>
; DI void gemm_mainloop(const GemmDesc& d, int m0, int n0, bf16_t* smem, f32x16 (&acc)[2][2], int dry) {
;     ...
;   auto mma = [&](int set) {
; #pragma unroll
;     for (int a = 0; a < 2; ++a)
; #pragma unroll
;       for (int b = 0; b < (HALF ? 1 : 2); ++b) {
;         if (SWAP) acc[a][b] = MFMA32(fb[set][b], fa[set][a], acc[a][b]);
;         else      acc[a][b] = MFMA32(fa[set][a], fb[set][b], acc[a][b]);
;       }
;   };
;     ...
;   auto stage = [&](int cur, u32x4 (&ran)[4], u32x4 (&rbn)[4], int ks) {
;     ldf(cur, 1, 1); SB_;
;     mma(0); SB_;
;     ldf(cur, 2, 0); SB_;
;     lw(ran, rbn, cur ^ 1);
;     gl(ran, rbn, (ks + 3 < nk) ? ks + 3 : nk - 1);
;     SB_;
;     mma(1); SB_;
;     __syncthreads();
;     ldf(cur, 3, 1); SB_;
;     mma(0); SB_;
;     ldf(cur ^ 1, 0, 0);
;     SB_;
;     mma(1); SB_;
;     __syncthreads();
;   };
	v_mfma_f32_16x16x32_bf16 v[0:3], v[80:83], v[64:67], v[0:3]
	v_mfma_f32_16x16x32_bf16 v[4:7], v[84:87], v[64:67], v[4:7]
	s_add_u32 m0, s101, 0x9000
	v_lshl_add_u64 v[210:211], v[156:157], 0, s[18:19]
	global_load_lds_dwordx4 v[210:211], off
	v_mfma_f32_16x16x32_bf16 v[8:11], v[88:91], v[64:67], v[8:11]
	v_mfma_f32_16x16x32_bf16 v[12:15], v[92:95], v[64:67], v[12:15]
	s_add_u32 m0, s101, 0xd000
	v_lshl_add_u64 v[210:211], v[158:159], 0, s[18:19]
	global_load_lds_dwordx4 v[210:211], off
	v_mfma_f32_16x16x32_bf16 v[16:19], v[80:83], v[68:71], v[16:19]
	v_mfma_f32_16x16x32_bf16 v[20:23], v[84:87], v[68:71], v[20:23]
	s_add_u32 m0, s101, 0xa000
	v_lshl_add_u64 v[210:211], v[160:161], 0, s[18:19]
	global_load_lds_dwordx4 v[210:211], off
	v_mfma_f32_16x16x32_bf16 v[24:27], v[88:91], v[68:71], v[24:27]
	v_mfma_f32_16x16x32_bf16 v[28:31], v[92:95], v[68:71], v[28:31]
	s_add_u32 m0, s101, 0xe000
	v_lshl_add_u64 v[210:211], v[162:163], 0, s[18:19]
	global_load_lds_dwordx4 v[210:211], off
	v_mfma_f32_16x16x32_bf16 v[32:35], v[80:83], v[72:75], v[32:35]
	v_mfma_f32_16x16x32_bf16 v[36:39], v[84:87], v[72:75], v[36:39]
	s_add_u32 m0, s101, 0xb000
	v_lshl_add_u64 v[210:211], v[164:165], 0, s[18:19]
	global_load_lds_dwordx4 v[210:211], off
	v_mfma_f32_16x16x32_bf16 v[40:43], v[88:91], v[72:75], v[40:43]
	v_mfma_f32_16x16x32_bf16 v[44:47], v[92:95], v[72:75], v[44:47]
	s_add_u32 m0, s101, 0xf000
	v_lshl_add_u64 v[210:211], v[166:167], 0, s[18:19]
	global_load_lds_dwordx4 v[210:211], off
	v_mfma_f32_16x16x32_bf16 v[48:51], v[80:83], v[76:79], v[48:51]
	v_mfma_f32_16x16x32_bf16 v[52:55], v[84:87], v[76:79], v[52:55]
	v_mfma_f32_16x16x32_bf16 v[56:59], v[88:91], v[76:79], v[56:59]
	v_mfma_f32_16x16x32_bf16 v[60:63], v[92:95], v[76:79], v[60:63]
	s_waitcnt vmcnt(0) lgkmcnt(0)
	s_barrier
.LBB0_1462:
	ds_read_b128 v[64:67], v168 offset:32768
	ds_read_b128 v[68:71], v168 offset:34816
	ds_read_b128 v[72:75], v168 offset:36864
	ds_read_b128 v[76:79], v168 offset:38912
	ds_read_b128 v[80:83], v169 offset:32768
	ds_read_b128 v[84:87], v169 offset:34816
	ds_read_b128 v[88:91], v169 offset:36864
	ds_read_b128 v[92:95], v169 offset:38912
	s_add_i32 s4, s14, 2
	s_min_u32 s4, s4, 15
	s_lshl_b32 s18, s4, 7
	s_add_u32 m0, s101, 0x0
	v_lshl_add_u64 v[210:211], v[152:153], 0, s[18:19]
	global_load_lds_dwordx4 v[210:211], off
	s_add_u32 m0, s101, 0x4000
	v_lshl_add_u64 v[210:211], v[154:155], 0, s[18:19]
	global_load_lds_dwordx4 v[210:211], off
	ds_read_b128 v[128:131], v220 offset:32768
	ds_read_b128 v[132:135], v220 offset:34816
	ds_read_b128 v[136:139], v220 offset:36864
	ds_read_b128 v[140:143], v220 offset:38912
	ds_read_b128 v[192:195], v221 offset:32768
	ds_read_b128 v[196:199], v221 offset:34816
	ds_read_b128 v[200:203], v221 offset:36864
	ds_read_b128 v[204:207], v221 offset:38912
	v_mfma_f32_16x16x32_bf16 v[0:3], v[112:115], v[96:99], v[0:3]
	v_mfma_f32_16x16x32_bf16 v[4:7], v[116:119], v[96:99], v[4:7]
	s_add_u32 m0, s101, 0x1000
	v_lshl_add_u64 v[210:211], v[156:157], 0, s[18:19]
	global_load_lds_dwordx4 v[210:211], off
	v_mfma_f32_16x16x32_bf16 v[8:11], v[120:123], v[96:99], v[8:11]
	v_mfma_f32_16x16x32_bf16 v[12:15], v[124:127], v[96:99], v[12:15]
	s_add_u32 m0, s101, 0x5000
	v_lshl_add_u64 v[210:211], v[158:159], 0, s[18:19]
	global_load_lds_dwordx4 v[210:211], off
	v_mfma_f32_16x16x32_bf16 v[16:19], v[112:115], v[100:103], v[16:19]
	v_mfma_f32_16x16x32_bf16 v[20:23], v[116:119], v[100:103], v[20:23]
	s_add_u32 m0, s101, 0x2000
	v_lshl_add_u64 v[210:211], v[160:161], 0, s[18:19]
	global_load_lds_dwordx4 v[210:211], off
	v_mfma_f32_16x16x32_bf16 v[24:27], v[120:123], v[100:103], v[24:27]
	v_mfma_f32_16x16x32_bf16 v[28:31], v[124:127], v[100:103], v[28:31]
	s_add_u32 m0, s101, 0x6000
	v_lshl_add_u64 v[210:211], v[162:163], 0, s[18:19]
	global_load_lds_dwordx4 v[210:211], off
	v_mfma_f32_16x16x32_bf16 v[32:35], v[112:115], v[104:107], v[32:35]
	v_mfma_f32_16x16x32_bf16 v[36:39], v[116:119], v[104:107], v[36:39]
	s_add_u32 m0, s101, 0x3000
	v_lshl_add_u64 v[210:211], v[164:165], 0, s[18:19]
	global_load_lds_dwordx4 v[210:211], off
	v_mfma_f32_16x16x32_bf16 v[40:43], v[120:123], v[104:107], v[40:43]
	v_mfma_f32_16x16x32_bf16 v[44:47], v[124:127], v[104:107], v[44:47]
	s_add_u32 m0, s101, 0x7000
	v_lshl_add_u64 v[210:211], v[166:167], 0, s[18:19]
	global_load_lds_dwordx4 v[210:211], off
	v_mfma_f32_16x16x32_bf16 v[48:51], v[112:115], v[108:111], v[48:51]
	v_mfma_f32_16x16x32_bf16 v[52:55], v[116:119], v[108:111], v[52:55]
	v_mfma_f32_16x16x32_bf16 v[56:59], v[120:123], v[108:111], v[56:59]
	v_mfma_f32_16x16x32_bf16 v[60:63], v[124:127], v[108:111], v[60:63]
	s_waitcnt lgkmcnt(8)
	v_mfma_f32_16x16x32_bf16 v[0:3], v[80:83], v[64:67], v[0:3]
	v_mfma_f32_16x16x32_bf16 v[4:7], v[84:87], v[64:67], v[4:7]
	v_mfma_f32_16x16x32_bf16 v[8:11], v[88:91], v[64:67], v[8:11]
	v_mfma_f32_16x16x32_bf16 v[12:15], v[92:95], v[64:67], v[12:15]
	v_mfma_f32_16x16x32_bf16 v[16:19], v[80:83], v[68:71], v[16:19]
	v_mfma_f32_16x16x32_bf16 v[20:23], v[84:87], v[68:71], v[20:23]
	v_mfma_f32_16x16x32_bf16 v[24:27], v[88:91], v[68:71], v[24:27]
	v_mfma_f32_16x16x32_bf16 v[28:31], v[92:95], v[68:71], v[28:31]
	v_mfma_f32_16x16x32_bf16 v[32:35], v[80:83], v[72:75], v[32:35]
	v_mfma_f32_16x16x32_bf16 v[36:39], v[84:87], v[72:75], v[36:39]
	v_mfma_f32_16x16x32_bf16 v[40:43], v[88:91], v[72:75], v[40:43]
	v_mfma_f32_16x16x32_bf16 v[44:47], v[92:95], v[72:75], v[44:47]
	v_mfma_f32_16x16x32_bf16 v[48:51], v[80:83], v[76:79], v[48:51]
	v_mfma_f32_16x16x32_bf16 v[52:55], v[84:87], v[76:79], v[52:55]
	v_mfma_f32_16x16x32_bf16 v[56:59], v[88:91], v[76:79], v[56:59]
	v_mfma_f32_16x16x32_bf16 v[60:63], v[92:95], v[76:79], v[60:63]
	s_waitcnt vmcnt(0) lgkmcnt(0)
	s_barrier
; #define SB_ __builtin_amdgcn_sched_barrier(0)
; template <bool SWAP, bool HALF>
; DI void gemm_mainloop(const GemmDesc& d, int m0, int n0, bf16_t* smem, f32x16 (&acc)[2][2], int dry) {
;     ...
;   auto stage = [&](int cur, u32x4 (&ran)[4], u32x4 (&rbn)[4], int ks) {
;     ldf(cur, 1, 1); SB_;
;     mma(0); SB_;
;     ldf(cur, 2, 0); SB_;
;     lw(ran, rbn, cur ^ 1);
;     gl(ran, rbn, (ks + 3 < nk) ? ks + 3 : nk - 1);
;     SB_;
;     mma(1); SB_;
;     __syncthreads();
;     ldf(cur, 3, 1); SB_;
;     mma(0); SB_;
;     ldf(cur ^ 1, 0, 0);
;     SB_;
;     mma(1); SB_;
;     __syncthreads();
;   };
;   gl(ra0, rb0, 0);
;   gl(ra1, rb1, 1);
;   lw(ra0, rb0, 0);
;   gl(ra0, rb0, 2);
;   __syncthreads();
;   ldf(0, 0, 0);
; #pragma unroll 1
;   for (int ks = 0; ks < nk; ks += 2) {
;     stage(0, ra1, rb1, ks);
;     stage(1, ra0, rb0, ks + 1);
;   }
	ds_read_b128 v[64:67], v168 offset:0
	ds_read_b128 v[68:71], v168 offset:2048
	ds_read_b128 v[72:75], v168 offset:4096
	ds_read_b128 v[76:79], v168 offset:6144
	ds_read_b128 v[80:83], v169 offset:0
	ds_read_b128 v[84:87], v169 offset:2048
	ds_read_b128 v[88:91], v169 offset:4096
	ds_read_b128 v[92:95], v169 offset:6144
	s_add_i32 s4, s14, 3
	s_min_u32 s4, s4, 15
	s_lshl_b32 s18, s4, 7
	s_add_u32 m0, s101, 0x8000
	v_lshl_add_u64 v[210:211], v[152:153], 0, s[18:19]
	global_load_lds_dwordx4 v[210:211], off
	s_add_u32 m0, s101, 0xc000
	v_lshl_add_u64 v[210:211], v[154:155], 0, s[18:19]
	global_load_lds_dwordx4 v[210:211], off
	ds_read_b128 v[96:99], v220 offset:0
	ds_read_b128 v[100:103], v220 offset:2048
	ds_read_b128 v[104:107], v220 offset:4096
	ds_read_b128 v[108:111], v220 offset:6144
	ds_read_b128 v[112:115], v221 offset:0
	ds_read_b128 v[116:119], v221 offset:2048
	ds_read_b128 v[120:123], v221 offset:4096
	ds_read_b128 v[124:127], v221 offset:6144
	v_mfma_f32_16x16x32_bf16 v[0:3], v[192:195], v[128:131], v[0:3]
	v_mfma_f32_16x16x32_bf16 v[4:7], v[196:199], v[128:131], v[4:7]
	s_add_u32 m0, s101, 0x9000
	v_lshl_add_u64 v[210:211], v[156:157], 0, s[18:19]
	global_load_lds_dwordx4 v[210:211], off
	v_mfma_f32_16x16x32_bf16 v[8:11], v[200:203], v[128:131], v[8:11]
	v_mfma_f32_16x16x32_bf16 v[12:15], v[204:207], v[128:131], v[12:15]
	s_add_u32 m0, s101, 0xd000
	v_lshl_add_u64 v[210:211], v[158:159], 0, s[18:19]
	global_load_lds_dwordx4 v[210:211], off
	v_mfma_f32_16x16x32_bf16 v[16:19], v[192:195], v[132:135], v[16:19]
	v_mfma_f32_16x16x32_bf16 v[20:23], v[196:199], v[132:135], v[20:23]
	s_add_u32 m0, s101, 0xa000
	v_lshl_add_u64 v[210:211], v[160:161], 0, s[18:19]
	global_load_lds_dwordx4 v[210:211], off
	v_mfma_f32_16x16x32_bf16 v[24:27], v[200:203], v[132:135], v[24:27]
	v_mfma_f32_16x16x32_bf16 v[28:31], v[204:207], v[132:135], v[28:31]
	s_add_u32 m0, s101, 0xe000
	v_lshl_add_u64 v[210:211], v[162:163], 0, s[18:19]
	global_load_lds_dwordx4 v[210:211], off
	v_mfma_f32_16x16x32_bf16 v[32:35], v[192:195], v[136:139], v[32:35]
	v_mfma_f32_16x16x32_bf16 v[36:39], v[196:199], v[136:139], v[36:39]
	s_add_u32 m0, s101, 0xb000
	v_lshl_add_u64 v[210:211], v[164:165], 0, s[18:19]
	global_load_lds_dwordx4 v[210:211], off
	v_mfma_f32_16x16x32_bf16 v[40:43], v[200:203], v[136:139], v[40:43]
	v_mfma_f32_16x16x32_bf16 v[44:47], v[204:207], v[136:139], v[44:47]
	s_add_u32 m0, s101, 0xf000
	v_lshl_add_u64 v[210:211], v[166:167], 0, s[18:19]
	global_load_lds_dwordx4 v[210:211], off
	v_mfma_f32_16x16x32_bf16 v[48:51], v[192:195], v[140:143], v[48:51]
	v_mfma_f32_16x16x32_bf16 v[52:55], v[196:199], v[140:143], v[52:55]
	v_mfma_f32_16x16x32_bf16 v[56:59], v[200:203], v[140:143], v[56:59]
	v_mfma_f32_16x16x32_bf16 v[60:63], v[204:207], v[140:143], v[60:63]
	s_waitcnt lgkmcnt(8)
	v_mfma_f32_16x16x32_bf16 v[0:3], v[80:83], v[64:67], v[0:3]
	v_mfma_f32_16x16x32_bf16 v[4:7], v[84:87], v[64:67], v[4:7]
	v_mfma_f32_16x16x32_bf16 v[8:11], v[88:91], v[64:67], v[8:11]
	v_mfma_f32_16x16x32_bf16 v[12:15], v[92:95], v[64:67], v[12:15]
	v_mfma_f32_16x16x32_bf16 v[16:19], v[80:83], v[68:71], v[16:19]
	v_mfma_f32_16x16x32_bf16 v[20:23], v[84:87], v[68:71], v[20:23]
	v_mfma_f32_16x16x32_bf16 v[24:27], v[88:91], v[68:71], v[24:27]
	v_mfma_f32_16x16x32_bf16 v[28:31], v[92:95], v[68:71], v[28:31]
	v_mfma_f32_16x16x32_bf16 v[32:35], v[80:83], v[72:75], v[32:35]
	v_mfma_f32_16x16x32_bf16 v[36:39], v[84:87], v[72:75], v[36:39]
	v_mfma_f32_16x16x32_bf16 v[40:43], v[88:91], v[72:75], v[40:43]
	v_mfma_f32_16x16x32_bf16 v[44:47], v[92:95], v[72:75], v[44:47]
	v_mfma_f32_16x16x32_bf16 v[48:51], v[80:83], v[76:79], v[48:51]
	v_mfma_f32_16x16x32_bf16 v[52:55], v[84:87], v[76:79], v[52:55]
	v_mfma_f32_16x16x32_bf16 v[56:59], v[88:91], v[76:79], v[56:59]
	v_mfma_f32_16x16x32_bf16 v[60:63], v[92:95], v[76:79], v[60:63]
	s_add_i32 s4, s14, 2
	s_cmp_lt_u32 s14, 12
	s_mov_b32 s14, s4
	s_waitcnt vmcnt(0) lgkmcnt(0)
	s_barrier
	s_cbranch_scc1 .LBB0_1462
; DI float ssq_f(u64 v) { return (float)v * (1.f / 1048576.f); }
; #define SB_ __builtin_amdgcn_sched_barrier(0)
; template <bool SWAP, bool HALF>
; DI void gemm_mainloop(const GemmDesc& d, int m0, int n0, bf16_t* smem, f32x16 (&acc)[2][2], int dry) {
;     ...
;     ldf(cur, 3, 1); SB_;
;     mma(0); SB_;
;     ldf(cur ^ 1, 0, 0);
;     SB_;
;     mma(1); SB_;
;     __syncthreads();
;   };
;   gl(ra0, rb0, 0);
;   gl(ra1, rb1, 1);
;   lw(ra0, rb0, 0);
;   gl(ra0, rb0, 2);
;   __syncthreads();
;   ldf(0, 0, 0);
; #pragma unroll 1
;   for (int ks = 0; ks < nk; ks += 2) {
;     stage(0, ra1, rb1, ks);
;     stage(1, ra0, rb0, ks + 1);
;   }
; DI void gemm_tile(const GemmDesc& d, int m0, int n0, bf16_t* smem, int dry) {
;     ...
;   } else if (t < 128) {
;     rs_s[t] = rsqrtf(ssq_f(myss) * d.inv_dim + EPS);
	ds_read_b128 v[64:67], v168 offset:32768
	ds_read_b128 v[68:71], v168 offset:34816
	ds_read_b128 v[72:75], v168 offset:36864
	ds_read_b128 v[76:79], v168 offset:38912
	ds_read_b128 v[80:83], v169 offset:32768
	ds_read_b128 v[84:87], v169 offset:34816
	ds_read_b128 v[88:91], v169 offset:36864
	ds_read_b128 v[92:95], v169 offset:38912
	ds_read_b128 v[128:131], v220 offset:32768
	ds_read_b128 v[132:135], v220 offset:34816
	ds_read_b128 v[136:139], v220 offset:36864
	ds_read_b128 v[140:143], v220 offset:38912
	ds_read_b128 v[192:195], v221 offset:32768
	ds_read_b128 v[196:199], v221 offset:34816
	ds_read_b128 v[200:203], v221 offset:36864
	ds_read_b128 v[204:207], v221 offset:38912
	v_mfma_f32_16x16x32_bf16 v[0:3], v[112:115], v[96:99], v[0:3]
	v_mfma_f32_16x16x32_bf16 v[4:7], v[116:119], v[96:99], v[4:7]
	v_mfma_f32_16x16x32_bf16 v[8:11], v[120:123], v[96:99], v[8:11]
	v_mfma_f32_16x16x32_bf16 v[12:15], v[124:127], v[96:99], v[12:15]
	v_mfma_f32_16x16x32_bf16 v[16:19], v[112:115], v[100:103], v[16:19]
	v_mfma_f32_16x16x32_bf16 v[20:23], v[116:119], v[100:103], v[20:23]
	v_mfma_f32_16x16x32_bf16 v[24:27], v[120:123], v[100:103], v[24:27]
	v_mfma_f32_16x16x32_bf16 v[28:31], v[124:127], v[100:103], v[28:31]
	v_mfma_f32_16x16x32_bf16 v[32:35], v[112:115], v[104:107], v[32:35]
	v_mfma_f32_16x16x32_bf16 v[36:39], v[116:119], v[104:107], v[36:39]
	v_mfma_f32_16x16x32_bf16 v[40:43], v[120:123], v[104:107], v[40:43]
	v_mfma_f32_16x16x32_bf16 v[44:47], v[124:127], v[104:107], v[44:47]
	v_mfma_f32_16x16x32_bf16 v[48:51], v[112:115], v[108:111], v[48:51]
	v_mfma_f32_16x16x32_bf16 v[52:55], v[116:119], v[108:111], v[52:55]
	v_mfma_f32_16x16x32_bf16 v[56:59], v[120:123], v[108:111], v[56:59]
	v_mfma_f32_16x16x32_bf16 v[60:63], v[124:127], v[108:111], v[60:63]
	s_waitcnt lgkmcnt(8)
	v_mfma_f32_16x16x32_bf16 v[0:3], v[80:83], v[64:67], v[0:3]
	v_mfma_f32_16x16x32_bf16 v[4:7], v[84:87], v[64:67], v[4:7]
	v_mfma_f32_16x16x32_bf16 v[8:11], v[88:91], v[64:67], v[8:11]
	v_mfma_f32_16x16x32_bf16 v[12:15], v[92:95], v[64:67], v[12:15]
	v_mfma_f32_16x16x32_bf16 v[16:19], v[80:83], v[68:71], v[16:19]
	v_mfma_f32_16x16x32_bf16 v[20:23], v[84:87], v[68:71], v[20:23]
	v_mfma_f32_16x16x32_bf16 v[24:27], v[88:91], v[68:71], v[24:27]
	v_mfma_f32_16x16x32_bf16 v[28:31], v[92:95], v[68:71], v[28:31]
	v_mfma_f32_16x16x32_bf16 v[32:35], v[80:83], v[72:75], v[32:35]
	v_mfma_f32_16x16x32_bf16 v[36:39], v[84:87], v[72:75], v[36:39]
	v_mfma_f32_16x16x32_bf16 v[40:43], v[88:91], v[72:75], v[40:43]
	v_mfma_f32_16x16x32_bf16 v[44:47], v[92:95], v[72:75], v[44:47]
	v_mfma_f32_16x16x32_bf16 v[48:51], v[80:83], v[76:79], v[48:51]
	v_mfma_f32_16x16x32_bf16 v[52:55], v[84:87], v[76:79], v[52:55]
	v_mfma_f32_16x16x32_bf16 v[56:59], v[88:91], v[76:79], v[56:59]
	v_mfma_f32_16x16x32_bf16 v[60:63], v[92:95], v[76:79], v[60:63]
	s_waitcnt lgkmcnt(0)
	s_barrier
	v_mfma_f32_16x16x32_bf16 v[0:3], v[192:195], v[128:131], v[0:3]
	v_mfma_f32_16x16x32_bf16 v[4:7], v[196:199], v[128:131], v[4:7]
	v_mfma_f32_16x16x32_bf16 v[8:11], v[200:203], v[128:131], v[8:11]
	v_mfma_f32_16x16x32_bf16 v[12:15], v[204:207], v[128:131], v[12:15]
	v_mfma_f32_16x16x32_bf16 v[16:19], v[192:195], v[132:135], v[16:19]
	v_mfma_f32_16x16x32_bf16 v[20:23], v[196:199], v[132:135], v[20:23]
	v_mfma_f32_16x16x32_bf16 v[24:27], v[200:203], v[132:135], v[24:27]
	v_mfma_f32_16x16x32_bf16 v[28:31], v[204:207], v[132:135], v[28:31]
	v_mfma_f32_16x16x32_bf16 v[32:35], v[192:195], v[136:139], v[32:35]
	v_mfma_f32_16x16x32_bf16 v[36:39], v[196:199], v[136:139], v[36:39]
	v_mfma_f32_16x16x32_bf16 v[40:43], v[200:203], v[136:139], v[40:43]
	v_mfma_f32_16x16x32_bf16 v[44:47], v[204:207], v[136:139], v[44:47]
	v_mfma_f32_16x16x32_bf16 v[48:51], v[192:195], v[140:143], v[48:51]
	v_mfma_f32_16x16x32_bf16 v[52:55], v[196:199], v[140:143], v[52:55]
	v_mfma_f32_16x16x32_bf16 v[56:59], v[200:203], v[140:143], v[56:59]
	v_mfma_f32_16x16x32_bf16 v[60:63], v[204:207], v[140:143], v[60:63]
	s_and_saveexec_b64 s[4:5], vcc
	s_cbranch_execz .LBB0_1465
	s_mov_b32 s14, 0x800000
	s_waitcnt vmcnt(15)
	v_mul_f32_e32 v64, 0x4b800000, v170
	v_cmp_gt_f32_e32 vcc, s14, v170
	s_nop 1
	v_cndmask_b32_e32 v64, v170, v64, vcc
	v_rsq_f32_e32 v64, v64
	s_nop 0
	v_mul_f32_e32 v65, 0x45800000, v64
	v_cndmask_b32_e32 v64, v64, v65, vcc
	v_lshl_add_u32 v65, v150, 2, v181
	ds_write_b32 v65, v64

; DI int otid() { int t = threadIdx.x; asm volatile("" : "+v"(t)); return t; }
; template <bool SWAP, bool HALF>
; DI void gemm_mainloop(const GemmDesc& d, int m0, int n0, bf16_t* smem, f32x16 (&acc)[2][2], int dry) {
;   const int t = otid(), lane = t & 63, w = t >> 6, wm = w >> 1, wn = w & 1, r = lane & 31, hh = lane >> 5;
;   const int lrow = t >> 3, lkc = t & 7;
;   const bf16_t* ap[4]; const bf16_t* bp[4];
; #pragma unroll
;   for (int i = 0; i < 4; ++i) {
;     int am = m0 + lrow + 32 * i; am = am < M ? am : M - 1;
;     ap[i] = d.A + (size_t)am * d.lda + lkc * 8 + (d.a_grp ? (n0 / d.a_grp) * d.a_grp : 0);
;     bp[i] = d.Bt + (size_t)(n0 + lrow + 32 * i) * d.ldb + lkc * 8;
;   }
; #pragma unroll
;   for (int a = 0; a < 2; ++a)
; #pragma unroll
;     for (int b = 0; b < 2; ++b)
; #pragma unroll
;       for (int i = 0; i < 16; ++i) acc[a][b][i] = 0.f;
;   u32x4 ra0[4], rb0[4], ra1[4], rb1[4];
;   const int nk = d.K >> 6;
;   const int lds_w = lrow * LST + lkc * 8;
;     ...
;   gl(ra0, rb0, 0);
;   gl(ra1, rb1, 1);
;   lw(ra0, rb0, 0);
;   gl(ra0, rb0, 2);
;   __syncthreads();
;   ldf(0, 0, 0);
.LBB0_1527:
	s_lshr_b32 s1, s12, 3
	s_and_b32 s1, s1, 0xffffff8
	v_readlane_b32 s4, v228, 38
	s_sub_i32 s4, s4, s1
	s_min_i32 s4, s4, 8
	s_abs_i32 s5, s4
	v_cvt_f32_u32_e32 v0, s5
	s_sub_i32 s14, 0, s5
	s_lshl_b32 s10, s1, 3
	s_sub_i32 s10, s12, s10
	v_rcp_iflag_f32_e32 v0, v0
	s_abs_i32 s13, s10
	s_xor_b32 s11, s10, s4
	s_ashr_i32 s11, s11, 31
	v_mul_f32_e32 v0, 0x4f7ffffe, v0
	v_cvt_u32_f32_e32 v0, v0
	v_mov_b32_e32 v150, v172
	v_mov_b32_e32 v32, v172
	v_readfirstlane_b32 s15, v0
	s_mul_i32 s14, s14, s15
	s_mul_hi_u32 s14, s15, s14
	s_add_i32 s15, s15, s14
	s_mul_hi_u32 s14, s13, s15
	s_mul_i32 s15, s14, s5
	s_sub_i32 s13, s13, s15
	s_add_i32 s16, s14, 1
	s_sub_i32 s15, s13, s5
	s_cmp_ge_u32 s13, s5
	s_cselect_b32 s14, s16, s14
	s_cselect_b32 s13, s15, s13
	s_add_i32 s15, s14, 1
	s_cmp_ge_u32 s13, s5
	s_cselect_b32 s5, s15, s14
	s_xor_b32 s5, s5, s11
	s_sub_i32 s11, s5, s11
	s_mul_i32 s4, s11, s4
	s_sub_i32 s4, s10, s4
	s_add_i32 s1, s1, s4
	s_lshl_b32 s1, s1, 10
	s_or_b32 s13, s1, s29
	v_lshlrev_b32_e32 v0, 3, v32
	v_ashrrev_i32_e32 v8, 3, v32
	v_and_b32_e32 v33, 56, v0
	v_add_u32_e32 v9, s13, v8
	v_lshlrev_b32_e32 v144, 1, v33
	v_lshl_add_u64 v[4:5], s[68:69], 0, v[144:145]
	v_min_i32_e32 v0, 0x803f, v9
	v_mad_i64_i32 v[152:153], s[4:5], v0, s26, v[4:5]
	s_lshl_b32 s4, s11, 7
	v_min_i32_e32 v11, 0x801f, v9
	v_add_u32_e32 v10, s4, v8
	v_add_u32_e32 v11, 32, v11
	v_lshl_add_u64 v[6:7], s[6:7], 0, v[144:145]
	v_mad_i64_i32 v[156:157], s[10:11], v11, s26, v[4:5]
	v_add_u32_e32 v11, 32, v10
	v_mad_i64_i32 v[158:159], s[10:11], v11, s26, v[6:7]
	v_min_i32_e32 v11, 0x7fff, v9
	v_min_i32_e32 v9, 0x7fdf, v9
	v_add_u32_e32 v11, 64, v11
	v_add_u32_e32 v9, 0x60, v9
	v_mad_i64_i32 v[160:161], s[10:11], v11, s26, v[4:5]
	v_add_u32_e32 v11, 64, v10
	v_mad_i64_i32 v[164:165], s[10:11], v9, s26, v[4:5]
	v_add_u32_e32 v4, 0x60, v10
	s_movk_i32 s5, 0x48
	s_mov_b32 s1, 0
	v_mad_i64_i32 v[154:155], s[10:11], v10, s26, v[6:7]
	v_mad_i64_i32 v[162:163], s[10:11], v11, s26, v[6:7]
	v_mad_i64_i32 v[166:167], s[10:11], v4, s26, v[6:7]
	v_and_b32_e32 v34, 31, v32
	v_mul_lo_u32 v35, v8, s5
	v_add_lshl_u32 v144, v35, v33, 1
	s_waitcnt vmcnt(15)
	s_waitcnt vmcnt(14)
	s_waitcnt vmcnt(13)
	s_waitcnt vmcnt(12)
	s_waitcnt vmcnt(11)
	s_waitcnt vmcnt(10)
	s_waitcnt vmcnt(9)
	s_waitcnt vmcnt(8)
	v_lshrrev_b32_e32 v0, 1, v32
	v_and_or_b32 v1, v0, s72, v34
	v_and_b32_e32 v0, 16, v0
	s_movk_i32 s5, 0x90
	v_mad_u64_u32 v[168:169], s[10:11], v1, s5, v[0:1]
	v_and_b32_e32 v1, 0x5f, v32
	v_mul_u32_u24_e32 v1, 0x48, v1
	v_lshl_add_u32 v169, v1, 1, v0
	v_bfe_u32 v212, v172, 4, 3
	v_lshlrev_b32_e32 v212, 4, v212
	v_xor_b32_e32 v152, v152, v212
	v_xor_b32_e32 v154, v154, v212
	v_xor_b32_e32 v156, v156, v212
	v_xor_b32_e32 v158, v158, v212
	v_xor_b32_e32 v160, v160, v212
	v_xor_b32_e32 v162, v162, v212
	v_xor_b32_e32 v164, v164, v212
	v_xor_b32_e32 v166, v166, v212
	v_lshrrev_b32_e32 v213, 6, v172
	s_nop 1
	v_readfirstlane_b32 s101, v213
	s_lshl_b32 s101, s101, 10
	s_add_u32 m0, s101, 0x0
	s_nop 0
	global_load_lds_dwordx4 v[152:153], off
	s_add_u32 m0, s101, 0x4000
	s_nop 0
	global_load_lds_dwordx4 v[154:155], off
	s_add_u32 m0, s101, 0x1000
	s_nop 0
	global_load_lds_dwordx4 v[156:157], off
	s_add_u32 m0, s101, 0x5000
	s_nop 0
	global_load_lds_dwordx4 v[158:159], off
	s_add_u32 m0, s101, 0x2000
	s_nop 0
	global_load_lds_dwordx4 v[160:161], off
	s_add_u32 m0, s101, 0x6000
	s_nop 0
	global_load_lds_dwordx4 v[162:163], off
	s_add_u32 m0, s101, 0x3000
	s_nop 0
	global_load_lds_dwordx4 v[164:165], off
	s_add_u32 m0, s101, 0x7000
	s_nop 0
	global_load_lds_dwordx4 v[166:167], off
	v_and_b32_e32 v212, 15, v172
	v_bfe_u32 v213, v172, 4, 2
	v_lshrrev_b32_e32 v214, 1, v212
	v_xor_b32_e32 v213, v213, v214
	v_lshlrev_b32_e32 v213, 4, v213
	v_lshl_or_b32 v212, v212, 7, v213
	v_lshrrev_b32_e32 v214, 7, v172
	v_lshl_add_u32 v168, v214, 13, v212
	v_bfe_u32 v214, v172, 6, 1
	v_lshl_add_u32 v169, v214, 13, v212
	v_add_u32_e32 v169, 0x4000, v169
	v_xor_b32_e32 v220, 64, v168
	v_xor_b32_e32 v221, 64, v169
	s_waitcnt vmcnt(0) lgkmcnt(0)
	s_barrier
	v_mov_b32_e32 v0, 0
	v_add_u32_e32 v170, 0x9000, v144
	v_mov_b32_e32 v1, v0
	v_mov_b32_e32 v2, v0
	v_mov_b32_e32 v3, v0
	v_mov_b32_e32 v4, v0
	v_mov_b32_e32 v5, v0
	v_mov_b32_e32 v6, v0
	v_mov_b32_e32 v7, v0
	v_mov_b32_e32 v8, v0
	v_mov_b32_e32 v9, v0
	v_mov_b32_e32 v10, v0
	v_mov_b32_e32 v11, v0
	v_mov_b32_e32 v12, v0
	v_mov_b32_e32 v13, v0
	v_mov_b32_e32 v14, v0
	v_mov_b32_e32 v15, v0
	v_mov_b32_e32 v16, v0
	v_mov_b32_e32 v17, v0
	v_mov_b32_e32 v18, v0
	v_mov_b32_e32 v19, v0
	v_mov_b32_e32 v20, v0
	v_mov_b32_e32 v21, v0
	v_mov_b32_e32 v22, v0
	v_mov_b32_e32 v23, v0
	v_mov_b32_e32 v24, v0
	v_mov_b32_e32 v25, v0
	v_mov_b32_e32 v26, v0
	v_mov_b32_e32 v27, v0
	v_mov_b32_e32 v28, v0
	v_mov_b32_e32 v29, v0
	v_mov_b32_e32 v30, v0
	v_mov_b32_e32 v31, v0
	v_mov_b32_e32 v32, v0
	v_mov_b32_e32 v33, v0
	v_mov_b32_e32 v34, v0
	v_mov_b32_e32 v35, v0
	v_mov_b32_e32 v36, v0
	v_mov_b32_e32 v37, v0
	v_mov_b32_e32 v38, v0
	v_mov_b32_e32 v39, v0
	v_mov_b32_e32 v40, v0
	v_mov_b32_e32 v41, v0
	v_mov_b32_e32 v42, v0
	v_mov_b32_e32 v43, v0
	v_mov_b32_e32 v44, v0
	v_mov_b32_e32 v45, v0
	v_mov_b32_e32 v46, v0
	v_mov_b32_e32 v47, v0
	v_mov_b32_e32 v48, v0
	v_mov_b32_e32 v49, v0
	v_mov_b32_e32 v50, v0
	v_mov_b32_e32 v51, v0
	v_mov_b32_e32 v52, v0
	v_mov_b32_e32 v53, v0
	v_mov_b32_e32 v54, v0
	v_mov_b32_e32 v55, v0
	v_mov_b32_e32 v56, v0
	v_mov_b32_e32 v57, v0
	v_mov_b32_e32 v58, v0
	v_mov_b32_e32 v59, v0
	v_mov_b32_e32 v60, v0
	v_mov_b32_e32 v61, v0
	v_mov_b32_e32 v62, v0
	v_mov_b32_e32 v63, v0
	ds_read_b128 v[64:67], v168 offset:0
	ds_read_b128 v[68:71], v168 offset:2048
	ds_read_b128 v[72:75], v168 offset:4096
	ds_read_b128 v[76:79], v168 offset:6144
	ds_read_b128 v[80:83], v169 offset:0
	ds_read_b128 v[84:87], v169 offset:2048
	ds_read_b128 v[88:91], v169 offset:4096
	ds_read_b128 v[92:95], v169 offset:6144
	s_add_i32 s5, s1, 1
	s_min_u32 s5, s5, 43
	s_lshl_b32 s18, s5, 7
	s_add_u32 m0, s101, 0x8000
	v_lshl_add_u64 v[210:211], v[152:153], 0, s[18:19]
	global_load_lds_dwordx4 v[210:211], off
	s_add_u32 m0, s101, 0xc000
	v_lshl_add_u64 v[210:211], v[154:155], 0, s[18:19]
	global_load_lds_dwordx4 v[210:211], off
	ds_read_b128 v[96:99], v220 offset:0
	ds_read_b128 v[100:103], v220 offset:2048
	ds_read_b128 v[104:107], v220 offset:4096
	ds_read_b128 v[108:111], v220 offset:6144
	ds_read_b128 v[112:115], v221 offset:0
	ds_read_b128 v[116:119], v221 offset:2048
	ds_read_b128 v[120:123], v221 offset:4096
	ds_read_b128 v[124:127], v221 offset:6144
	s_waitcnt lgkmcnt(8)
; #define MFMA32(a, b, c) __builtin_amdgcn_mfma_f32_32x32x16_bf16((a), (b), (c), 0, 0, 0)
; #define SB_ __builtin_amdgcn_sched_barrier(0)
; template <bool SWAP, bool HALF>
; DI void gemm_mainloop(const GemmDesc& d, int m0, int n0, bf16_t* smem, f32x16 (&acc)[2][2], int dry) {
;     ...
;   auto mma = [&](int set) {
; #pragma unroll
;     for (int a = 0; a < 2; ++a)
; #pragma unroll
;       for (int b = 0; b < (HALF ? 1 : 2); ++b) {
;         if (SWAP) acc[a][b] = MFMA32(fb[set][b], fa[set][a], acc[a][b]);
;         else      acc[a][b] = MFMA32(fa[set][a], fb[set][b], acc[a][b]);
;       }
;   };
;     ...
;   auto stage = [&](int cur, u32x4 (&ran)[4], u32x4 (&rbn)[4], int ks) {
;     ldf(cur, 1, 1); SB_;
;     mma(0); SB_;
;     ldf(cur, 2, 0); SB_;
;     lw(ran, rbn, cur ^ 1);
;     gl(ran, rbn, (ks + 3 < nk) ? ks + 3 : nk - 1);
;     SB_;
;     mma(1); SB_;
;     __syncthreads();
;     ldf(cur, 3, 1); SB_;
;     mma(0); SB_;
;     ldf(cur ^ 1, 0, 0);
;     SB_;
;     mma(1); SB_;
;     __syncthreads();
;   };
	v_mfma_f32_16x16x32_bf16 v[0:3], v[80:83], v[64:67], v[0:3]
	v_mfma_f32_16x16x32_bf16 v[4:7], v[84:87], v[64:67], v[4:7]
	s_add_u32 m0, s101, 0x9000
	v_lshl_add_u64 v[210:211], v[156:157], 0, s[18:19]
	global_load_lds_dwordx4 v[210:211], off
	v_mfma_f32_16x16x32_bf16 v[8:11], v[88:91], v[64:67], v[8:11]
	v_mfma_f32_16x16x32_bf16 v[12:15], v[92:95], v[64:67], v[12:15]
	s_add_u32 m0, s101, 0xd000
	v_lshl_add_u64 v[210:211], v[158:159], 0, s[18:19]
	global_load_lds_dwordx4 v[210:211], off
	v_mfma_f32_16x16x32_bf16 v[16:19], v[80:83], v[68:71], v[16:19]
	v_mfma_f32_16x16x32_bf16 v[20:23], v[84:87], v[68:71], v[20:23]
	s_add_u32 m0, s101, 0xa000
	v_lshl_add_u64 v[210:211], v[160:161], 0, s[18:19]
	global_load_lds_dwordx4 v[210:211], off
	v_mfma_f32_16x16x32_bf16 v[24:27], v[88:91], v[68:71], v[24:27]
	v_mfma_f32_16x16x32_bf16 v[28:31], v[92:95], v[68:71], v[28:31]
	s_add_u32 m0, s101, 0xe000
	v_lshl_add_u64 v[210:211], v[162:163], 0, s[18:19]
	global_load_lds_dwordx4 v[210:211], off
	v_mfma_f32_16x16x32_bf16 v[32:35], v[80:83], v[72:75], v[32:35]
	v_mfma_f32_16x16x32_bf16 v[36:39], v[84:87], v[72:75], v[36:39]
	s_add_u32 m0, s101, 0xb000
	v_lshl_add_u64 v[210:211], v[164:165], 0, s[18:19]
	global_load_lds_dwordx4 v[210:211], off
	v_mfma_f32_16x16x32_bf16 v[40:43], v[88:91], v[72:75], v[40:43]
	v_mfma_f32_16x16x32_bf16 v[44:47], v[92:95], v[72:75], v[44:47]
	s_add_u32 m0, s101, 0xf000
	v_lshl_add_u64 v[210:211], v[166:167], 0, s[18:19]
	global_load_lds_dwordx4 v[210:211], off
	v_mfma_f32_16x16x32_bf16 v[48:51], v[80:83], v[76:79], v[48:51]
	v_mfma_f32_16x16x32_bf16 v[52:55], v[84:87], v[76:79], v[52:55]
	v_mfma_f32_16x16x32_bf16 v[56:59], v[88:91], v[76:79], v[56:59]
	v_mfma_f32_16x16x32_bf16 v[60:63], v[92:95], v[76:79], v[60:63]
	s_waitcnt vmcnt(0) lgkmcnt(0)
	s_barrier
.LBB0_1528:
	ds_read_b128 v[64:67], v168 offset:32768
	ds_read_b128 v[68:71], v168 offset:34816
	ds_read_b128 v[72:75], v168 offset:36864
	ds_read_b128 v[76:79], v168 offset:38912
	ds_read_b128 v[80:83], v169 offset:32768
	ds_read_b128 v[84:87], v169 offset:34816
	ds_read_b128 v[88:91], v169 offset:36864
	ds_read_b128 v[92:95], v169 offset:38912
	s_add_i32 s5, s1, 2
	s_min_u32 s5, s5, 43
	s_lshl_b32 s18, s5, 7
	s_add_u32 m0, s101, 0x0
	v_lshl_add_u64 v[210:211], v[152:153], 0, s[18:19]
	global_load_lds_dwordx4 v[210:211], off
	s_add_u32 m0, s101, 0x4000
	v_lshl_add_u64 v[210:211], v[154:155], 0, s[18:19]
	global_load_lds_dwordx4 v[210:211], off
	ds_read_b128 v[128:131], v220 offset:32768
	ds_read_b128 v[132:135], v220 offset:34816
	ds_read_b128 v[136:139], v220 offset:36864
	ds_read_b128 v[140:143], v220 offset:38912
	ds_read_b128 v[192:195], v221 offset:32768
	ds_read_b128 v[196:199], v221 offset:34816
	ds_read_b128 v[200:203], v221 offset:36864
	ds_read_b128 v[204:207], v221 offset:38912
	v_mfma_f32_16x16x32_bf16 v[0:3], v[112:115], v[96:99], v[0:3]
	v_mfma_f32_16x16x32_bf16 v[4:7], v[116:119], v[96:99], v[4:7]
	s_add_u32 m0, s101, 0x1000
	v_lshl_add_u64 v[210:211], v[156:157], 0, s[18:19]
	global_load_lds_dwordx4 v[210:211], off
	v_mfma_f32_16x16x32_bf16 v[8:11], v[120:123], v[96:99], v[8:11]
	v_mfma_f32_16x16x32_bf16 v[12:15], v[124:127], v[96:99], v[12:15]
	s_add_u32 m0, s101, 0x5000
	v_lshl_add_u64 v[210:211], v[158:159], 0, s[18:19]
	global_load_lds_dwordx4 v[210:211], off
	v_mfma_f32_16x16x32_bf16 v[16:19], v[112:115], v[100:103], v[16:19]
	v_mfma_f32_16x16x32_bf16 v[20:23], v[116:119], v[100:103], v[20:23]
	s_add_u32 m0, s101, 0x2000
	v_lshl_add_u64 v[210:211], v[160:161], 0, s[18:19]
	global_load_lds_dwordx4 v[210:211], off
	v_mfma_f32_16x16x32_bf16 v[24:27], v[120:123], v[100:103], v[24:27]
	v_mfma_f32_16x16x32_bf16 v[28:31], v[124:127], v[100:103], v[28:31]
	s_add_u32 m0, s101, 0x6000
	v_lshl_add_u64 v[210:211], v[162:163], 0, s[18:19]
	global_load_lds_dwordx4 v[210:211], off
	v_mfma_f32_16x16x32_bf16 v[32:35], v[112:115], v[104:107], v[32:35]
	v_mfma_f32_16x16x32_bf16 v[36:39], v[116:119], v[104:107], v[36:39]
	s_add_u32 m0, s101, 0x3000
	v_lshl_add_u64 v[210:211], v[164:165], 0, s[18:19]
	global_load_lds_dwordx4 v[210:211], off
	v_mfma_f32_16x16x32_bf16 v[40:43], v[120:123], v[104:107], v[40:43]
	v_mfma_f32_16x16x32_bf16 v[44:47], v[124:127], v[104:107], v[44:47]
	s_add_u32 m0, s101, 0x7000
	v_lshl_add_u64 v[210:211], v[166:167], 0, s[18:19]
	global_load_lds_dwordx4 v[210:211], off
	v_mfma_f32_16x16x32_bf16 v[48:51], v[112:115], v[108:111], v[48:51]
	v_mfma_f32_16x16x32_bf16 v[52:55], v[116:119], v[108:111], v[52:55]
	v_mfma_f32_16x16x32_bf16 v[56:59], v[120:123], v[108:111], v[56:59]
	v_mfma_f32_16x16x32_bf16 v[60:63], v[124:127], v[108:111], v[60:63]
	s_waitcnt lgkmcnt(8)
	v_mfma_f32_16x16x32_bf16 v[0:3], v[80:83], v[64:67], v[0:3]
	v_mfma_f32_16x16x32_bf16 v[4:7], v[84:87], v[64:67], v[4:7]
	v_mfma_f32_16x16x32_bf16 v[8:11], v[88:91], v[64:67], v[8:11]
	v_mfma_f32_16x16x32_bf16 v[12:15], v[92:95], v[64:67], v[12:15]
	v_mfma_f32_16x16x32_bf16 v[16:19], v[80:83], v[68:71], v[16:19]
	v_mfma_f32_16x16x32_bf16 v[20:23], v[84:87], v[68:71], v[20:23]
	v_mfma_f32_16x16x32_bf16 v[24:27], v[88:91], v[68:71], v[24:27]
	v_mfma_f32_16x16x32_bf16 v[28:31], v[92:95], v[68:71], v[28:31]
	v_mfma_f32_16x16x32_bf16 v[32:35], v[80:83], v[72:75], v[32:35]
	v_mfma_f32_16x16x32_bf16 v[36:39], v[84:87], v[72:75], v[36:39]
	v_mfma_f32_16x16x32_bf16 v[40:43], v[88:91], v[72:75], v[40:43]
	v_mfma_f32_16x16x32_bf16 v[44:47], v[92:95], v[72:75], v[44:47]
	v_mfma_f32_16x16x32_bf16 v[48:51], v[80:83], v[76:79], v[48:51]
	v_mfma_f32_16x16x32_bf16 v[52:55], v[84:87], v[76:79], v[52:55]
	v_mfma_f32_16x16x32_bf16 v[56:59], v[88:91], v[76:79], v[56:59]
	v_mfma_f32_16x16x32_bf16 v[60:63], v[92:95], v[76:79], v[60:63]
	s_waitcnt vmcnt(0) lgkmcnt(0)
	s_barrier
; #define SB_ __builtin_amdgcn_sched_barrier(0)
; template <bool SWAP, bool HALF>
; DI void gemm_mainloop(const GemmDesc& d, int m0, int n0, bf16_t* smem, f32x16 (&acc)[2][2], int dry) {
;     ...
;   auto stage = [&](int cur, u32x4 (&ran)[4], u32x4 (&rbn)[4], int ks) {
;     ldf(cur, 1, 1); SB_;
;     mma(0); SB_;
;     ldf(cur, 2, 0); SB_;
;     lw(ran, rbn, cur ^ 1);
;     gl(ran, rbn, (ks + 3 < nk) ? ks + 3 : nk - 1);
;     SB_;
;     mma(1); SB_;
;     __syncthreads();
;     ldf(cur, 3, 1); SB_;
;     mma(0); SB_;
;     ldf(cur ^ 1, 0, 0);
;     SB_;
;     mma(1); SB_;
;     __syncthreads();
;   };
;   gl(ra0, rb0, 0);
;   gl(ra1, rb1, 1);
;   lw(ra0, rb0, 0);
;   gl(ra0, rb0, 2);
;   __syncthreads();
;   ldf(0, 0, 0);
; #pragma unroll 1
;   for (int ks = 0; ks < nk; ks += 2) {
;     stage(0, ra1, rb1, ks);
;     stage(1, ra0, rb0, ks + 1);
;   }
	ds_read_b128 v[64:67], v168 offset:0
	ds_read_b128 v[68:71], v168 offset:2048
	ds_read_b128 v[72:75], v168 offset:4096
	ds_read_b128 v[76:79], v168 offset:6144
	ds_read_b128 v[80:83], v169 offset:0
	ds_read_b128 v[84:87], v169 offset:2048
	ds_read_b128 v[88:91], v169 offset:4096
	ds_read_b128 v[92:95], v169 offset:6144
	s_add_i32 s5, s1, 3
	s_min_u32 s5, s5, 43
	s_lshl_b32 s18, s5, 7
	s_add_u32 m0, s101, 0x8000
	v_lshl_add_u64 v[210:211], v[152:153], 0, s[18:19]
	global_load_lds_dwordx4 v[210:211], off
	s_add_u32 m0, s101, 0xc000
	v_lshl_add_u64 v[210:211], v[154:155], 0, s[18:19]
	global_load_lds_dwordx4 v[210:211], off
	ds_read_b128 v[96:99], v220 offset:0
	ds_read_b128 v[100:103], v220 offset:2048
	ds_read_b128 v[104:107], v220 offset:4096
	ds_read_b128 v[108:111], v220 offset:6144
	ds_read_b128 v[112:115], v221 offset:0
	ds_read_b128 v[116:119], v221 offset:2048
	ds_read_b128 v[120:123], v221 offset:4096
	ds_read_b128 v[124:127], v221 offset:6144
	v_mfma_f32_16x16x32_bf16 v[0:3], v[192:195], v[128:131], v[0:3]
	v_mfma_f32_16x16x32_bf16 v[4:7], v[196:199], v[128:131], v[4:7]
	s_add_u32 m0, s101, 0x9000
	v_lshl_add_u64 v[210:211], v[156:157], 0, s[18:19]
	global_load_lds_dwordx4 v[210:211], off
	v_mfma_f32_16x16x32_bf16 v[8:11], v[200:203], v[128:131], v[8:11]
	v_mfma_f32_16x16x32_bf16 v[12:15], v[204:207], v[128:131], v[12:15]
	s_add_u32 m0, s101, 0xd000
	v_lshl_add_u64 v[210:211], v[158:159], 0, s[18:19]
	global_load_lds_dwordx4 v[210:211], off
	v_mfma_f32_16x16x32_bf16 v[16:19], v[192:195], v[132:135], v[16:19]
	v_mfma_f32_16x16x32_bf16 v[20:23], v[196:199], v[132:135], v[20:23]
	s_add_u32 m0, s101, 0xa000
	v_lshl_add_u64 v[210:211], v[160:161], 0, s[18:19]
	global_load_lds_dwordx4 v[210:211], off
	v_mfma_f32_16x16x32_bf16 v[24:27], v[200:203], v[132:135], v[24:27]
	v_mfma_f32_16x16x32_bf16 v[28:31], v[204:207], v[132:135], v[28:31]
	s_add_u32 m0, s101, 0xe000
	v_lshl_add_u64 v[210:211], v[162:163], 0, s[18:19]
	global_load_lds_dwordx4 v[210:211], off
	v_mfma_f32_16x16x32_bf16 v[32:35], v[192:195], v[136:139], v[32:35]
	v_mfma_f32_16x16x32_bf16 v[36:39], v[196:199], v[136:139], v[36:39]
	s_add_u32 m0, s101, 0xb000
	v_lshl_add_u64 v[210:211], v[164:165], 0, s[18:19]
	global_load_lds_dwordx4 v[210:211], off
	v_mfma_f32_16x16x32_bf16 v[40:43], v[200:203], v[136:139], v[40:43]
	v_mfma_f32_16x16x32_bf16 v[44:47], v[204:207], v[136:139], v[44:47]
	s_add_u32 m0, s101, 0xf000
	v_lshl_add_u64 v[210:211], v[166:167], 0, s[18:19]
	global_load_lds_dwordx4 v[210:211], off
	v_mfma_f32_16x16x32_bf16 v[48:51], v[192:195], v[140:143], v[48:51]
	v_mfma_f32_16x16x32_bf16 v[52:55], v[196:199], v[140:143], v[52:55]
	v_mfma_f32_16x16x32_bf16 v[56:59], v[200:203], v[140:143], v[56:59]
	v_mfma_f32_16x16x32_bf16 v[60:63], v[204:207], v[140:143], v[60:63]
	s_waitcnt lgkmcnt(8)
	v_mfma_f32_16x16x32_bf16 v[0:3], v[80:83], v[64:67], v[0:3]
	v_mfma_f32_16x16x32_bf16 v[4:7], v[84:87], v[64:67], v[4:7]
	v_mfma_f32_16x16x32_bf16 v[8:11], v[88:91], v[64:67], v[8:11]
	v_mfma_f32_16x16x32_bf16 v[12:15], v[92:95], v[64:67], v[12:15]
	v_mfma_f32_16x16x32_bf16 v[16:19], v[80:83], v[68:71], v[16:19]
	v_mfma_f32_16x16x32_bf16 v[20:23], v[84:87], v[68:71], v[20:23]
	v_mfma_f32_16x16x32_bf16 v[24:27], v[88:91], v[68:71], v[24:27]
	v_mfma_f32_16x16x32_bf16 v[28:31], v[92:95], v[68:71], v[28:31]
	v_mfma_f32_16x16x32_bf16 v[32:35], v[80:83], v[72:75], v[32:35]
	v_mfma_f32_16x16x32_bf16 v[36:39], v[84:87], v[72:75], v[36:39]
	v_mfma_f32_16x16x32_bf16 v[40:43], v[88:91], v[72:75], v[40:43]
	v_mfma_f32_16x16x32_bf16 v[44:47], v[92:95], v[72:75], v[44:47]
	v_mfma_f32_16x16x32_bf16 v[48:51], v[80:83], v[76:79], v[48:51]
	v_mfma_f32_16x16x32_bf16 v[52:55], v[84:87], v[76:79], v[52:55]
	v_mfma_f32_16x16x32_bf16 v[56:59], v[88:91], v[76:79], v[56:59]
	v_mfma_f32_16x16x32_bf16 v[60:63], v[92:95], v[76:79], v[60:63]
	s_add_i32 s5, s1, 2
	s_cmp_lt_u32 s1, 40
	s_mov_b32 s1, s5
	s_waitcnt vmcnt(0) lgkmcnt(0)
	s_barrier
	s_cbranch_scc1 .LBB0_1528
	ds_read_b128 v[64:67], v168 offset:32768
	ds_read_b128 v[68:71], v168 offset:34816
	ds_read_b128 v[72:75], v168 offset:36864
	ds_read_b128 v[76:79], v168 offset:38912
	ds_read_b128 v[80:83], v169 offset:32768
	ds_read_b128 v[84:87], v169 offset:34816
	ds_read_b128 v[88:91], v169 offset:36864
	ds_read_b128 v[92:95], v169 offset:38912
	ds_read_b128 v[128:131], v220 offset:32768
	ds_read_b128 v[132:135], v220 offset:34816
	ds_read_b128 v[136:139], v220 offset:36864
	ds_read_b128 v[140:143], v220 offset:38912
	ds_read_b128 v[192:195], v221 offset:32768
	ds_read_b128 v[196:199], v221 offset:34816
	ds_read_b128 v[200:203], v221 offset:36864
	ds_read_b128 v[204:207], v221 offset:38912
	v_mfma_f32_16x16x32_bf16 v[0:3], v[112:115], v[96:99], v[0:3]
	v_mfma_f32_16x16x32_bf16 v[4:7], v[116:119], v[96:99], v[4:7]
	v_mfma_f32_16x16x32_bf16 v[8:11], v[120:123], v[96:99], v[8:11]
	v_mfma_f32_16x16x32_bf16 v[12:15], v[124:127], v[96:99], v[12:15]
	v_mfma_f32_16x16x32_bf16 v[16:19], v[112:115], v[100:103], v[16:19]
	v_mfma_f32_16x16x32_bf16 v[20:23], v[116:119], v[100:103], v[20:23]
	v_mfma_f32_16x16x32_bf16 v[24:27], v[120:123], v[100:103], v[24:27]
	v_mfma_f32_16x16x32_bf16 v[28:31], v[124:127], v[100:103], v[28:31]
	v_mfma_f32_16x16x32_bf16 v[32:35], v[112:115], v[104:107], v[32:35]
	v_mfma_f32_16x16x32_bf16 v[36:39], v[116:119], v[104:107], v[36:39]
	v_mfma_f32_16x16x32_bf16 v[40:43], v[120:123], v[104:107], v[40:43]
	v_mfma_f32_16x16x32_bf16 v[44:47], v[124:127], v[104:107], v[44:47]
	v_mfma_f32_16x16x32_bf16 v[48:51], v[112:115], v[108:111], v[48:51]
	v_mfma_f32_16x16x32_bf16 v[52:55], v[116:119], v[108:111], v[52:55]
	v_mfma_f32_16x16x32_bf16 v[56:59], v[120:123], v[108:111], v[56:59]
	v_mfma_f32_16x16x32_bf16 v[60:63], v[124:127], v[108:111], v[60:63]
	s_waitcnt lgkmcnt(8)
	v_mfma_f32_16x16x32_bf16 v[0:3], v[80:83], v[64:67], v[0:3]
	v_mfma_f32_16x16x32_bf16 v[4:7], v[84:87], v[64:67], v[4:7]
	v_mfma_f32_16x16x32_bf16 v[8:11], v[88:91], v[64:67], v[8:11]
	v_mfma_f32_16x16x32_bf16 v[12:15], v[92:95], v[64:67], v[12:15]
	v_mfma_f32_16x16x32_bf16 v[16:19], v[80:83], v[68:71], v[16:19]
	v_mfma_f32_16x16x32_bf16 v[20:23], v[84:87], v[68:71], v[20:23]
	v_mfma_f32_16x16x32_bf16 v[24:27], v[88:91], v[68:71], v[24:27]
	v_mfma_f32_16x16x32_bf16 v[28:31], v[92:95], v[68:71], v[28:31]
	v_mfma_f32_16x16x32_bf16 v[32:35], v[80:83], v[72:75], v[32:35]
	v_mfma_f32_16x16x32_bf16 v[36:39], v[84:87], v[72:75], v[36:39]
	v_mfma_f32_16x16x32_bf16 v[40:43], v[88:91], v[72:75], v[40:43]
	v_mfma_f32_16x16x32_bf16 v[44:47], v[92:95], v[72:75], v[44:47]
	v_mfma_f32_16x16x32_bf16 v[48:51], v[80:83], v[76:79], v[48:51]
	v_mfma_f32_16x16x32_bf16 v[52:55], v[84:87], v[76:79], v[52:55]
	v_mfma_f32_16x16x32_bf16 v[56:59], v[88:91], v[76:79], v[56:59]
	v_mfma_f32_16x16x32_bf16 v[60:63], v[92:95], v[76:79], v[60:63]
	s_waitcnt lgkmcnt(0)
	s_barrier
; DI float ssq_f(u64 v) { return (float)v * (1.f / 1048576.f); }
; DI void gemm_tile(const GemmDesc& d, int m0, int n0, bf16_t* smem, int dry) {
;     ...
;   u32x2 hpre[16];
;   if (d.epi == EPI_RESID) {
; #pragma unroll
;     for (int pass = 0; pass < 16; ++pass) {
;       int m = m0 + pass * 8 + (t >> 5); m = m < M ? m : M - 1;
;       hpre[pass] = *(const u32x2*)(d.hb + (size_t)m * D + d.c_off + n0 + (t & 31) * 4);
;     }
;   } else if (t < 128) {
;     rs_s[t] = rsqrtf(ssq_f(myss) * d.inv_dim + EPS);
;   }
;   if (half) {
; #pragma unroll
;     for (int a = 0; a < 2; ++a)
; #pragma unroll
;       for (int g = 0; g < 4; ++g) {
;         f32x4 o;
; #pragma unroll
;         for (int j = 0; j < 4; ++j) o[j] = acc[a][0][4 * g + j];
;         *(f32x4*)(Ct + (a * 32 + r) * CS + w * 32 + 8 * g + 4 * hh) = o;
;       }
;   } else {
; #pragma unroll
;     for (int a = 0; a < 2; ++a)
; #pragma unroll
;       for (int b = 0; b < 2; ++b)
; #pragma unroll
;         for (int g = 0; g < 4; ++g) {
;           f32x4 o;
; #pragma unroll
;           for (int j = 0; j < 4; ++j) o[j] = acc[a][b][4 * g + j];
;           *(f32x4*)(Ct + (wm * 64 + a * 32 + r) * CS + wn * 64 + b * 32 + 8 * g + 4 * hh) = o;
;         }
;   }
;   __syncthreads();
	v_mfma_f32_16x16x32_bf16 v[0:3], v[192:195], v[128:131], v[0:3]
	v_mfma_f32_16x16x32_bf16 v[4:7], v[196:199], v[128:131], v[4:7]
	v_mfma_f32_16x16x32_bf16 v[8:11], v[200:203], v[128:131], v[8:11]
	v_mfma_f32_16x16x32_bf16 v[12:15], v[204:207], v[128:131], v[12:15]
	v_mfma_f32_16x16x32_bf16 v[16:19], v[192:195], v[132:135], v[16:19]
	v_mfma_f32_16x16x32_bf16 v[20:23], v[196:199], v[132:135], v[20:23]
	v_mfma_f32_16x16x32_bf16 v[24:27], v[200:203], v[132:135], v[24:27]
	v_mfma_f32_16x16x32_bf16 v[28:31], v[204:207], v[132:135], v[28:31]
	v_mfma_f32_16x16x32_bf16 v[32:35], v[192:195], v[136:139], v[32:35]
	v_mfma_f32_16x16x32_bf16 v[36:39], v[196:199], v[136:139], v[36:39]
	v_mfma_f32_16x16x32_bf16 v[40:43], v[200:203], v[136:139], v[40:43]
	v_mfma_f32_16x16x32_bf16 v[44:47], v[204:207], v[136:139], v[44:47]
	v_mfma_f32_16x16x32_bf16 v[48:51], v[192:195], v[140:143], v[48:51]
	v_mfma_f32_16x16x32_bf16 v[52:55], v[196:199], v[140:143], v[52:55]
	v_mfma_f32_16x16x32_bf16 v[56:59], v[200:203], v[140:143], v[56:59]
	v_mfma_f32_16x16x32_bf16 v[60:63], v[204:207], v[140:143], v[60:63]
	s_waitcnt vmcnt(7)
	v_ashrrev_i32_e32 v98, 5, v150
	v_add_u32_e32 v92, s13, v98
	s_ashr_i32 s5, s4, 31
	s_lshl_b64 s[10:11], s[4:5], 1
	v_add_u32_e32 v70, 16, v92
	v_add_u32_e32 v72, 24, v92
	s_add_u32 s10, s56, s10
	v_lshlrev_b32_e32 v64, 3, v150
	v_min_i32_e32 v66, 0x803f, v92
	v_add_u32_e32 v68, 8, v92
	v_min_i32_e32 v70, 0x803f, v70
	v_min_i32_e32 v72, 0x803f, v72
	s_addc_u32 s11, s57, s11
	v_and_b32_e32 v144, 0xf8, v64
	v_ashrrev_i32_e32 v67, 31, v66
	v_min_i32_e32 v68, 0x803f, v68
	v_ashrrev_i32_e32 v71, 31, v70
	v_ashrrev_i32_e32 v73, 31, v72
	v_lshl_add_u64 v[64:65], s[10:11], 0, v[144:145]
	v_lshlrev_b64 v[66:67], 11, v[66:67]
	v_ashrrev_i32_e32 v69, 31, v68
	v_lshlrev_b64 v[70:71], 11, v[70:71]
	v_lshlrev_b64 v[72:73], 11, v[72:73]
	v_lshl_add_u64 v[66:67], v[64:65], 0, v[66:67]
	v_lshlrev_b64 v[68:69], 11, v[68:69]
	v_lshl_add_u64 v[70:71], v[64:65], 0, v[70:71]
	v_lshl_add_u64 v[72:73], v[64:65], 0, v[72:73]
	v_lshl_add_u64 v[68:69], v[64:65], 0, v[68:69]
	global_load_dwordx2 v[96:97], v[66:67], off
	global_load_dwordx2 v[94:95], v[68:69], off
	global_load_dwordx2 v[90:91], v[70:71], off
	global_load_dwordx2 v[88:89], v[72:73], off
	v_add_u32_e32 v66, 32, v92
	v_add_u32_e32 v70, 48, v92
	v_add_u32_e32 v72, 56, v92
	v_min_i32_e32 v66, 0x803f, v66
	v_add_u32_e32 v68, 40, v92
	v_min_i32_e32 v70, 0x803f, v70
	v_min_i32_e32 v72, 0x803f, v72
	v_ashrrev_i32_e32 v67, 31, v66
	v_min_i32_e32 v68, 0x803f, v68
	v_ashrrev_i32_e32 v71, 31, v70
	v_ashrrev_i32_e32 v73, 31, v72
	v_lshlrev_b64 v[66:67], 11, v[66:67]
	v_ashrrev_i32_e32 v69, 31, v68
	v_lshlrev_b64 v[70:71], 11, v[70:71]
	v_lshlrev_b64 v[72:73], 11, v[72:73]
	v_lshl_add_u64 v[66:67], v[64:65], 0, v[66:67]
	v_lshlrev_b64 v[68:69], 11, v[68:69]
	v_lshl_add_u64 v[70:71], v[64:65], 0, v[70:71]
	v_lshl_add_u64 v[72:73], v[64:65], 0, v[72:73]
	v_lshl_add_u64 v[68:69], v[64:65], 0, v[68:69]
	global_load_dwordx2 v[86:87], v[66:67], off
	global_load_dwordx2 v[84:85], v[68:69], off
	global_load_dwordx2 v[82:83], v[70:71], off
	global_load_dwordx2 v[80:81], v[72:73], off
	v_add_u32_e32 v66, 64, v92
	v_add_u32_e32 v70, 0x50, v92
	v_add_u32_e32 v72, 0x58, v92
	v_min_i32_e32 v66, 0x803f, v66
	v_add_u32_e32 v68, 0x48, v92
	v_min_i32_e32 v70, 0x803f, v70
	v_min_i32_e32 v72, 0x803f, v72
	v_ashrrev_i32_e32 v67, 31, v66
	v_min_i32_e32 v68, 0x803f, v68
	v_ashrrev_i32_e32 v71, 31, v70
	v_ashrrev_i32_e32 v73, 31, v72
	v_lshlrev_b64 v[66:67], 11, v[66:67]
	v_ashrrev_i32_e32 v69, 31, v68
	v_lshlrev_b64 v[70:71], 11, v[70:71]
	v_lshlrev_b64 v[72:73], 11, v[72:73]
	v_lshl_add_u64 v[66:67], v[64:65], 0, v[66:67]
	v_lshlrev_b64 v[68:69], 11, v[68:69]
	v_lshl_add_u64 v[70:71], v[64:65], 0, v[70:71]
	v_lshl_add_u64 v[72:73], v[64:65], 0, v[72:73]
	v_lshl_add_u64 v[68:69], v[64:65], 0, v[68:69]
	global_load_dwordx2 v[78:79], v[66:67], off
	global_load_dwordx2 v[76:77], v[68:69], off
	global_load_dwordx2 v[74:75], v[70:71], off
	s_nop 0
	global_load_dwordx2 v[72:73], v[72:73], off
	v_add_u32_e32 v70, 0x70, v92
	v_min_i32_e32 v70, 0x803f, v70
	v_ashrrev_i32_e32 v71, 31, v70
	v_lshlrev_b64 v[70:71], 11, v[70:71]
	v_add_u32_e32 v66, 0x60, v92
	v_add_u32_e32 v68, 0x68, v92
	s_waitcnt vmcnt(18)
	v_lshl_add_u64 v[100:101], v[64:65], 0, v[70:71]
	v_add_u32_e32 v70, 0x78, v92
	v_min_i32_e32 v66, 0x803f, v66
	v_min_i32_e32 v68, 0x803f, v68
	v_min_i32_e32 v70, 0x803f, v70
	v_ashrrev_i32_e32 v67, 31, v66
	v_ashrrev_i32_e32 v69, 31, v68
	v_ashrrev_i32_e32 v71, 31, v70
	v_lshlrev_b64 v[66:67], 11, v[66:67]
	v_lshlrev_b64 v[68:69], 11, v[68:69]
	v_lshlrev_b64 v[70:71], 11, v[70:71]
	v_lshl_add_u64 v[66:67], v[64:65], 0, v[66:67]
	v_lshl_add_u64 v[68:69], v[64:65], 0, v[68:69]
	v_lshl_add_u64 v[64:65], v[64:65], 0, v[70:71]
	global_load_dwordx2 v[70:71], v[66:67], off
	s_nop 0
	global_load_dwordx2 v[68:69], v[68:69], off
	s_nop 0
	global_load_dwordx2 v[66:67], v[100:101], off
	s_nop 0
	global_load_dwordx2 v[64:65], v[64:65], off
	v_and_b32_e32 v99, 31, v150
	v_lshrrev_b32_e32 v100, 1, v150
	v_lshlrev_b32_e32 v93, 2, v150
	v_and_or_b32 v101, v100, s72, v99
	v_and_b32_e32 v100, 16, v100
	s_movk_i32 s1, 0x100
	v_and_or_b32 v100, v93, s1, v100
	v_mad_u64_u32 v[100:101], s[10:11], v101, s22, v[100:101]
	v_and_b32_e32 v212, 15, v172
	v_lshrrev_b32_e32 v213, 1, v172
	v_and_or_b32 v212, v213, s72, v212
	v_lshlrev_b32_e32 v213, 2, v172
	v_and_b32_e32 v214, 0x30, v172
	v_and_b32_e32 v213, 0x100, v213
	v_or_b32_e32 v213, v213, v214
	v_mad_u32_u24 v100, v212, s22, v213
	ds_write_b128 v100, v[0:3]
	ds_write_b128 v100, v[4:7] offset:64
	ds_write_b128 v100, v[8:11] offset:128
	ds_write_b128 v100, v[12:15] offset:192
	ds_write_b128 v100, v[16:19] offset:8448
	ds_write_b128 v100, v[20:23] offset:8512
	ds_write_b128 v100, v[24:27] offset:8576
	ds_write_b128 v100, v[28:31] offset:8640
	ds_write_b128 v100, v[32:35] offset:16896
	ds_write_b128 v100, v[36:39] offset:16960
	ds_write_b128 v100, v[40:43] offset:17024
	ds_write_b128 v100, v[44:47] offset:17088
	ds_write_b128 v100, v[48:51] offset:25344
	ds_write_b128 v100, v[52:55] offset:25408
	ds_write_b128 v100, v[56:59] offset:25472
	ds_write_b128 v100, v[60:63] offset:25536
	v_lshl_or_b32 v0, v99, 2, s4
	v_lshlrev_b32_e32 v2, 4, v99
	v_cmp_gt_i32_e64 s[4:5], s23, v92
	v_mov_b32_e32 v4, 0
	v_ashrrev_i32_e32 v93, 31, v92
	v_ashrrev_i32_e32 v1, 31, v0
	s_waitcnt lgkmcnt(0)
	s_barrier
; DI void gemm_tile(const GemmDesc& d, int m0, int n0, bf16_t* smem, int dry) {
;     ...
;     for (int pass = 0; pass < 16; ++pass) {
;       const int row = pass * 8 + (t >> 5), c4 = t & 31, m = m0 + row;
;       float part = 0.f;
;       if (m < M) {
;         const f32x4 v = *(const f32x4*)(Ct + row * CS + c4 * 4);
;         const int n = d.c_off + n0 + c4 * 4;
;         f32x4 hv;
;         hv[0] = __uint_as_float(hpre[pass][0] << 16); hv[1] = __uint_as_float(hpre[pass][0] & 0xffff0000u);
;         hv[2] = __uint_as_float(hpre[pass][1] << 16); hv[3] = __uint_as_float(hpre[pass][1] & 0xffff0000u);
; #pragma unroll
;         for (int j = 0; j < 4; ++j) { hv[j] += v[j]; part += hv[j] * hv[j]; }
;         u32x2 o; o[0] = pk_bf16(hv[0], hv[1]); o[1] = pk_bf16(hv[2], hv[3]);
;         *(u32x2*)(d.hb + (size_t)m * D + n) = o;
;       }
	s_and_saveexec_b64 s[10:11], s[4:5]
	s_cbranch_execz .LBB0_1531
	v_mad_u64_u32 v[4:5], s[14:15], v98, s22, v[2:3]
	ds_read_b128 v[4:7], v4
	s_waitcnt vmcnt(15)
	v_lshlrev_b32_e32 v8, 16, v96
	v_and_b32_e32 v9, 0xffff0000, v96
	v_and_b32_e32 v11, 0xffff0000, v97
	v_lshlrev_b32_e32 v10, 16, v97
	s_waitcnt lgkmcnt(0)
	v_pk_add_f32 v[8:9], v[4:5], v[8:9]
	v_pk_add_f32 v[6:7], v[6:7], v[10:11]
	v_pk_mul_f32 v[4:5], v[8:9], v[8:9]
	v_pk_mul_f32 v[10:11], v[6:7], v[6:7]
	v_add_f32_e32 v3, v4, v5
	v_cvt_pk_bf16_f32 v8, v8, v9
	v_cvt_pk_bf16_f32 v9, v6, v7
	v_lshlrev_b64 v[6:7], 11, v[92:93]
	v_add_f32_e32 v3, v10, v3
	v_lshl_add_u64 v[6:7], s[56:57], 0, v[6:7]
	v_add_f32_e32 v4, v11, v3
	v_lshl_add_u64 v[6:7], v[0:1], 1, v[6:7]
	global_store_dwordx2 v[6:7], v[8:9], off
